# P10 sub-key score blocks: 32 fragment loads queued 15-deep (global saddr form) ahead of the MFMA chains, xor-based ordf
# speedup vs baseline: 1.1401x; 1.0059x over previous
; #define MFMA(a, b, c) __builtin_amdgcn_mfma_f32_16x16x32_bf16((a), (b), (c), 0, 0, 0)
; DI unsigned ordf(float f) { unsigned u = __float_as_uint(f); return (u & 0x80000000u) ? ~u : (u | 0x80000000u); }
; DI void peer_topk_wave(const Params& p, int item, unsigned* lds  ) {
;     ...
;   for (int pp = 0; pp < 2; ++pp) {
;     bf16x8 qf[4];
; #pragma unroll
;     for (int ks = 0; ks < 4; ++ks) qf[ks] = *(const bf16x8*)&p.pq[(size_t)(row0 + r) * 2048 + h * 256 + pp * 128 + ks * 32 + kg * 8];
;     unsigned kk[32];
;     const u16* sk = p.subkb + (size_t)(h * 2 + pp) * 16384;
; #pragma unroll
;     for (int mt = 0; mt < 8; ++mt) {
;       f32x4 a = (f32x4){0.f, 0.f, 0.f, 0.f};
; #pragma unroll
;       for (int ks = 0; ks < 4; ++ks) {
;         bf16x8 kf = *(const bf16x8*)&sk[(mt * 16 + r) * 128 + ks * 32 + kg * 8];
;         a = MFMA(kf, qf[ks], a);
;       }
; #pragma unroll
;       for (int j = 0; j < 4; ++j) kk[mt * 4 + j] = (ordf(a[j]) & ~127u) | (unsigned)(mt * 16 + kg * 4 + j);
;     }
.LBB0_1091:
	ds_read_b64 v[0:1], v142
	ds_read_b64 v[86:87], v143
	v_and_or_b32 v84, v141, -16, v134
	v_ashrrev_i32_e32 v85, 31, v84
	v_and_b32_e32 v146, 7, v145
	v_lshlrev_b64 v[2:3], 12, v[84:85]
	s_waitcnt lgkmcnt(0)
	v_lshl_add_u64 v[0:1], v[0:1], 0, v[2:3]
	v_lshlrev_b32_e32 v16, 9, v146
	v_lshl_add_u64 v[0:1], v[0:1], 0, v[16:17]
	v_lshlrev_b32_e32 v16, 16, v146
	v_lshl_add_u64 v[86:87], v[86:87], 0, v[16:17]
	v_lshl_add_u64 v[88:89], v[0:1], 0, v[18:19]
	v_lshl_add_u64 v[156:157], v[86:87], 0, v[20:21]
	flat_load_dwordx4 v[12:15], v[88:89]
	flat_load_dwordx4 v[8:11], v[88:89] offset:64
	flat_load_dwordx4 v[4:7], v[88:89] offset:128
	flat_load_dwordx4 v[0:3], v[88:89] offset:192
	v_readfirstlane_b32 s0, v86
	v_readfirstlane_b32 s1, v87
	s_nop 3
	s_add_u32 s2, s0, 0x0
	s_addc_u32 s3, s1, 0
	global_load_dwordx4 v[24:27], v20, s[2:3]
	global_load_dwordx4 v[28:31], v20, s[2:3] offset:64
	global_load_dwordx4 v[32:35], v20, s[2:3] offset:128
	global_load_dwordx4 v[36:39], v20, s[2:3] offset:192
	s_add_u32 s2, s0, 0x1000
	s_addc_u32 s3, s1, 0
	global_load_dwordx4 v[40:43], v20, s[2:3]
	global_load_dwordx4 v[44:47], v20, s[2:3] offset:64
	global_load_dwordx4 v[48:51], v20, s[2:3] offset:128
	global_load_dwordx4 v[52:55], v20, s[2:3] offset:192
	s_add_u32 s2, s0, 0x2000
	s_addc_u32 s3, s1, 0
	global_load_dwordx4 v[56:59], v20, s[2:3]
	global_load_dwordx4 v[60:63], v20, s[2:3] offset:64
	global_load_dwordx4 v[64:67], v20, s[2:3] offset:128
	global_load_dwordx4 v[68:71], v20, s[2:3] offset:192
	s_add_u32 s2, s0, 0x3000
	s_addc_u32 s3, s1, 0
	global_load_dwordx4 v[72:75], v20, s[2:3]
	global_load_dwordx4 v[76:79], v20, s[2:3] offset:64
	global_load_dwordx4 v[80:83], v20, s[2:3] offset:128
	s_waitcnt vmcnt(11) lgkmcnt(0)
	v_mfma_f32_16x16x32_bf16 v[190:193], v[24:27], v[12:15], 0
	v_mfma_f32_16x16x32_bf16 v[190:193], v[28:31], v[8:11], v[190:193]
	v_mfma_f32_16x16x32_bf16 v[190:193], v[32:35], v[4:7], v[190:193]
	v_mfma_f32_16x16x32_bf16 v[190:193], v[36:39], v[0:3], v[190:193]
	global_load_dwordx4 v[24:27], v20, s[2:3] offset:192
	s_add_u32 s2, s0, 0x4000
	s_addc_u32 s3, s1, 0
	global_load_dwordx4 v[28:31], v20, s[2:3]
	global_load_dwordx4 v[32:35], v20, s[2:3] offset:64
	global_load_dwordx4 v[36:39], v20, s[2:3] offset:128
	s_waitcnt vmcnt(11)
	v_mfma_f32_16x16x32_bf16 v[198:201], v[40:43], v[12:15], 0
	v_mfma_f32_16x16x32_bf16 v[198:201], v[44:47], v[8:11], v[198:201]
	v_mfma_f32_16x16x32_bf16 v[198:201], v[48:51], v[4:7], v[198:201]
	v_mfma_f32_16x16x32_bf16 v[198:201], v[52:55], v[0:3], v[198:201]
	global_load_dwordx4 v[40:43], v20, s[2:3] offset:192
	s_add_u32 s2, s0, 0x5000
	s_addc_u32 s3, s1, 0
	global_load_dwordx4 v[44:47], v20, s[2:3]
	global_load_dwordx4 v[48:51], v20, s[2:3] offset:64
	global_load_dwordx4 v[52:55], v20, s[2:3] offset:128
	s_nop 7
	s_nop 3
	v_ashrrev_i32_e32 v197, 31, v190
	v_or_b32_e32 v197, 0x80000000, v197
	v_xor_b32_e32 v197, v190, v197
	v_and_or_b32 v147, v197, s80, v170
	v_ashrrev_i32_e32 v202, 31, v191
	v_or_b32_e32 v202, 0x80000000, v202
	v_xor_b32_e32 v202, v191, v202
	v_and_or_b32 v148, v202, s80, v113
	v_ashrrev_i32_e32 v197, 31, v192
	v_or_b32_e32 v197, 0x80000000, v197
	v_xor_b32_e32 v197, v192, v197
	v_and_or_b32 v149, v197, s80, v114
	v_ashrrev_i32_e32 v202, 31, v193
	v_or_b32_e32 v202, 0x80000000, v202
	v_xor_b32_e32 v202, v193, v202
	v_and_or_b32 v150, v202, s80, v115
	s_waitcnt vmcnt(11)
	v_mfma_f32_16x16x32_bf16 v[190:193], v[56:59], v[12:15], 0
	v_mfma_f32_16x16x32_bf16 v[190:193], v[60:63], v[8:11], v[190:193]
	v_mfma_f32_16x16x32_bf16 v[190:193], v[64:67], v[4:7], v[190:193]
	v_mfma_f32_16x16x32_bf16 v[190:193], v[68:71], v[0:3], v[190:193]
	global_load_dwordx4 v[56:59], v20, s[2:3] offset:192
	s_add_u32 s2, s0, 0x6000
	s_addc_u32 s3, s1, 0
	global_load_dwordx4 v[60:63], v20, s[2:3]
	global_load_dwordx4 v[64:67], v20, s[2:3] offset:64
	global_load_dwordx4 v[68:71], v20, s[2:3] offset:128
	s_nop 7
	s_nop 3
	v_ashrrev_i32_e32 v197, 31, v198
	v_or_b32_e32 v197, 0x80000000, v197
	v_xor_b32_e32 v197, v198, v197
	v_and_or_b32 v151, v197, s80, v90
	v_ashrrev_i32_e32 v202, 31, v199
	v_or_b32_e32 v202, 0x80000000, v202
	v_xor_b32_e32 v202, v199, v202
	v_and_or_b32 v152, v202, s80, v116
	v_ashrrev_i32_e32 v197, 31, v200
	v_or_b32_e32 v197, 0x80000000, v197
	v_xor_b32_e32 v197, v200, v197
	v_and_or_b32 v153, v197, s80, v117
	v_ashrrev_i32_e32 v202, 31, v201
	v_or_b32_e32 v202, 0x80000000, v202
	v_xor_b32_e32 v202, v201, v202
	v_and_or_b32 v154, v202, s80, v118
	s_waitcnt vmcnt(11)
	v_mfma_f32_16x16x32_bf16 v[198:201], v[72:75], v[12:15], 0
	v_mfma_f32_16x16x32_bf16 v[198:201], v[76:79], v[8:11], v[198:201]
	v_mfma_f32_16x16x32_bf16 v[198:201], v[80:83], v[4:7], v[198:201]
	v_mfma_f32_16x16x32_bf16 v[198:201], v[24:27], v[0:3], v[198:201]
	global_load_dwordx4 v[72:75], v20, s[2:3] offset:192
	s_add_u32 s2, s0, 0x7000
	s_addc_u32 s3, s1, 0
	global_load_dwordx4 v[76:79], v20, s[2:3]
	global_load_dwordx4 v[80:83], v20, s[2:3] offset:64
	global_load_dwordx4 v[24:27], v20, s[2:3] offset:128
	s_nop 7
	s_nop 3
	v_ashrrev_i32_e32 v197, 31, v190
	v_or_b32_e32 v197, 0x80000000, v197
	v_xor_b32_e32 v197, v190, v197
	v_and_or_b32 v155, v197, s80, v91
	v_ashrrev_i32_e32 v202, 31, v191
	v_or_b32_e32 v202, 0x80000000, v202
	v_xor_b32_e32 v202, v191, v202
	v_and_or_b32 v156, v202, s80, v119
	v_ashrrev_i32_e32 v197, 31, v192
	v_or_b32_e32 v197, 0x80000000, v197
	v_xor_b32_e32 v197, v192, v197
	v_and_or_b32 v157, v197, s80, v120
	v_ashrrev_i32_e32 v202, 31, v193
	v_or_b32_e32 v202, 0x80000000, v202
	v_xor_b32_e32 v202, v193, v202
	v_and_or_b32 v158, v202, s80, v121
	s_waitcnt vmcnt(11)
; #define MFMA(a, b, c) __builtin_amdgcn_mfma_f32_16x16x32_bf16((a), (b), (c), 0, 0, 0)
; DI unsigned ordf(float f) { unsigned u = __float_as_uint(f); return (u & 0x80000000u) ? ~u : (u | 0x80000000u); }
; DI void peer_topk_wave(const Params& p, int item, unsigned* lds  ) {
;     ...
;     for (int mt = 0; mt < 8; ++mt) {
;       f32x4 a = (f32x4){0.f, 0.f, 0.f, 0.f};
; #pragma unroll
;       for (int ks = 0; ks < 4; ++ks) {
;         bf16x8 kf = *(const bf16x8*)&sk[(mt * 16 + r) * 128 + ks * 32 + kg * 8];
;         a = MFMA(kf, qf[ks], a);
;       }
; #pragma unroll
;       for (int j = 0; j < 4; ++j) kk[mt * 4 + j] = (ordf(a[j]) & ~127u) | (unsigned)(mt * 16 + kg * 4 + j);
;     }
; #pragma unroll
;     for (int rr = 0; rr < 16; ++rr) {
;       unsigned m = 0;
; #pragma unroll
;       for (int i = 0; i < 32; ++i) m = umax(m, kk[i]);
;       m = umax(m, (unsigned)__shfl_xor((int)m, 16));
;       m = umax(m, (unsigned)__shfl_xor((int)m, 32));
	v_mfma_f32_16x16x32_bf16 v[190:193], v[28:31], v[12:15], 0
	v_mfma_f32_16x16x32_bf16 v[190:193], v[32:35], v[8:11], v[190:193]
	v_mfma_f32_16x16x32_bf16 v[190:193], v[36:39], v[4:7], v[190:193]
	v_mfma_f32_16x16x32_bf16 v[190:193], v[40:43], v[0:3], v[190:193]
	global_load_dwordx4 v[28:31], v20, s[2:3] offset:192
	s_nop 7
	s_nop 3
	v_ashrrev_i32_e32 v197, 31, v198
	v_or_b32_e32 v197, 0x80000000, v197
	v_xor_b32_e32 v197, v198, v197
	v_and_or_b32 v159, v197, s80, v92
	v_ashrrev_i32_e32 v202, 31, v199
	v_or_b32_e32 v202, 0x80000000, v202
	v_xor_b32_e32 v202, v199, v202
	v_and_or_b32 v160, v202, s80, v122
	v_ashrrev_i32_e32 v197, 31, v200
	v_or_b32_e32 v197, 0x80000000, v197
	v_xor_b32_e32 v197, v200, v197
	v_and_or_b32 v161, v197, s80, v123
	v_ashrrev_i32_e32 v202, 31, v201
	v_or_b32_e32 v202, 0x80000000, v202
	v_xor_b32_e32 v202, v201, v202
	v_and_or_b32 v162, v202, s80, v124
	s_waitcnt vmcnt(8)
	v_mfma_f32_16x16x32_bf16 v[198:201], v[44:47], v[12:15], 0
	v_mfma_f32_16x16x32_bf16 v[198:201], v[48:51], v[8:11], v[198:201]
	v_mfma_f32_16x16x32_bf16 v[198:201], v[52:55], v[4:7], v[198:201]
	v_mfma_f32_16x16x32_bf16 v[198:201], v[56:59], v[0:3], v[198:201]
	s_nop 7
	s_nop 3
	v_ashrrev_i32_e32 v197, 31, v190
	v_or_b32_e32 v197, 0x80000000, v197
	v_xor_b32_e32 v197, v190, v197
	v_and_or_b32 v164, v197, s80, v93
	v_ashrrev_i32_e32 v202, 31, v191
	v_or_b32_e32 v202, 0x80000000, v202
	v_xor_b32_e32 v202, v191, v202
	v_and_or_b32 v165, v202, s80, v125
	v_ashrrev_i32_e32 v197, 31, v192
	v_or_b32_e32 v197, 0x80000000, v197
	v_xor_b32_e32 v197, v192, v197
	v_and_or_b32 v166, v197, s80, v126
	v_ashrrev_i32_e32 v202, 31, v193
	v_or_b32_e32 v202, 0x80000000, v202
	v_xor_b32_e32 v202, v193, v202
	v_and_or_b32 v167, v202, s80, v127
	s_waitcnt vmcnt(4)
	v_mfma_f32_16x16x32_bf16 v[190:193], v[60:63], v[12:15], 0
	v_mfma_f32_16x16x32_bf16 v[190:193], v[64:67], v[8:11], v[190:193]
	v_mfma_f32_16x16x32_bf16 v[190:193], v[68:71], v[4:7], v[190:193]
	v_mfma_f32_16x16x32_bf16 v[190:193], v[72:75], v[0:3], v[190:193]
	s_nop 7
	s_nop 3
	v_ashrrev_i32_e32 v197, 31, v198
	v_or_b32_e32 v197, 0x80000000, v197
	v_xor_b32_e32 v197, v198, v197
	v_and_or_b32 v168, v197, s80, v94
	v_ashrrev_i32_e32 v202, 31, v199
	v_or_b32_e32 v202, 0x80000000, v202
	v_xor_b32_e32 v202, v199, v202
	v_and_or_b32 v169, v202, s80, v129
	v_ashrrev_i32_e32 v197, 31, v200
	v_or_b32_e32 v197, 0x80000000, v197
	v_xor_b32_e32 v197, v200, v197
	v_and_or_b32 v171, v197, s80, v130
	v_ashrrev_i32_e32 v202, 31, v201
	v_or_b32_e32 v202, 0x80000000, v202
	v_xor_b32_e32 v202, v201, v202
	v_and_or_b32 v172, v202, s80, v131
	s_waitcnt vmcnt(0)
	v_mfma_f32_16x16x32_bf16 v[198:201], v[76:79], v[12:15], 0
	v_mfma_f32_16x16x32_bf16 v[198:201], v[80:83], v[8:11], v[198:201]
	v_mfma_f32_16x16x32_bf16 v[198:201], v[24:27], v[4:7], v[198:201]
	v_mfma_f32_16x16x32_bf16 v[198:201], v[28:31], v[0:3], v[198:201]
	s_nop 7
	s_nop 3
	v_ashrrev_i32_e32 v197, 31, v190
	v_or_b32_e32 v197, 0x80000000, v197
	v_xor_b32_e32 v197, v190, v197
	v_and_or_b32 v173, v197, s80, v95
	v_ashrrev_i32_e32 v202, 31, v191
	v_or_b32_e32 v202, 0x80000000, v202
	v_xor_b32_e32 v202, v191, v202
	v_and_or_b32 v180, v202, s80, v135
	v_ashrrev_i32_e32 v197, 31, v192
	v_or_b32_e32 v197, 0x80000000, v197
	v_xor_b32_e32 v197, v192, v197
	v_and_or_b32 v181, v197, s80, v136
	v_ashrrev_i32_e32 v202, 31, v193
	v_or_b32_e32 v202, 0x80000000, v202
	v_xor_b32_e32 v202, v193, v202
	v_and_or_b32 v182, v202, s80, v137
	s_nop 7
	s_nop 3
	v_ashrrev_i32_e32 v197, 31, v198
	v_or_b32_e32 v197, 0x80000000, v197
	v_xor_b32_e32 v197, v198, v197
	v_and_or_b32 v0, v197, s80, v96
	v_ashrrev_i32_e32 v202, 31, v199
	v_or_b32_e32 v202, 0x80000000, v202
	v_xor_b32_e32 v202, v199, v202
	v_and_or_b32 v1, v202, s80, v138
	v_ashrrev_i32_e32 v197, 31, v200
	v_or_b32_e32 v197, 0x80000000, v197
	v_xor_b32_e32 v197, v200, v197
	v_and_or_b32 v2, v197, s80, v139
	v_ashrrev_i32_e32 v202, 31, v201
	v_or_b32_e32 v202, 0x80000000, v202
	v_xor_b32_e32 v202, v201, v202
	v_and_or_b32 v3, v202, s80, v140
	v_max_u32_e32 v4, v147, v148
	v_max3_u32 v4, v4, v149, v150
	v_max3_u32 v4, v4, v151, v152
	v_max3_u32 v4, v4, v153, v154
	v_max3_u32 v4, v4, v155, v156
	v_max3_u32 v4, v4, v157, v158
	v_max3_u32 v4, v4, v159, v160
	v_max3_u32 v4, v4, v161, v162
	v_max3_u32 v4, v4, v164, v165
	v_max3_u32 v4, v4, v166, v167
	v_max3_u32 v4, v4, v168, v169
	v_max3_u32 v4, v4, v171, v172
	v_max3_u32 v4, v4, v173, v180
	v_max3_u32 v4, v4, v181, v182
	v_and_or_b32 v3, v3, s80, v140
	v_max3_u32 v4, v4, v0, v1
	v_max3_u32 v4, v4, v2, v3
	ds_bpermute_b32 v5, v111, v4
	s_waitcnt lgkmcnt(0)
	v_max_u32_e32 v4, v4, v5
	ds_bpermute_b32 v5, v112, v4
	s_waitcnt lgkmcnt(0)
; DI void peer_topk_wave(const Params& p, int item, unsigned* lds  ) {
;     ...
; #pragma unroll
;     for (int rr = 0; rr < 16; ++rr) {
;       unsigned m = 0;
; #pragma unroll
;       for (int i = 0; i < 32; ++i) m = umax(m, kk[i]);
;       m = umax(m, (unsigned)__shfl_xor((int)m, 16));
;       m = umax(m, (unsigned)__shfl_xor((int)m, 32));
;       win[pp][rr] = m;
; #pragma unroll
;       for (int i = 0; i < 32; ++i) kk[i] = (kk[i] == m) ? 0u : kk[i];
;     }
	v_max_u32_e32 v16, v4, v5
	v_cmp_ne_u32_e32 vcc, v147, v16
	v_cmp_ne_u32_e64 s[98:99], v148, v16
	v_cmp_ne_u32_e64 s[100:101], v149, v16
	v_cndmask_b32_e32 v4, 0, v147, vcc
	v_cndmask_b32_e64 v5, 0, v148, s[98:99]
	v_max_u32_e32 v147, v4, v5
	v_cndmask_b32_e64 v6, 0, v149, s[100:101]
	v_cmp_ne_u32_e32 vcc, v150, v16
	v_cmp_ne_u32_e64 s[98:99], v151, v16
	v_cmp_ne_u32_e64 s[100:101], v152, v16
	v_cndmask_b32_e32 v7, 0, v150, vcc
	v_max3_u32 v147, v147, v6, v7
	v_cndmask_b32_e64 v8, 0, v151, s[98:99]
	v_cndmask_b32_e64 v9, 0, v152, s[100:101]
	v_cmp_ne_u32_e32 vcc, v153, v16
	v_max3_u32 v147, v147, v8, v9
	v_cmp_ne_u32_e64 s[98:99], v154, v16
	v_cndmask_b32_e32 v10, 0, v153, vcc
	v_cmp_ne_u32_e64 s[100:101], v155, v16
	v_cndmask_b32_e64 v11, 0, v154, s[98:99]
	v_max3_u32 v147, v147, v10, v11
	v_cndmask_b32_e64 v12, 0, v155, s[100:101]
	v_cmp_ne_u32_e32 vcc, v156, v16
	v_cmp_ne_u32_e64 s[98:99], v157, v16
	v_cmp_ne_u32_e64 s[100:101], v158, v16
	v_cndmask_b32_e32 v13, 0, v156, vcc
	v_max3_u32 v147, v147, v12, v13
	v_cndmask_b32_e64 v14, 0, v157, s[98:99]
	v_cndmask_b32_e64 v15, 0, v158, s[100:101]
	v_cmp_ne_u32_e32 vcc, v159, v16
	v_max3_u32 v147, v147, v14, v15
	v_cmp_ne_u32_e64 s[98:99], v160, v16
	v_cndmask_b32_e32 v148, 0, v159, vcc
	v_cmp_ne_u32_e64 s[100:101], v161, v16
	v_cndmask_b32_e64 v149, 0, v160, s[98:99]
	v_max3_u32 v147, v147, v148, v149
	v_cndmask_b32_e64 v150, 0, v161, s[100:101]
	v_cmp_ne_u32_e32 vcc, v162, v16
	v_cmp_ne_u32_e64 s[98:99], v164, v16
	v_cmp_ne_u32_e64 s[100:101], v165, v16
	v_cndmask_b32_e32 v151, 0, v162, vcc
	v_max3_u32 v147, v147, v150, v151
	v_cndmask_b32_e64 v152, 0, v164, s[98:99]
	v_cndmask_b32_e64 v153, 0, v165, s[100:101]
	v_cmp_ne_u32_e32 vcc, v166, v16
	v_max3_u32 v147, v147, v152, v153
	v_cmp_ne_u32_e64 s[98:99], v167, v16
	v_cndmask_b32_e32 v154, 0, v166, vcc
	v_cmp_ne_u32_e64 s[100:101], v168, v16
	v_cndmask_b32_e64 v155, 0, v167, s[98:99]
	v_max3_u32 v147, v147, v154, v155
	v_cndmask_b32_e64 v156, 0, v168, s[100:101]
	v_cmp_ne_u32_e32 vcc, v169, v16
	v_cmp_ne_u32_e64 s[98:99], v171, v16
	v_cmp_ne_u32_e64 s[100:101], v172, v16
	v_cndmask_b32_e32 v157, 0, v169, vcc
	v_max3_u32 v147, v147, v156, v157
	v_cndmask_b32_e64 v158, 0, v171, s[98:99]
	v_cndmask_b32_e64 v159, 0, v172, s[100:101]
	v_cmp_ne_u32_e32 vcc, v173, v16
	v_max3_u32 v147, v147, v158, v159
	v_cmp_ne_u32_e64 s[98:99], v180, v16
	v_cndmask_b32_e32 v160, 0, v173, vcc
	v_cmp_ne_u32_e64 s[100:101], v181, v16
	v_cndmask_b32_e64 v161, 0, v180, s[98:99]
	v_max3_u32 v147, v147, v160, v161
	v_cndmask_b32_e64 v162, 0, v181, s[100:101]
	v_cmp_ne_u32_e32 vcc, v182, v16
	v_cmp_ne_u32_e64 s[98:99], v0, v16
	v_cmp_ne_u32_e64 s[100:101], v1, v16
	v_cndmask_b32_e32 v164, 0, v182, vcc
	v_max3_u32 v147, v147, v162, v164
	v_cndmask_b32_e64 v0, 0, v0, s[98:99]
	v_cndmask_b32_e64 v1, 0, v1, s[100:101]
	v_cmp_ne_u32_e32 vcc, v2, v16
	v_max3_u32 v147, v147, v0, v1
	v_cmp_ne_u32_e64 s[98:99], v3, v16
	v_cndmask_b32_e32 v2, 0, v2, vcc
	s_nop 0
	v_cndmask_b32_e64 v3, 0, v3, s[98:99]
	v_max3_u32 v147, v147, v2, v3
	ds_bpermute_b32 v165, v111, v147
	s_waitcnt lgkmcnt(0)
	v_max_u32_e32 v147, v147, v165
	ds_bpermute_b32 v165, v112, v147
	s_waitcnt lgkmcnt(0)
	v_max_u32_e32 v147, v147, v165
	v_cmp_ne_u32_e32 vcc, v4, v147
	v_cmp_ne_u32_e64 s[98:99], v5, v147
	v_cmp_ne_u32_e64 s[100:101], v6, v147
	v_cndmask_b32_e32 v4, 0, v4, vcc
	v_cndmask_b32_e64 v5, 0, v5, s[98:99]
	v_cndmask_b32_e64 v6, 0, v6, s[100:101]
	v_cmp_ne_u32_e32 vcc, v7, v147
	v_cmp_ne_u32_e64 s[98:99], v8, v147
	v_cmp_ne_u32_e64 s[100:101], v9, v147
	v_cndmask_b32_e32 v7, 0, v7, vcc
	v_cndmask_b32_e64 v8, 0, v8, s[98:99]
	v_cndmask_b32_e64 v9, 0, v9, s[100:101]
	v_cmp_ne_u32_e32 vcc, v10, v147
	v_cmp_ne_u32_e64 s[98:99], v11, v147
	v_cmp_ne_u32_e64 s[100:101], v12, v147
	v_cndmask_b32_e32 v10, 0, v10, vcc
	v_cndmask_b32_e64 v11, 0, v11, s[98:99]
	v_cndmask_b32_e64 v12, 0, v12, s[100:101]
	v_cmp_ne_u32_e32 vcc, v13, v147
	v_cmp_ne_u32_e64 s[98:99], v14, v147
	v_cmp_ne_u32_e64 s[100:101], v15, v147
	v_cndmask_b32_e32 v13, 0, v13, vcc
	v_cndmask_b32_e64 v14, 0, v14, s[98:99]
	v_cndmask_b32_e64 v15, 0, v15, s[100:101]
	v_cmp_ne_u32_e32 vcc, v148, v147
	v_cmp_ne_u32_e64 s[98:99], v149, v147
	v_cmp_ne_u32_e64 s[100:101], v150, v147
	v_cndmask_b32_e32 v165, 0, v148, vcc
	v_max_u32_e32 v148, v4, v5
	v_max3_u32 v148, v148, v6, v7
	v_cndmask_b32_e64 v149, 0, v149, s[98:99]
	v_max3_u32 v148, v148, v8, v9
	v_max3_u32 v148, v148, v10, v11
	v_cndmask_b32_e64 v150, 0, v150, s[100:101]
	v_cmp_ne_u32_e32 vcc, v151, v147
	v_max3_u32 v148, v148, v12, v13
	v_max3_u32 v148, v148, v14, v15
	v_cndmask_b32_e32 v151, 0, v151, vcc
	v_cmp_ne_u32_e64 s[98:99], v152, v147
	v_max3_u32 v148, v148, v165, v149
	v_max3_u32 v148, v148, v150, v151
	v_cndmask_b32_e64 v152, 0, v152, s[98:99]
	v_cmp_ne_u32_e64 s[100:101], v153, v147
	v_cmp_ne_u32_e32 vcc, v154, v147
	v_cmp_ne_u32_e64 s[98:99], v155, v147
	v_cndmask_b32_e64 v153, 0, v153, s[100:101]
	v_max3_u32 v148, v148, v152, v153
	v_cndmask_b32_e32 v154, 0, v154, vcc
	v_cndmask_b32_e64 v155, 0, v155, s[98:99]
	v_cmp_ne_u32_e64 s[100:101], v156, v147
	v_max3_u32 v148, v148, v154, v155
	v_cmp_ne_u32_e32 vcc, v157, v147
	v_cndmask_b32_e64 v156, 0, v156, s[100:101]
	v_cmp_ne_u32_e64 s[98:99], v158, v147
	v_cndmask_b32_e32 v157, 0, v157, vcc
	v_max3_u32 v148, v148, v156, v157
	v_cndmask_b32_e64 v158, 0, v158, s[98:99]
	v_cmp_ne_u32_e64 s[100:101], v159, v147
	v_cmp_ne_u32_e32 vcc, v160, v147
	v_cmp_ne_u32_e64 s[98:99], v161, v147
	v_cndmask_b32_e64 v159, 0, v159, s[100:101]
	v_max3_u32 v148, v148, v158, v159
	v_cndmask_b32_e32 v160, 0, v160, vcc
	v_cndmask_b32_e64 v161, 0, v161, s[98:99]
	v_cmp_ne_u32_e64 s[100:101], v162, v147
	v_max3_u32 v148, v148, v160, v161
	v_cmp_ne_u32_e32 vcc, v164, v147
	v_cndmask_b32_e64 v162, 0, v162, s[100:101]
	v_cmp_ne_u32_e64 s[98:99], v0, v147
	v_cndmask_b32_e32 v164, 0, v164, vcc
	v_max3_u32 v148, v148, v162, v164
	v_cndmask_b32_e64 v0, 0, v0, s[98:99]
	v_cmp_ne_u32_e64 s[100:101], v1, v147
	v_cmp_ne_u32_e32 vcc, v2, v147
	v_cmp_ne_u32_e64 s[98:99], v3, v147
	v_cndmask_b32_e64 v1, 0, v1, s[100:101]
	v_max3_u32 v148, v148, v0, v1
	v_cndmask_b32_e32 v2, 0, v2, vcc
	v_cndmask_b32_e64 v3, 0, v3, s[98:99]
	v_max3_u32 v148, v148, v2, v3
	ds_bpermute_b32 v166, v111, v148
	s_waitcnt lgkmcnt(0)
; DI void peer_topk_wave(const Params& p, int item, unsigned* lds  ) {
;     ...
; #pragma unroll
;     for (int rr = 0; rr < 16; ++rr) {
;       unsigned m = 0;
; #pragma unroll
;       for (int i = 0; i < 32; ++i) m = umax(m, kk[i]);
;       m = umax(m, (unsigned)__shfl_xor((int)m, 16));
;       m = umax(m, (unsigned)__shfl_xor((int)m, 32));
;       win[pp][rr] = m;
; #pragma unroll
;       for (int i = 0; i < 32; ++i) kk[i] = (kk[i] == m) ? 0u : kk[i];
;     }
	v_max_u32_e32 v148, v148, v166
	ds_bpermute_b32 v166, v112, v148
	s_waitcnt lgkmcnt(0)
	v_max_u32_e32 v148, v148, v166
	v_cmp_ne_u32_e32 vcc, v4, v148
	v_cmp_ne_u32_e64 s[98:99], v5, v148
	v_cmp_ne_u32_e64 s[100:101], v6, v148
	v_cndmask_b32_e32 v4, 0, v4, vcc
	v_cndmask_b32_e64 v5, 0, v5, s[98:99]
	v_cndmask_b32_e64 v6, 0, v6, s[100:101]
	v_cmp_ne_u32_e32 vcc, v7, v148
	v_cmp_ne_u32_e64 s[98:99], v8, v148
	v_cmp_ne_u32_e64 s[100:101], v9, v148
	v_cndmask_b32_e32 v7, 0, v7, vcc
	v_cndmask_b32_e64 v8, 0, v8, s[98:99]
	v_cndmask_b32_e64 v9, 0, v9, s[100:101]
	v_cmp_ne_u32_e32 vcc, v10, v148
	v_cmp_ne_u32_e64 s[98:99], v11, v148
	v_cmp_ne_u32_e64 s[100:101], v12, v148
	v_cndmask_b32_e32 v10, 0, v10, vcc
	v_cndmask_b32_e64 v11, 0, v11, s[98:99]
	v_cndmask_b32_e64 v12, 0, v12, s[100:101]
	v_cmp_ne_u32_e32 vcc, v13, v148
	v_cmp_ne_u32_e64 s[98:99], v14, v148
	v_cmp_ne_u32_e64 s[100:101], v15, v148
	v_cndmask_b32_e32 v13, 0, v13, vcc
	v_cndmask_b32_e64 v14, 0, v14, s[98:99]
	v_cndmask_b32_e64 v15, 0, v15, s[100:101]
	v_cmp_ne_u32_e32 vcc, v165, v148
	v_cmp_ne_u32_e64 s[98:99], v149, v148
	v_cmp_ne_u32_e64 s[100:101], v150, v148
	v_cndmask_b32_e32 v165, 0, v165, vcc
	v_cndmask_b32_e64 v166, 0, v149, s[98:99]
	v_max_u32_e32 v149, v4, v5
	v_max3_u32 v149, v149, v6, v7
	v_cndmask_b32_e64 v150, 0, v150, s[100:101]
	v_cmp_ne_u32_e32 vcc, v151, v148
	v_max3_u32 v149, v149, v8, v9
	v_max3_u32 v149, v149, v10, v11
	v_cndmask_b32_e32 v151, 0, v151, vcc
	v_cmp_ne_u32_e64 s[98:99], v152, v148
	v_max3_u32 v149, v149, v12, v13
	v_max3_u32 v149, v149, v14, v15
	v_cndmask_b32_e64 v152, 0, v152, s[98:99]
	v_cmp_ne_u32_e64 s[100:101], v153, v148
	v_max3_u32 v149, v149, v165, v166
	v_max3_u32 v149, v149, v150, v151
	v_cndmask_b32_e64 v153, 0, v153, s[100:101]
	v_cmp_ne_u32_e32 vcc, v154, v148
	v_max3_u32 v149, v149, v152, v153
	v_cmp_ne_u32_e64 s[98:99], v155, v148
	v_cndmask_b32_e32 v154, 0, v154, vcc
	v_cmp_ne_u32_e64 s[100:101], v156, v148
	v_cndmask_b32_e64 v155, 0, v155, s[98:99]
	v_max3_u32 v149, v149, v154, v155
	v_cndmask_b32_e64 v156, 0, v156, s[100:101]
	v_cmp_ne_u32_e32 vcc, v157, v148
	v_cmp_ne_u32_e64 s[98:99], v158, v148
	v_cmp_ne_u32_e64 s[100:101], v159, v148
	v_cndmask_b32_e32 v157, 0, v157, vcc
	v_max3_u32 v149, v149, v156, v157
	v_cndmask_b32_e64 v158, 0, v158, s[98:99]
	v_cndmask_b32_e64 v159, 0, v159, s[100:101]
	v_cmp_ne_u32_e32 vcc, v160, v148
	v_max3_u32 v149, v149, v158, v159
	v_cmp_ne_u32_e64 s[98:99], v161, v148
	v_cndmask_b32_e32 v160, 0, v160, vcc
	v_cmp_ne_u32_e64 s[100:101], v162, v148
	v_cndmask_b32_e64 v161, 0, v161, s[98:99]
	v_max3_u32 v149, v149, v160, v161
	v_cndmask_b32_e64 v162, 0, v162, s[100:101]
	v_cmp_ne_u32_e32 vcc, v164, v148
	v_cmp_ne_u32_e64 s[98:99], v0, v148
	v_cmp_ne_u32_e64 s[100:101], v1, v148
	v_cndmask_b32_e32 v164, 0, v164, vcc
	v_max3_u32 v149, v149, v162, v164
	v_cndmask_b32_e64 v0, 0, v0, s[98:99]
	v_cndmask_b32_e64 v1, 0, v1, s[100:101]
	v_cmp_ne_u32_e32 vcc, v2, v148
	v_max3_u32 v149, v149, v0, v1
	v_cmp_ne_u32_e64 s[98:99], v3, v148
	v_cndmask_b32_e32 v2, 0, v2, vcc
	s_nop 0
	v_cndmask_b32_e64 v3, 0, v3, s[98:99]
	v_max3_u32 v149, v149, v2, v3
	ds_bpermute_b32 v167, v111, v149
	s_waitcnt lgkmcnt(0)
	v_max_u32_e32 v149, v149, v167
	ds_bpermute_b32 v167, v112, v149
	s_waitcnt lgkmcnt(0)
	v_max_u32_e32 v149, v149, v167
	v_cmp_ne_u32_e32 vcc, v4, v149
	v_cmp_ne_u32_e64 s[98:99], v5, v149
	v_cmp_ne_u32_e64 s[100:101], v6, v149
	v_cndmask_b32_e32 v4, 0, v4, vcc
	v_cndmask_b32_e64 v5, 0, v5, s[98:99]
	v_cndmask_b32_e64 v6, 0, v6, s[100:101]
	v_cmp_ne_u32_e32 vcc, v7, v149
	v_cmp_ne_u32_e64 s[98:99], v8, v149
	v_cmp_ne_u32_e64 s[100:101], v9, v149
	v_cndmask_b32_e32 v7, 0, v7, vcc
	v_cndmask_b32_e64 v8, 0, v8, s[98:99]
	v_cndmask_b32_e64 v9, 0, v9, s[100:101]
	v_cmp_ne_u32_e32 vcc, v10, v149
	v_cmp_ne_u32_e64 s[98:99], v11, v149
	v_cmp_ne_u32_e64 s[100:101], v12, v149
	v_cndmask_b32_e32 v10, 0, v10, vcc
	v_cndmask_b32_e64 v11, 0, v11, s[98:99]
	v_cndmask_b32_e64 v12, 0, v12, s[100:101]
	v_cmp_ne_u32_e32 vcc, v13, v149
	v_cmp_ne_u32_e64 s[98:99], v14, v149
	v_cmp_ne_u32_e64 s[100:101], v15, v149
	v_cndmask_b32_e32 v13, 0, v13, vcc
	v_cndmask_b32_e64 v14, 0, v14, s[98:99]
	v_cndmask_b32_e64 v15, 0, v15, s[100:101]
	v_cmp_ne_u32_e32 vcc, v165, v149
	v_cmp_ne_u32_e64 s[98:99], v166, v149
	v_cmp_ne_u32_e64 s[100:101], v150, v149
	v_cndmask_b32_e32 v165, 0, v165, vcc
	v_cndmask_b32_e64 v166, 0, v166, s[98:99]
	v_cndmask_b32_e64 v167, 0, v150, s[100:101]
	v_cmp_ne_u32_e32 vcc, v151, v149
	v_max_u32_e32 v150, v4, v5
	v_max3_u32 v150, v150, v6, v7
	v_cndmask_b32_e32 v151, 0, v151, vcc
	v_cmp_ne_u32_e64 s[98:99], v152, v149
	v_max3_u32 v150, v150, v8, v9
	v_max3_u32 v150, v150, v10, v11
	v_cndmask_b32_e64 v152, 0, v152, s[98:99]
	v_cmp_ne_u32_e64 s[100:101], v153, v149
	v_max3_u32 v150, v150, v12, v13
	v_max3_u32 v150, v150, v14, v15
	v_cndmask_b32_e64 v153, 0, v153, s[100:101]
	v_cmp_ne_u32_e32 vcc, v154, v149
	v_max3_u32 v150, v150, v165, v166
	v_max3_u32 v150, v150, v167, v151
	v_cndmask_b32_e32 v154, 0, v154, vcc
	v_cmp_ne_u32_e64 s[98:99], v155, v149
	v_max3_u32 v150, v150, v152, v153
	v_cmp_ne_u32_e64 s[100:101], v156, v149
	v_cndmask_b32_e64 v155, 0, v155, s[98:99]
	v_max3_u32 v150, v150, v154, v155
	v_cndmask_b32_e64 v156, 0, v156, s[100:101]
	v_cmp_ne_u32_e32 vcc, v157, v149
	v_cmp_ne_u32_e64 s[98:99], v158, v149
	v_cmp_ne_u32_e64 s[100:101], v159, v149
	v_cndmask_b32_e32 v157, 0, v157, vcc
	v_max3_u32 v150, v150, v156, v157
	v_cndmask_b32_e64 v158, 0, v158, s[98:99]
	v_cndmask_b32_e64 v159, 0, v159, s[100:101]
	v_cmp_ne_u32_e32 vcc, v160, v149
	v_max3_u32 v150, v150, v158, v159
	v_cmp_ne_u32_e64 s[98:99], v161, v149
	v_cndmask_b32_e32 v160, 0, v160, vcc
	v_cmp_ne_u32_e64 s[100:101], v162, v149
	v_cndmask_b32_e64 v161, 0, v161, s[98:99]
	v_max3_u32 v150, v150, v160, v161
	v_cndmask_b32_e64 v162, 0, v162, s[100:101]
	v_cmp_ne_u32_e32 vcc, v164, v149
	v_cmp_ne_u32_e64 s[98:99], v0, v149
	v_cmp_ne_u32_e64 s[100:101], v1, v149
	v_cndmask_b32_e32 v164, 0, v164, vcc
	v_max3_u32 v150, v150, v162, v164
	v_cndmask_b32_e64 v0, 0, v0, s[98:99]
	v_cndmask_b32_e64 v1, 0, v1, s[100:101]
	v_cmp_ne_u32_e32 vcc, v2, v149
	v_max3_u32 v150, v150, v0, v1
	v_cmp_ne_u32_e64 s[98:99], v3, v149
	v_cndmask_b32_e32 v2, 0, v2, vcc
	s_nop 0
	v_cndmask_b32_e64 v3, 0, v3, s[98:99]
	v_max3_u32 v150, v150, v2, v3
	ds_bpermute_b32 v168, v111, v150
	s_waitcnt lgkmcnt(0)
; DI void peer_topk_wave(const Params& p, int item, unsigned* lds  ) {
;     ...
; #pragma unroll
;     for (int rr = 0; rr < 16; ++rr) {
;       unsigned m = 0;
; #pragma unroll
;       for (int i = 0; i < 32; ++i) m = umax(m, kk[i]);
;       m = umax(m, (unsigned)__shfl_xor((int)m, 16));
;       m = umax(m, (unsigned)__shfl_xor((int)m, 32));
;       win[pp][rr] = m;
; #pragma unroll
;       for (int i = 0; i < 32; ++i) kk[i] = (kk[i] == m) ? 0u : kk[i];
;     }
	v_max_u32_e32 v150, v150, v168
	ds_bpermute_b32 v168, v112, v150
	s_waitcnt lgkmcnt(0)
	v_max_u32_e32 v150, v150, v168
	v_cmp_ne_u32_e32 vcc, v4, v150
	v_cmp_ne_u32_e64 s[98:99], v5, v150
	v_cmp_ne_u32_e64 s[100:101], v6, v150
	v_cndmask_b32_e32 v4, 0, v4, vcc
	v_cndmask_b32_e64 v5, 0, v5, s[98:99]
	v_cndmask_b32_e64 v6, 0, v6, s[100:101]
	v_cmp_ne_u32_e32 vcc, v7, v150
	v_cmp_ne_u32_e64 s[98:99], v8, v150
	v_cmp_ne_u32_e64 s[100:101], v9, v150
	v_cndmask_b32_e32 v7, 0, v7, vcc
	v_cndmask_b32_e64 v8, 0, v8, s[98:99]
	v_cndmask_b32_e64 v9, 0, v9, s[100:101]
	v_cmp_ne_u32_e32 vcc, v10, v150
	v_cmp_ne_u32_e64 s[98:99], v11, v150
	v_cmp_ne_u32_e64 s[100:101], v12, v150
	v_cndmask_b32_e32 v10, 0, v10, vcc
	v_cndmask_b32_e64 v11, 0, v11, s[98:99]
	v_cndmask_b32_e64 v12, 0, v12, s[100:101]
	v_cmp_ne_u32_e32 vcc, v13, v150
	v_cmp_ne_u32_e64 s[98:99], v14, v150
	v_cmp_ne_u32_e64 s[100:101], v15, v150
	v_cndmask_b32_e32 v13, 0, v13, vcc
	v_cndmask_b32_e64 v14, 0, v14, s[98:99]
	v_cndmask_b32_e64 v15, 0, v15, s[100:101]
	v_cmp_ne_u32_e32 vcc, v165, v150
	v_cmp_ne_u32_e64 s[98:99], v166, v150
	v_cmp_ne_u32_e64 s[100:101], v167, v150
	v_cndmask_b32_e32 v165, 0, v165, vcc
	v_cndmask_b32_e64 v166, 0, v166, s[98:99]
	v_cndmask_b32_e64 v167, 0, v167, s[100:101]
	v_cmp_ne_u32_e32 vcc, v151, v150
	v_cmp_ne_u32_e64 s[98:99], v152, v150
	v_cmp_ne_u32_e64 s[100:101], v153, v150
	v_cndmask_b32_e32 v168, 0, v151, vcc
	v_max_u32_e32 v151, v4, v5
	v_max3_u32 v151, v151, v6, v7
	v_cndmask_b32_e64 v152, 0, v152, s[98:99]
	v_max3_u32 v151, v151, v8, v9
	v_max3_u32 v151, v151, v10, v11
	v_cndmask_b32_e64 v153, 0, v153, s[100:101]
	v_cmp_ne_u32_e32 vcc, v154, v150
	v_max3_u32 v151, v151, v12, v13
	v_max3_u32 v151, v151, v14, v15
	v_cndmask_b32_e32 v154, 0, v154, vcc
	v_cmp_ne_u32_e64 s[98:99], v155, v150
	v_max3_u32 v151, v151, v165, v166
	v_max3_u32 v151, v151, v167, v168
	v_cndmask_b32_e64 v155, 0, v155, s[98:99]
	v_cmp_ne_u32_e64 s[100:101], v156, v150
	v_max3_u32 v151, v151, v152, v153
	v_max3_u32 v151, v151, v154, v155
	v_cndmask_b32_e64 v156, 0, v156, s[100:101]
	v_cmp_ne_u32_e32 vcc, v157, v150
	v_cmp_ne_u32_e64 s[98:99], v158, v150
	v_cmp_ne_u32_e64 s[100:101], v159, v150
	v_cndmask_b32_e32 v157, 0, v157, vcc
	v_max3_u32 v151, v151, v156, v157
	v_cndmask_b32_e64 v158, 0, v158, s[98:99]
	v_cndmask_b32_e64 v159, 0, v159, s[100:101]
	v_cmp_ne_u32_e32 vcc, v160, v150
	v_max3_u32 v151, v151, v158, v159
	v_cmp_ne_u32_e64 s[98:99], v161, v150
	v_cndmask_b32_e32 v160, 0, v160, vcc
	v_cmp_ne_u32_e64 s[100:101], v162, v150
	v_cndmask_b32_e64 v161, 0, v161, s[98:99]
	v_max3_u32 v151, v151, v160, v161
	v_cndmask_b32_e64 v162, 0, v162, s[100:101]
	v_cmp_ne_u32_e32 vcc, v164, v150
	v_cmp_ne_u32_e64 s[98:99], v0, v150
	v_cmp_ne_u32_e64 s[100:101], v1, v150
	v_cndmask_b32_e32 v164, 0, v164, vcc
	v_max3_u32 v151, v151, v162, v164
	v_cndmask_b32_e64 v0, 0, v0, s[98:99]
	v_cndmask_b32_e64 v1, 0, v1, s[100:101]
	v_cmp_ne_u32_e32 vcc, v2, v150
	v_max3_u32 v151, v151, v0, v1
	v_cmp_ne_u32_e64 s[98:99], v3, v150
	v_cndmask_b32_e32 v2, 0, v2, vcc
	s_nop 0
	v_cndmask_b32_e64 v3, 0, v3, s[98:99]
	v_max3_u32 v151, v151, v2, v3
	ds_bpermute_b32 v169, v111, v151
	s_waitcnt lgkmcnt(0)
	v_max_u32_e32 v151, v151, v169
	ds_bpermute_b32 v169, v112, v151
	s_waitcnt lgkmcnt(0)
	v_max_u32_e32 v151, v151, v169
	v_cmp_ne_u32_e32 vcc, v4, v151
	v_cmp_ne_u32_e64 s[98:99], v5, v151
	v_cmp_ne_u32_e64 s[100:101], v6, v151
	v_cndmask_b32_e32 v4, 0, v4, vcc
	v_cndmask_b32_e64 v5, 0, v5, s[98:99]
	v_cndmask_b32_e64 v6, 0, v6, s[100:101]
	v_cmp_ne_u32_e32 vcc, v7, v151
	v_cmp_ne_u32_e64 s[98:99], v8, v151
	v_cmp_ne_u32_e64 s[100:101], v9, v151
	v_cndmask_b32_e32 v7, 0, v7, vcc
	v_cndmask_b32_e64 v8, 0, v8, s[98:99]
	v_cndmask_b32_e64 v9, 0, v9, s[100:101]
	v_cmp_ne_u32_e32 vcc, v10, v151
	v_cmp_ne_u32_e64 s[98:99], v11, v151
	v_cmp_ne_u32_e64 s[100:101], v12, v151
	v_cndmask_b32_e32 v10, 0, v10, vcc
	v_cndmask_b32_e64 v11, 0, v11, s[98:99]
	v_cndmask_b32_e64 v12, 0, v12, s[100:101]
	v_cmp_ne_u32_e32 vcc, v13, v151
	v_cmp_ne_u32_e64 s[98:99], v14, v151
	v_cmp_ne_u32_e64 s[100:101], v15, v151
	v_cndmask_b32_e32 v13, 0, v13, vcc
	v_cndmask_b32_e64 v14, 0, v14, s[98:99]
	v_cndmask_b32_e64 v15, 0, v15, s[100:101]
	v_cmp_ne_u32_e32 vcc, v165, v151
	v_cmp_ne_u32_e64 s[98:99], v166, v151
	v_cmp_ne_u32_e64 s[100:101], v167, v151
	v_cndmask_b32_e32 v165, 0, v165, vcc
	v_cndmask_b32_e64 v166, 0, v166, s[98:99]
	v_cndmask_b32_e64 v167, 0, v167, s[100:101]
	v_cmp_ne_u32_e32 vcc, v168, v151
	v_cmp_ne_u32_e64 s[98:99], v152, v151
	v_cmp_ne_u32_e64 s[100:101], v153, v151
	v_cndmask_b32_e32 v168, 0, v168, vcc
	v_cndmask_b32_e64 v169, 0, v152, s[98:99]
	v_max_u32_e32 v152, v4, v5
	v_max3_u32 v152, v152, v6, v7
	v_cndmask_b32_e64 v153, 0, v153, s[100:101]
	v_cmp_ne_u32_e32 vcc, v154, v151
	v_max3_u32 v152, v152, v8, v9
	v_max3_u32 v152, v152, v10, v11
	v_cndmask_b32_e32 v154, 0, v154, vcc
	v_cmp_ne_u32_e64 s[98:99], v155, v151
	v_max3_u32 v152, v152, v12, v13
	v_max3_u32 v152, v152, v14, v15
	v_cndmask_b32_e64 v155, 0, v155, s[98:99]
	v_cmp_ne_u32_e64 s[100:101], v156, v151
	v_max3_u32 v152, v152, v165, v166
	v_max3_u32 v152, v152, v167, v168
	v_cndmask_b32_e64 v156, 0, v156, s[100:101]
	v_cmp_ne_u32_e32 vcc, v157, v151
	v_max3_u32 v152, v152, v169, v153
	v_max3_u32 v152, v152, v154, v155
	v_cndmask_b32_e32 v157, 0, v157, vcc
	v_cmp_ne_u32_e64 s[98:99], v158, v151
	v_max3_u32 v152, v152, v156, v157
	v_cmp_ne_u32_e64 s[100:101], v159, v151
	v_cndmask_b32_e64 v158, 0, v158, s[98:99]
	v_cmp_ne_u32_e32 vcc, v160, v151
	v_cndmask_b32_e64 v159, 0, v159, s[100:101]
	v_max3_u32 v152, v152, v158, v159
	v_cndmask_b32_e32 v160, 0, v160, vcc
	v_cmp_ne_u32_e64 s[98:99], v161, v151
	v_cmp_ne_u32_e64 s[100:101], v162, v151
	v_cmp_ne_u32_e32 vcc, v164, v151
	v_cndmask_b32_e64 v161, 0, v161, s[98:99]
	v_max3_u32 v152, v152, v160, v161
	v_cndmask_b32_e64 v162, 0, v162, s[100:101]
	v_cndmask_b32_e32 v164, 0, v164, vcc
	v_cmp_ne_u32_e64 s[98:99], v0, v151
	v_max3_u32 v152, v152, v162, v164
	v_cmp_ne_u32_e64 s[100:101], v1, v151
	v_cndmask_b32_e64 v0, 0, v0, s[98:99]
	v_cmp_ne_u32_e32 vcc, v2, v151
	v_cndmask_b32_e64 v1, 0, v1, s[100:101]
	v_max3_u32 v152, v152, v0, v1
	v_cndmask_b32_e32 v2, 0, v2, vcc
	v_cmp_ne_u32_e64 s[98:99], v3, v151
	s_nop 0
	s_nop 0
	v_cndmask_b32_e64 v3, 0, v3, s[98:99]
	v_max3_u32 v152, v152, v2, v3
	ds_bpermute_b32 v171, v111, v152
	s_waitcnt lgkmcnt(0)
; DI void peer_topk_wave(const Params& p, int item, unsigned* lds  ) {
;     ...
; #pragma unroll
;     for (int rr = 0; rr < 16; ++rr) {
;       unsigned m = 0;
; #pragma unroll
;       for (int i = 0; i < 32; ++i) m = umax(m, kk[i]);
;       m = umax(m, (unsigned)__shfl_xor((int)m, 16));
;       m = umax(m, (unsigned)__shfl_xor((int)m, 32));
;       win[pp][rr] = m;
; #pragma unroll
;       for (int i = 0; i < 32; ++i) kk[i] = (kk[i] == m) ? 0u : kk[i];
;     }
	v_max_u32_e32 v152, v152, v171
	ds_bpermute_b32 v171, v112, v152
	s_waitcnt lgkmcnt(0)
	v_max_u32_e32 v152, v152, v171
	v_cmp_ne_u32_e32 vcc, v4, v152
	v_cmp_ne_u32_e64 s[98:99], v5, v152
	v_cmp_ne_u32_e64 s[100:101], v6, v152
	v_cndmask_b32_e32 v4, 0, v4, vcc
	v_cndmask_b32_e64 v5, 0, v5, s[98:99]
	v_cndmask_b32_e64 v6, 0, v6, s[100:101]
	v_cmp_ne_u32_e32 vcc, v7, v152
	v_cmp_ne_u32_e64 s[98:99], v8, v152
	v_cmp_ne_u32_e64 s[100:101], v9, v152
	v_cndmask_b32_e32 v7, 0, v7, vcc
	v_cndmask_b32_e64 v8, 0, v8, s[98:99]
	v_cndmask_b32_e64 v9, 0, v9, s[100:101]
	v_cmp_ne_u32_e32 vcc, v10, v152
	v_cmp_ne_u32_e64 s[98:99], v11, v152
	v_cmp_ne_u32_e64 s[100:101], v12, v152
	v_cndmask_b32_e32 v10, 0, v10, vcc
	v_cndmask_b32_e64 v11, 0, v11, s[98:99]
	v_cndmask_b32_e64 v12, 0, v12, s[100:101]
	v_cmp_ne_u32_e32 vcc, v13, v152
	v_cmp_ne_u32_e64 s[98:99], v14, v152
	v_cmp_ne_u32_e64 s[100:101], v15, v152
	v_cndmask_b32_e32 v13, 0, v13, vcc
	v_cndmask_b32_e64 v14, 0, v14, s[98:99]
	v_cndmask_b32_e64 v15, 0, v15, s[100:101]
	v_cmp_ne_u32_e32 vcc, v165, v152
	v_cmp_ne_u32_e64 s[98:99], v166, v152
	v_cmp_ne_u32_e64 s[100:101], v167, v152
	v_cndmask_b32_e32 v165, 0, v165, vcc
	v_cndmask_b32_e64 v166, 0, v166, s[98:99]
	v_cndmask_b32_e64 v167, 0, v167, s[100:101]
	v_cmp_ne_u32_e32 vcc, v168, v152
	v_cmp_ne_u32_e64 s[98:99], v169, v152
	v_cmp_ne_u32_e64 s[100:101], v153, v152
	v_cndmask_b32_e32 v168, 0, v168, vcc
	v_cndmask_b32_e64 v169, 0, v169, s[98:99]
	v_cndmask_b32_e64 v171, 0, v153, s[100:101]
	v_cmp_ne_u32_e32 vcc, v154, v152
	v_max_u32_e32 v153, v4, v5
	v_max3_u32 v153, v153, v6, v7
	v_cndmask_b32_e32 v154, 0, v154, vcc
	v_cmp_ne_u32_e64 s[98:99], v155, v152
	v_max3_u32 v153, v153, v8, v9
	v_max3_u32 v153, v153, v10, v11
	v_cndmask_b32_e64 v155, 0, v155, s[98:99]
	v_cmp_ne_u32_e64 s[100:101], v156, v152
	v_max3_u32 v153, v153, v12, v13
	v_max3_u32 v153, v153, v14, v15
	v_cndmask_b32_e64 v156, 0, v156, s[100:101]
	v_cmp_ne_u32_e32 vcc, v157, v152
	v_max3_u32 v153, v153, v165, v166
	v_max3_u32 v153, v153, v167, v168
	v_cndmask_b32_e32 v157, 0, v157, vcc
	v_cmp_ne_u32_e64 s[98:99], v158, v152
	v_max3_u32 v153, v153, v169, v171
	v_max3_u32 v153, v153, v154, v155
	v_cndmask_b32_e64 v158, 0, v158, s[98:99]
	v_cmp_ne_u32_e64 s[100:101], v159, v152
	v_max3_u32 v153, v153, v156, v157
	v_cmp_ne_u32_e32 vcc, v160, v152
	v_cndmask_b32_e64 v159, 0, v159, s[100:101]
	v_max3_u32 v153, v153, v158, v159
	v_cndmask_b32_e32 v160, 0, v160, vcc
	v_cmp_ne_u32_e64 s[98:99], v161, v152
	v_cmp_ne_u32_e64 s[100:101], v162, v152
	v_cmp_ne_u32_e32 vcc, v164, v152
	v_cndmask_b32_e64 v161, 0, v161, s[98:99]
	v_max3_u32 v153, v153, v160, v161
	v_cndmask_b32_e64 v162, 0, v162, s[100:101]
	v_cndmask_b32_e32 v164, 0, v164, vcc
	v_cmp_ne_u32_e64 s[98:99], v0, v152
	v_max3_u32 v153, v153, v162, v164
	v_cmp_ne_u32_e64 s[100:101], v1, v152
	v_cndmask_b32_e64 v0, 0, v0, s[98:99]
	v_cmp_ne_u32_e32 vcc, v2, v152
	v_cndmask_b32_e64 v1, 0, v1, s[100:101]
	v_max3_u32 v153, v153, v0, v1
	v_cndmask_b32_e32 v2, 0, v2, vcc
	v_cmp_ne_u32_e64 s[98:99], v3, v152
	s_nop 0
	s_nop 0
	v_cndmask_b32_e64 v3, 0, v3, s[98:99]
	v_max3_u32 v153, v153, v2, v3
	ds_bpermute_b32 v172, v111, v153
	s_waitcnt lgkmcnt(0)
	v_max_u32_e32 v153, v153, v172
	ds_bpermute_b32 v172, v112, v153
	s_waitcnt lgkmcnt(0)
	v_max_u32_e32 v153, v153, v172
	v_cmp_ne_u32_e32 vcc, v4, v153
	v_cmp_ne_u32_e64 s[98:99], v5, v153
	v_cmp_ne_u32_e64 s[100:101], v6, v153
	v_cndmask_b32_e32 v4, 0, v4, vcc
	v_cndmask_b32_e64 v5, 0, v5, s[98:99]
	v_cndmask_b32_e64 v6, 0, v6, s[100:101]
	v_cmp_ne_u32_e32 vcc, v7, v153
	v_cmp_ne_u32_e64 s[98:99], v8, v153
	v_cmp_ne_u32_e64 s[100:101], v9, v153
	v_cndmask_b32_e32 v7, 0, v7, vcc
	v_cndmask_b32_e64 v8, 0, v8, s[98:99]
	v_cndmask_b32_e64 v9, 0, v9, s[100:101]
	v_cmp_ne_u32_e32 vcc, v10, v153
	v_cmp_ne_u32_e64 s[98:99], v11, v153
	v_cmp_ne_u32_e64 s[100:101], v12, v153
	v_cndmask_b32_e32 v10, 0, v10, vcc
	v_cndmask_b32_e64 v11, 0, v11, s[98:99]
	v_cndmask_b32_e64 v12, 0, v12, s[100:101]
	v_cmp_ne_u32_e32 vcc, v13, v153
	v_cmp_ne_u32_e64 s[98:99], v14, v153
	v_cmp_ne_u32_e64 s[100:101], v15, v153
	v_cndmask_b32_e32 v13, 0, v13, vcc
	v_cndmask_b32_e64 v14, 0, v14, s[98:99]
	v_cndmask_b32_e64 v15, 0, v15, s[100:101]
	v_cmp_ne_u32_e32 vcc, v165, v153
	v_cmp_ne_u32_e64 s[98:99], v166, v153
	v_cmp_ne_u32_e64 s[100:101], v167, v153
	v_cndmask_b32_e32 v165, 0, v165, vcc
	v_cndmask_b32_e64 v166, 0, v166, s[98:99]
	v_cndmask_b32_e64 v167, 0, v167, s[100:101]
	v_cmp_ne_u32_e32 vcc, v168, v153
	v_cmp_ne_u32_e64 s[98:99], v169, v153
	v_cmp_ne_u32_e64 s[100:101], v171, v153
	v_cndmask_b32_e32 v168, 0, v168, vcc
	v_cndmask_b32_e64 v169, 0, v169, s[98:99]
	v_cndmask_b32_e64 v171, 0, v171, s[100:101]
	v_cmp_ne_u32_e32 vcc, v154, v153
	v_cmp_ne_u32_e64 s[98:99], v155, v153
	v_cmp_ne_u32_e64 s[100:101], v156, v153
	v_cndmask_b32_e32 v172, 0, v154, vcc
	v_max_u32_e32 v154, v4, v5
	v_max3_u32 v154, v154, v6, v7
	v_max3_u32 v154, v154, v8, v9
	v_cndmask_b32_e64 v155, 0, v155, s[98:99]
	v_max3_u32 v154, v154, v10, v11
	v_max3_u32 v154, v154, v12, v13
	v_cndmask_b32_e64 v156, 0, v156, s[100:101]
	v_cmp_ne_u32_e32 vcc, v157, v153
	v_max3_u32 v154, v154, v14, v15
	v_max3_u32 v154, v154, v165, v166
	v_cndmask_b32_e32 v157, 0, v157, vcc
	v_cmp_ne_u32_e64 s[98:99], v158, v153
	v_max3_u32 v154, v154, v167, v168
	v_max3_u32 v154, v154, v169, v171
	v_cndmask_b32_e64 v158, 0, v158, s[98:99]
	v_cmp_ne_u32_e64 s[100:101], v159, v153
	v_max3_u32 v154, v154, v172, v155
	v_max3_u32 v154, v154, v156, v157
	v_cndmask_b32_e64 v159, 0, v159, s[100:101]
	v_cmp_ne_u32_e32 vcc, v160, v153
	v_max3_u32 v154, v154, v158, v159
	v_cmp_ne_u32_e64 s[98:99], v161, v153
	v_cndmask_b32_e32 v160, 0, v160, vcc
	v_cmp_ne_u32_e64 s[100:101], v162, v153
	v_cndmask_b32_e64 v161, 0, v161, s[98:99]
	v_max3_u32 v154, v154, v160, v161
	v_cndmask_b32_e64 v162, 0, v162, s[100:101]
	v_cmp_ne_u32_e32 vcc, v164, v153
	v_cmp_ne_u32_e64 s[98:99], v0, v153
	v_cmp_ne_u32_e64 s[100:101], v1, v153
	v_cndmask_b32_e32 v164, 0, v164, vcc
	v_max3_u32 v154, v154, v162, v164
	v_cndmask_b32_e64 v0, 0, v0, s[98:99]
	v_cndmask_b32_e64 v1, 0, v1, s[100:101]
	v_cmp_ne_u32_e32 vcc, v2, v153
	v_max3_u32 v154, v154, v0, v1
	v_cmp_ne_u32_e64 s[98:99], v3, v153
	v_cndmask_b32_e32 v2, 0, v2, vcc
	s_nop 0
	v_cndmask_b32_e64 v3, 0, v3, s[98:99]
	v_max3_u32 v154, v154, v2, v3
	ds_bpermute_b32 v173, v111, v154
	s_waitcnt lgkmcnt(0)
; DI void peer_topk_wave(const Params& p, int item, unsigned* lds  ) {
;     ...
; #pragma unroll
;     for (int rr = 0; rr < 16; ++rr) {
;       unsigned m = 0;
; #pragma unroll
;       for (int i = 0; i < 32; ++i) m = umax(m, kk[i]);
;       m = umax(m, (unsigned)__shfl_xor((int)m, 16));
;       m = umax(m, (unsigned)__shfl_xor((int)m, 32));
;       win[pp][rr] = m;
; #pragma unroll
;       for (int i = 0; i < 32; ++i) kk[i] = (kk[i] == m) ? 0u : kk[i];
;     }
	v_max_u32_e32 v154, v154, v173
	ds_bpermute_b32 v173, v112, v154
	s_waitcnt lgkmcnt(0)
	v_max_u32_e32 v154, v154, v173
	v_cmp_ne_u32_e32 vcc, v4, v154
	v_cmp_ne_u32_e64 s[98:99], v5, v154
	v_cmp_ne_u32_e64 s[100:101], v6, v154
	v_cndmask_b32_e32 v4, 0, v4, vcc
	v_cndmask_b32_e64 v5, 0, v5, s[98:99]
	v_cndmask_b32_e64 v6, 0, v6, s[100:101]
	v_cmp_ne_u32_e32 vcc, v7, v154
	v_cmp_ne_u32_e64 s[98:99], v8, v154
	v_cmp_ne_u32_e64 s[100:101], v9, v154
	v_cndmask_b32_e32 v7, 0, v7, vcc
	v_cndmask_b32_e64 v8, 0, v8, s[98:99]
	v_cndmask_b32_e64 v9, 0, v9, s[100:101]
	v_cmp_ne_u32_e32 vcc, v10, v154
	v_cmp_ne_u32_e64 s[98:99], v11, v154
	v_cmp_ne_u32_e64 s[100:101], v12, v154
	v_cndmask_b32_e32 v10, 0, v10, vcc
	v_cndmask_b32_e64 v11, 0, v11, s[98:99]
	v_cndmask_b32_e64 v12, 0, v12, s[100:101]
	v_cmp_ne_u32_e32 vcc, v13, v154
	v_cmp_ne_u32_e64 s[98:99], v14, v154
	v_cmp_ne_u32_e64 s[100:101], v15, v154
	v_cndmask_b32_e32 v13, 0, v13, vcc
	v_cndmask_b32_e64 v14, 0, v14, s[98:99]
	v_cndmask_b32_e64 v15, 0, v15, s[100:101]
	v_cmp_ne_u32_e32 vcc, v165, v154
	v_cmp_ne_u32_e64 s[98:99], v166, v154
	v_cmp_ne_u32_e64 s[100:101], v167, v154
	v_cndmask_b32_e32 v165, 0, v165, vcc
	v_cndmask_b32_e64 v166, 0, v166, s[98:99]
	v_cndmask_b32_e64 v167, 0, v167, s[100:101]
	v_cmp_ne_u32_e32 vcc, v168, v154
	v_cmp_ne_u32_e64 s[98:99], v169, v154
	v_cmp_ne_u32_e64 s[100:101], v171, v154
	v_cndmask_b32_e32 v168, 0, v168, vcc
	v_cndmask_b32_e64 v169, 0, v169, s[98:99]
	v_cndmask_b32_e64 v171, 0, v171, s[100:101]
	v_cmp_ne_u32_e32 vcc, v172, v154
	v_cmp_ne_u32_e64 s[98:99], v155, v154
	v_cmp_ne_u32_e64 s[100:101], v156, v154
	v_cndmask_b32_e32 v172, 0, v172, vcc
	v_cndmask_b32_e64 v173, 0, v155, s[98:99]
	v_max_u32_e32 v155, v4, v5
	v_max3_u32 v155, v155, v6, v7
	v_max3_u32 v155, v155, v8, v9
	v_max3_u32 v155, v155, v10, v11
	v_cndmask_b32_e64 v156, 0, v156, s[100:101]
	v_cmp_ne_u32_e32 vcc, v157, v154
	v_max3_u32 v155, v155, v12, v13
	v_max3_u32 v155, v155, v14, v15
	v_cndmask_b32_e32 v157, 0, v157, vcc
	v_cmp_ne_u32_e64 s[98:99], v158, v154
	v_max3_u32 v155, v155, v165, v166
	v_max3_u32 v155, v155, v167, v168
	v_cndmask_b32_e64 v158, 0, v158, s[98:99]
	v_cmp_ne_u32_e64 s[100:101], v159, v154
	v_max3_u32 v155, v155, v169, v171
	v_max3_u32 v155, v155, v172, v173
	v_cndmask_b32_e64 v159, 0, v159, s[100:101]
	v_cmp_ne_u32_e32 vcc, v160, v154
	v_max3_u32 v155, v155, v156, v157
	v_max3_u32 v155, v155, v158, v159
	v_cndmask_b32_e32 v160, 0, v160, vcc
	v_cmp_ne_u32_e64 s[98:99], v161, v154
	v_cmp_ne_u32_e64 s[100:101], v162, v154
	v_cmp_ne_u32_e32 vcc, v164, v154
	v_cndmask_b32_e64 v161, 0, v161, s[98:99]
	v_max3_u32 v155, v155, v160, v161
	v_cndmask_b32_e64 v162, 0, v162, s[100:101]
	v_cndmask_b32_e32 v164, 0, v164, vcc
	v_cmp_ne_u32_e64 s[98:99], v0, v154
	v_max3_u32 v155, v155, v162, v164
	v_cmp_ne_u32_e64 s[100:101], v1, v154
	v_cndmask_b32_e64 v0, 0, v0, s[98:99]
	v_cmp_ne_u32_e32 vcc, v2, v154
	v_cndmask_b32_e64 v1, 0, v1, s[100:101]
	v_max3_u32 v155, v155, v0, v1
	v_cndmask_b32_e32 v2, 0, v2, vcc
	v_cmp_ne_u32_e64 s[98:99], v3, v154
	s_nop 0
	s_nop 0
	v_cndmask_b32_e64 v3, 0, v3, s[98:99]
	v_max3_u32 v155, v155, v2, v3
	ds_bpermute_b32 v176, v111, v155
	s_waitcnt lgkmcnt(0)
	v_max_u32_e32 v155, v155, v176
	ds_bpermute_b32 v176, v112, v155
	s_waitcnt lgkmcnt(0)
	v_max_u32_e32 v155, v155, v176
	v_cmp_ne_u32_e32 vcc, v4, v155
	v_cmp_ne_u32_e64 s[98:99], v5, v155
	v_cmp_ne_u32_e64 s[100:101], v6, v155
	v_cndmask_b32_e32 v4, 0, v4, vcc
	v_cndmask_b32_e64 v5, 0, v5, s[98:99]
	v_cndmask_b32_e64 v6, 0, v6, s[100:101]
	v_cmp_ne_u32_e32 vcc, v7, v155
	v_cmp_ne_u32_e64 s[98:99], v8, v155
	v_cmp_ne_u32_e64 s[100:101], v9, v155
	v_cndmask_b32_e32 v7, 0, v7, vcc
	v_cndmask_b32_e64 v8, 0, v8, s[98:99]
	v_cndmask_b32_e64 v9, 0, v9, s[100:101]
	v_cmp_ne_u32_e32 vcc, v10, v155
	v_cmp_ne_u32_e64 s[98:99], v11, v155
	v_cmp_ne_u32_e64 s[100:101], v12, v155
	v_cndmask_b32_e32 v10, 0, v10, vcc
	v_cndmask_b32_e64 v11, 0, v11, s[98:99]
	v_cndmask_b32_e64 v12, 0, v12, s[100:101]
	v_cmp_ne_u32_e32 vcc, v13, v155
	v_cmp_ne_u32_e64 s[98:99], v14, v155
	v_cmp_ne_u32_e64 s[100:101], v15, v155
	v_cndmask_b32_e32 v13, 0, v13, vcc
	v_cndmask_b32_e64 v14, 0, v14, s[98:99]
	v_cndmask_b32_e64 v15, 0, v15, s[100:101]
	v_cmp_ne_u32_e32 vcc, v165, v155
	v_cmp_ne_u32_e64 s[98:99], v166, v155
	v_cmp_ne_u32_e64 s[100:101], v167, v155
	v_cndmask_b32_e32 v165, 0, v165, vcc
	v_cndmask_b32_e64 v166, 0, v166, s[98:99]
	v_cndmask_b32_e64 v167, 0, v167, s[100:101]
	v_cmp_ne_u32_e32 vcc, v168, v155
	v_cmp_ne_u32_e64 s[98:99], v169, v155
	v_cmp_ne_u32_e64 s[100:101], v171, v155
	v_cndmask_b32_e32 v168, 0, v168, vcc
	v_cndmask_b32_e64 v169, 0, v169, s[98:99]
	v_cndmask_b32_e64 v171, 0, v171, s[100:101]
	v_cmp_ne_u32_e32 vcc, v172, v155
	v_cmp_ne_u32_e64 s[98:99], v173, v155
	v_cmp_ne_u32_e64 s[100:101], v156, v155
	v_cndmask_b32_e32 v172, 0, v172, vcc
	v_cndmask_b32_e64 v173, 0, v173, s[98:99]
	v_cndmask_b32_e64 v176, 0, v156, s[100:101]
	v_max_u32_e32 v156, v4, v5
	v_max3_u32 v156, v156, v6, v7
	v_max3_u32 v156, v156, v8, v9
	v_cmp_ne_u32_e32 vcc, v157, v155
	v_max3_u32 v156, v156, v10, v11
	v_max3_u32 v156, v156, v12, v13
	v_cndmask_b32_e32 v157, 0, v157, vcc
	v_cmp_ne_u32_e64 s[98:99], v158, v155
	v_max3_u32 v156, v156, v14, v15
	v_max3_u32 v156, v156, v165, v166
	v_cndmask_b32_e64 v158, 0, v158, s[98:99]
	v_cmp_ne_u32_e64 s[100:101], v159, v155
	v_max3_u32 v156, v156, v167, v168
	v_max3_u32 v156, v156, v169, v171
	v_cndmask_b32_e64 v159, 0, v159, s[100:101]
	v_cmp_ne_u32_e32 vcc, v160, v155
	v_max3_u32 v156, v156, v172, v173
	v_max3_u32 v156, v156, v176, v157
	v_cndmask_b32_e32 v160, 0, v160, vcc
	v_cmp_ne_u32_e64 s[98:99], v161, v155
	v_max3_u32 v156, v156, v158, v159
	v_cmp_ne_u32_e64 s[100:101], v162, v155
	v_cndmask_b32_e64 v161, 0, v161, s[98:99]
	v_max3_u32 v156, v156, v160, v161
	v_cndmask_b32_e64 v162, 0, v162, s[100:101]
	v_cmp_ne_u32_e32 vcc, v164, v155
	v_cmp_ne_u32_e64 s[98:99], v0, v155
	v_cmp_ne_u32_e64 s[100:101], v1, v155
	v_cndmask_b32_e32 v164, 0, v164, vcc
	v_max3_u32 v156, v156, v162, v164
	v_cndmask_b32_e64 v0, 0, v0, s[98:99]
	v_cndmask_b32_e64 v1, 0, v1, s[100:101]
	v_cmp_ne_u32_e32 vcc, v2, v155
	v_max3_u32 v156, v156, v0, v1
	v_cmp_ne_u32_e64 s[98:99], v3, v155
	v_cndmask_b32_e32 v2, 0, v2, vcc
	s_nop 0
	v_cndmask_b32_e64 v3, 0, v3, s[98:99]
	v_max3_u32 v156, v156, v2, v3
	ds_bpermute_b32 v177, v111, v156
	s_waitcnt lgkmcnt(0)
; DI void peer_topk_wave(const Params& p, int item, unsigned* lds  ) {
;     ...
; #pragma unroll
;     for (int rr = 0; rr < 16; ++rr) {
;       unsigned m = 0;
; #pragma unroll
;       for (int i = 0; i < 32; ++i) m = umax(m, kk[i]);
;       m = umax(m, (unsigned)__shfl_xor((int)m, 16));
;       m = umax(m, (unsigned)__shfl_xor((int)m, 32));
;       win[pp][rr] = m;
; #pragma unroll
;       for (int i = 0; i < 32; ++i) kk[i] = (kk[i] == m) ? 0u : kk[i];
;     }
	v_max_u32_e32 v156, v156, v177
	ds_bpermute_b32 v177, v112, v156
	s_waitcnt lgkmcnt(0)
	v_max_u32_e32 v156, v156, v177
	v_cmp_ne_u32_e32 vcc, v4, v156
	v_cmp_ne_u32_e64 s[98:99], v5, v156
	v_cmp_ne_u32_e64 s[100:101], v6, v156
	v_cndmask_b32_e32 v4, 0, v4, vcc
	v_cndmask_b32_e64 v5, 0, v5, s[98:99]
	v_cndmask_b32_e64 v6, 0, v6, s[100:101]
	v_cmp_ne_u32_e32 vcc, v7, v156
	v_cmp_ne_u32_e64 s[98:99], v8, v156
	v_cmp_ne_u32_e64 s[100:101], v9, v156
	v_cndmask_b32_e32 v7, 0, v7, vcc
	v_cndmask_b32_e64 v8, 0, v8, s[98:99]
	v_cndmask_b32_e64 v9, 0, v9, s[100:101]
	v_cmp_ne_u32_e32 vcc, v10, v156
	v_cmp_ne_u32_e64 s[98:99], v11, v156
	v_cmp_ne_u32_e64 s[100:101], v12, v156
	v_cndmask_b32_e32 v10, 0, v10, vcc
	v_cndmask_b32_e64 v11, 0, v11, s[98:99]
	v_cndmask_b32_e64 v12, 0, v12, s[100:101]
	v_cmp_ne_u32_e32 vcc, v13, v156
	v_cmp_ne_u32_e64 s[98:99], v14, v156
	v_cmp_ne_u32_e64 s[100:101], v15, v156
	v_cndmask_b32_e32 v13, 0, v13, vcc
	v_cndmask_b32_e64 v14, 0, v14, s[98:99]
	v_cndmask_b32_e64 v15, 0, v15, s[100:101]
	v_cmp_ne_u32_e32 vcc, v165, v156
	v_cmp_ne_u32_e64 s[98:99], v166, v156
	v_cmp_ne_u32_e64 s[100:101], v167, v156
	v_cndmask_b32_e32 v165, 0, v165, vcc
	v_cndmask_b32_e64 v166, 0, v166, s[98:99]
	v_cndmask_b32_e64 v167, 0, v167, s[100:101]
	v_cmp_ne_u32_e32 vcc, v168, v156
	v_cmp_ne_u32_e64 s[98:99], v169, v156
	v_cmp_ne_u32_e64 s[100:101], v171, v156
	v_cndmask_b32_e32 v168, 0, v168, vcc
	v_cndmask_b32_e64 v169, 0, v169, s[98:99]
	v_cndmask_b32_e64 v171, 0, v171, s[100:101]
	v_cmp_ne_u32_e32 vcc, v172, v156
	v_cmp_ne_u32_e64 s[98:99], v173, v156
	v_cmp_ne_u32_e64 s[100:101], v176, v156
	v_cndmask_b32_e32 v172, 0, v172, vcc
	v_cndmask_b32_e64 v173, 0, v173, s[98:99]
	v_cndmask_b32_e64 v176, 0, v176, s[100:101]
	v_cmp_ne_u32_e32 vcc, v157, v156
	v_cmp_ne_u32_e64 s[98:99], v158, v156
	v_cmp_ne_u32_e64 s[100:101], v159, v156
	v_cndmask_b32_e32 v177, 0, v157, vcc
	v_max_u32_e32 v157, v4, v5
	v_max3_u32 v157, v157, v6, v7
	v_max3_u32 v157, v157, v8, v9
	v_max3_u32 v157, v157, v10, v11
	v_max3_u32 v157, v157, v12, v13
	v_max3_u32 v157, v157, v14, v15
	v_cndmask_b32_e64 v158, 0, v158, s[98:99]
	v_max3_u32 v157, v157, v165, v166
	v_max3_u32 v157, v157, v167, v168
	v_cndmask_b32_e64 v159, 0, v159, s[100:101]
	v_cmp_ne_u32_e32 vcc, v160, v156
	v_max3_u32 v157, v157, v169, v171
	v_max3_u32 v157, v157, v172, v173
	v_cndmask_b32_e32 v160, 0, v160, vcc
	v_cmp_ne_u32_e64 s[98:99], v161, v156
	v_max3_u32 v157, v157, v176, v177
	v_max3_u32 v157, v157, v158, v159
	v_cndmask_b32_e64 v161, 0, v161, s[98:99]
	v_cmp_ne_u32_e64 s[100:101], v162, v156
	v_max3_u32 v157, v157, v160, v161
	v_cmp_ne_u32_e32 vcc, v164, v156
	v_cndmask_b32_e64 v162, 0, v162, s[100:101]
	v_cmp_ne_u32_e64 s[98:99], v0, v156
	v_cndmask_b32_e32 v164, 0, v164, vcc
	v_max3_u32 v157, v157, v162, v164
	v_cndmask_b32_e64 v0, 0, v0, s[98:99]
	v_cmp_ne_u32_e64 s[100:101], v1, v156
	v_cmp_ne_u32_e32 vcc, v2, v156
	v_cmp_ne_u32_e64 s[98:99], v3, v156
	v_cndmask_b32_e64 v1, 0, v1, s[100:101]
	v_max3_u32 v157, v157, v0, v1
	v_cndmask_b32_e32 v2, 0, v2, vcc
	v_cndmask_b32_e64 v3, 0, v3, s[98:99]
	v_max3_u32 v157, v157, v2, v3
	ds_bpermute_b32 v178, v111, v157
	s_waitcnt lgkmcnt(0)
	v_max_u32_e32 v157, v157, v178
	ds_bpermute_b32 v178, v112, v157
	s_waitcnt lgkmcnt(0)
	v_max_u32_e32 v157, v157, v178
	v_cmp_ne_u32_e32 vcc, v4, v157
	v_cmp_ne_u32_e64 s[98:99], v5, v157
	v_cmp_ne_u32_e64 s[100:101], v6, v157
	v_cndmask_b32_e32 v4, 0, v4, vcc
	v_cndmask_b32_e64 v5, 0, v5, s[98:99]
	v_cndmask_b32_e64 v6, 0, v6, s[100:101]
	v_cmp_ne_u32_e32 vcc, v7, v157
	v_cmp_ne_u32_e64 s[98:99], v8, v157
	v_cmp_ne_u32_e64 s[100:101], v9, v157
	v_cndmask_b32_e32 v7, 0, v7, vcc
	v_cndmask_b32_e64 v8, 0, v8, s[98:99]
	v_cndmask_b32_e64 v9, 0, v9, s[100:101]
	v_cmp_ne_u32_e32 vcc, v10, v157
	v_cmp_ne_u32_e64 s[98:99], v11, v157
	v_cmp_ne_u32_e64 s[100:101], v12, v157
	v_cndmask_b32_e32 v10, 0, v10, vcc
	v_cndmask_b32_e64 v11, 0, v11, s[98:99]
	v_cndmask_b32_e64 v12, 0, v12, s[100:101]
	v_cmp_ne_u32_e32 vcc, v13, v157
	v_cmp_ne_u32_e64 s[98:99], v14, v157
	v_cmp_ne_u32_e64 s[100:101], v15, v157
	v_cndmask_b32_e32 v13, 0, v13, vcc
	v_cndmask_b32_e64 v14, 0, v14, s[98:99]
	v_cndmask_b32_e64 v15, 0, v15, s[100:101]
	v_cmp_ne_u32_e32 vcc, v165, v157
	v_cmp_ne_u32_e64 s[98:99], v166, v157
	v_cmp_ne_u32_e64 s[100:101], v167, v157
	v_cndmask_b32_e32 v165, 0, v165, vcc
	v_cndmask_b32_e64 v166, 0, v166, s[98:99]
	v_cndmask_b32_e64 v167, 0, v167, s[100:101]
	v_cmp_ne_u32_e32 vcc, v168, v157
	v_cmp_ne_u32_e64 s[98:99], v169, v157
	v_cmp_ne_u32_e64 s[100:101], v171, v157
	v_cndmask_b32_e32 v168, 0, v168, vcc
	v_cndmask_b32_e64 v169, 0, v169, s[98:99]
	v_cndmask_b32_e64 v171, 0, v171, s[100:101]
	v_cmp_ne_u32_e32 vcc, v172, v157
	v_cmp_ne_u32_e64 s[98:99], v173, v157
	v_cmp_ne_u32_e64 s[100:101], v176, v157
	v_cndmask_b32_e32 v172, 0, v172, vcc
	v_cndmask_b32_e64 v173, 0, v173, s[98:99]
	v_cndmask_b32_e64 v176, 0, v176, s[100:101]
	v_cmp_ne_u32_e32 vcc, v177, v157
	v_cmp_ne_u32_e64 s[98:99], v158, v157
	v_cmp_ne_u32_e64 s[100:101], v159, v157
	v_cndmask_b32_e32 v177, 0, v177, vcc
	v_cndmask_b32_e64 v178, 0, v158, s[98:99]
	v_max_u32_e32 v158, v4, v5
	v_max3_u32 v158, v158, v6, v7
	v_max3_u32 v158, v158, v8, v9
	v_max3_u32 v158, v158, v10, v11
	v_max3_u32 v158, v158, v12, v13
	v_max3_u32 v158, v158, v14, v15
	v_max3_u32 v158, v158, v165, v166
	v_cndmask_b32_e64 v159, 0, v159, s[100:101]
	v_cmp_ne_u32_e32 vcc, v160, v157
	v_max3_u32 v158, v158, v167, v168
	v_max3_u32 v158, v158, v169, v171
	v_cndmask_b32_e32 v160, 0, v160, vcc
	v_cmp_ne_u32_e64 s[98:99], v161, v157
	v_max3_u32 v158, v158, v172, v173
	v_max3_u32 v158, v158, v176, v177
	v_cndmask_b32_e64 v161, 0, v161, s[98:99]
	v_cmp_ne_u32_e64 s[100:101], v162, v157
	v_max3_u32 v158, v158, v178, v159
	v_max3_u32 v158, v158, v160, v161
	v_cndmask_b32_e64 v162, 0, v162, s[100:101]
	v_cmp_ne_u32_e32 vcc, v164, v157
	v_cmp_ne_u32_e64 s[98:99], v0, v157
	v_cmp_ne_u32_e64 s[100:101], v1, v157
	v_cndmask_b32_e32 v164, 0, v164, vcc
	v_max3_u32 v158, v158, v162, v164
	v_cndmask_b32_e64 v0, 0, v0, s[98:99]
	v_cndmask_b32_e64 v1, 0, v1, s[100:101]
	v_cmp_ne_u32_e32 vcc, v2, v157
	v_max3_u32 v158, v158, v0, v1
	v_cmp_ne_u32_e64 s[98:99], v3, v157
	v_cndmask_b32_e32 v2, 0, v2, vcc
	s_nop 0
	v_cndmask_b32_e64 v3, 0, v3, s[98:99]
	v_max3_u32 v158, v158, v2, v3
	ds_bpermute_b32 v179, v111, v158
	s_waitcnt lgkmcnt(0)
; DI void peer_topk_wave(const Params& p, int item, unsigned* lds  ) {
;     ...
; #pragma unroll
;     for (int rr = 0; rr < 16; ++rr) {
;       unsigned m = 0;
; #pragma unroll
;       for (int i = 0; i < 32; ++i) m = umax(m, kk[i]);
;       m = umax(m, (unsigned)__shfl_xor((int)m, 16));
;       m = umax(m, (unsigned)__shfl_xor((int)m, 32));
;       win[pp][rr] = m;
; #pragma unroll
;       for (int i = 0; i < 32; ++i) kk[i] = (kk[i] == m) ? 0u : kk[i];
;     }
	v_max_u32_e32 v158, v158, v179
	ds_bpermute_b32 v179, v112, v158
	s_waitcnt lgkmcnt(0)
	v_max_u32_e32 v158, v158, v179
	v_cmp_ne_u32_e32 vcc, v4, v158
	v_cmp_ne_u32_e64 s[98:99], v5, v158
	v_cmp_ne_u32_e64 s[100:101], v6, v158
	v_cndmask_b32_e32 v4, 0, v4, vcc
	v_cndmask_b32_e64 v5, 0, v5, s[98:99]
	v_cndmask_b32_e64 v6, 0, v6, s[100:101]
	v_cmp_ne_u32_e32 vcc, v7, v158
	v_cmp_ne_u32_e64 s[98:99], v8, v158
	v_cmp_ne_u32_e64 s[100:101], v9, v158
	v_cndmask_b32_e32 v7, 0, v7, vcc
	v_cndmask_b32_e64 v8, 0, v8, s[98:99]
	v_cndmask_b32_e64 v9, 0, v9, s[100:101]
	v_cmp_ne_u32_e32 vcc, v10, v158
	v_cmp_ne_u32_e64 s[98:99], v11, v158
	v_cmp_ne_u32_e64 s[100:101], v12, v158
	v_cndmask_b32_e32 v10, 0, v10, vcc
	v_cndmask_b32_e64 v11, 0, v11, s[98:99]
	v_cndmask_b32_e64 v12, 0, v12, s[100:101]
	v_cmp_ne_u32_e32 vcc, v13, v158
	v_cmp_ne_u32_e64 s[98:99], v14, v158
	v_cmp_ne_u32_e64 s[100:101], v15, v158
	v_cndmask_b32_e32 v13, 0, v13, vcc
	v_cndmask_b32_e64 v14, 0, v14, s[98:99]
	v_cndmask_b32_e64 v15, 0, v15, s[100:101]
	v_cmp_ne_u32_e32 vcc, v165, v158
	v_cmp_ne_u32_e64 s[98:99], v166, v158
	v_cmp_ne_u32_e64 s[100:101], v167, v158
	v_cndmask_b32_e32 v165, 0, v165, vcc
	v_cndmask_b32_e64 v166, 0, v166, s[98:99]
	v_cndmask_b32_e64 v167, 0, v167, s[100:101]
	v_cmp_ne_u32_e32 vcc, v168, v158
	v_cmp_ne_u32_e64 s[98:99], v169, v158
	v_cmp_ne_u32_e64 s[100:101], v171, v158
	v_cndmask_b32_e32 v168, 0, v168, vcc
	v_cndmask_b32_e64 v169, 0, v169, s[98:99]
	v_cndmask_b32_e64 v171, 0, v171, s[100:101]
	v_cmp_ne_u32_e32 vcc, v172, v158
	v_cmp_ne_u32_e64 s[98:99], v173, v158
	v_cmp_ne_u32_e64 s[100:101], v176, v158
	v_cndmask_b32_e32 v172, 0, v172, vcc
	v_cndmask_b32_e64 v173, 0, v173, s[98:99]
	v_cndmask_b32_e64 v176, 0, v176, s[100:101]
	v_cmp_ne_u32_e32 vcc, v177, v158
	v_cmp_ne_u32_e64 s[98:99], v178, v158
	v_cmp_ne_u32_e64 s[100:101], v159, v158
	v_cndmask_b32_e32 v177, 0, v177, vcc
	v_cndmask_b32_e64 v178, 0, v178, s[98:99]
	v_cndmask_b32_e64 v179, 0, v159, s[100:101]
	v_max_u32_e32 v159, v4, v5
	v_max3_u32 v159, v159, v6, v7
	v_max3_u32 v159, v159, v8, v9
	v_max3_u32 v159, v159, v10, v11
	v_max3_u32 v159, v159, v12, v13
	v_max3_u32 v159, v159, v14, v15
	v_cmp_ne_u32_e32 vcc, v160, v158
	v_max3_u32 v159, v159, v165, v166
	v_max3_u32 v159, v159, v167, v168
	v_cndmask_b32_e32 v160, 0, v160, vcc
	v_cmp_ne_u32_e64 s[98:99], v161, v158
	v_max3_u32 v159, v159, v169, v171
	v_max3_u32 v159, v159, v172, v173
	v_cndmask_b32_e64 v161, 0, v161, s[98:99]
	v_cmp_ne_u32_e64 s[100:101], v162, v158
	v_max3_u32 v159, v159, v176, v177
	v_max3_u32 v159, v159, v178, v179
	v_cndmask_b32_e64 v162, 0, v162, s[100:101]
	v_cmp_ne_u32_e32 vcc, v164, v158
	v_max3_u32 v159, v159, v160, v161
	v_cmp_ne_u32_e64 s[98:99], v0, v158
	v_cndmask_b32_e32 v164, 0, v164, vcc
	v_max3_u32 v159, v159, v162, v164
	v_cndmask_b32_e64 v0, 0, v0, s[98:99]
	v_cmp_ne_u32_e64 s[100:101], v1, v158
	v_cmp_ne_u32_e32 vcc, v2, v158
	v_cmp_ne_u32_e64 s[98:99], v3, v158
	v_cndmask_b32_e64 v1, 0, v1, s[100:101]
	v_max3_u32 v159, v159, v0, v1
	v_cndmask_b32_e32 v2, 0, v2, vcc
	v_cndmask_b32_e64 v3, 0, v3, s[98:99]
	v_max3_u32 v159, v159, v2, v3
	ds_bpermute_b32 v180, v111, v159
	s_waitcnt lgkmcnt(0)
	v_max_u32_e32 v159, v159, v180
	ds_bpermute_b32 v180, v112, v159
	s_waitcnt lgkmcnt(0)
	v_max_u32_e32 v159, v159, v180
	v_cmp_ne_u32_e32 vcc, v4, v159
	v_cmp_ne_u32_e64 s[98:99], v5, v159
	v_cmp_ne_u32_e64 s[100:101], v6, v159
	v_cndmask_b32_e32 v4, 0, v4, vcc
	v_cndmask_b32_e64 v5, 0, v5, s[98:99]
	v_cndmask_b32_e64 v6, 0, v6, s[100:101]
	v_cmp_ne_u32_e32 vcc, v7, v159
	v_cmp_ne_u32_e64 s[98:99], v8, v159
	v_cmp_ne_u32_e64 s[100:101], v9, v159
	v_cndmask_b32_e32 v7, 0, v7, vcc
	v_cndmask_b32_e64 v8, 0, v8, s[98:99]
	v_cndmask_b32_e64 v9, 0, v9, s[100:101]
	v_cmp_ne_u32_e32 vcc, v10, v159
	v_cmp_ne_u32_e64 s[98:99], v11, v159
	v_cmp_ne_u32_e64 s[100:101], v12, v159
	v_cndmask_b32_e32 v10, 0, v10, vcc
	v_cndmask_b32_e64 v11, 0, v11, s[98:99]
	v_cndmask_b32_e64 v12, 0, v12, s[100:101]
	v_cmp_ne_u32_e32 vcc, v13, v159
	v_cmp_ne_u32_e64 s[98:99], v14, v159
	v_cmp_ne_u32_e64 s[100:101], v15, v159
	v_cndmask_b32_e32 v13, 0, v13, vcc
	v_cndmask_b32_e64 v14, 0, v14, s[98:99]
	v_cndmask_b32_e64 v15, 0, v15, s[100:101]
	v_cmp_ne_u32_e32 vcc, v165, v159
	v_cmp_ne_u32_e64 s[98:99], v166, v159
	v_cmp_ne_u32_e64 s[100:101], v167, v159
	v_cndmask_b32_e32 v165, 0, v165, vcc
	v_cndmask_b32_e64 v166, 0, v166, s[98:99]
	v_cndmask_b32_e64 v167, 0, v167, s[100:101]
	v_cmp_ne_u32_e32 vcc, v168, v159
	v_cmp_ne_u32_e64 s[98:99], v169, v159
	v_cmp_ne_u32_e64 s[100:101], v171, v159
	v_cndmask_b32_e32 v168, 0, v168, vcc
	v_cndmask_b32_e64 v169, 0, v169, s[98:99]
	v_cndmask_b32_e64 v171, 0, v171, s[100:101]
	v_cmp_ne_u32_e32 vcc, v172, v159
	v_cmp_ne_u32_e64 s[98:99], v173, v159
	v_cmp_ne_u32_e64 s[100:101], v176, v159
	v_cndmask_b32_e32 v172, 0, v172, vcc
	v_cndmask_b32_e64 v173, 0, v173, s[98:99]
	v_cndmask_b32_e64 v176, 0, v176, s[100:101]
	v_cmp_ne_u32_e32 vcc, v177, v159
	v_cmp_ne_u32_e64 s[98:99], v178, v159
	v_cmp_ne_u32_e64 s[100:101], v179, v159
	v_cndmask_b32_e32 v177, 0, v177, vcc
	v_cndmask_b32_e64 v178, 0, v178, s[98:99]
	v_cndmask_b32_e64 v179, 0, v179, s[100:101]
	v_cmp_ne_u32_e32 vcc, v160, v159
	v_cmp_ne_u32_e64 s[98:99], v161, v159
	v_cmp_ne_u32_e64 s[100:101], v162, v159
	v_cndmask_b32_e32 v180, 0, v160, vcc
	v_max_u32_e32 v160, v4, v5
	v_max3_u32 v160, v160, v6, v7
	v_max3_u32 v160, v160, v8, v9
	v_max3_u32 v160, v160, v10, v11
	v_max3_u32 v160, v160, v12, v13
	v_max3_u32 v160, v160, v14, v15
	v_max3_u32 v160, v160, v165, v166
	v_max3_u32 v160, v160, v167, v168
	v_max3_u32 v160, v160, v169, v171
	v_cndmask_b32_e64 v161, 0, v161, s[98:99]
	v_max3_u32 v160, v160, v172, v173
	v_max3_u32 v160, v160, v176, v177
	v_cndmask_b32_e64 v162, 0, v162, s[100:101]
	v_cmp_ne_u32_e32 vcc, v164, v159
	v_max3_u32 v160, v160, v178, v179
	v_max3_u32 v160, v160, v180, v161
	v_cndmask_b32_e32 v164, 0, v164, vcc
	v_cmp_ne_u32_e64 s[98:99], v0, v159
	v_max3_u32 v160, v160, v162, v164
	v_cmp_ne_u32_e64 s[100:101], v1, v159
	v_cndmask_b32_e64 v0, 0, v0, s[98:99]
	v_cmp_ne_u32_e32 vcc, v2, v159
	v_cndmask_b32_e64 v1, 0, v1, s[100:101]
	v_max3_u32 v160, v160, v0, v1
	v_cndmask_b32_e32 v2, 0, v2, vcc
	v_cmp_ne_u32_e64 s[98:99], v3, v159
	s_nop 0
	s_nop 0
	v_cndmask_b32_e64 v3, 0, v3, s[98:99]
	v_max3_u32 v160, v160, v2, v3
	ds_bpermute_b32 v181, v111, v160
	s_waitcnt lgkmcnt(0)
; #define MFMA(a, b, c) __builtin_amdgcn_mfma_f32_16x16x32_bf16((a), (b), (c), 0, 0, 0)
; DI unsigned ordf(float f) { unsigned u = __float_as_uint(f); return (u & 0x80000000u) ? ~u : (u | 0x80000000u); }
; DI void peer_topk_wave(const Params& p, int item, unsigned* lds  ) {
;     ...
;     for (int ks = 0; ks < 4; ++ks) qf[ks] = *(const bf16x8*)&p.pq[(size_t)(row0 + r) * 2048 + h * 256 + pp * 128 + ks * 32 + kg * 8];
;     unsigned kk[32];
;     const u16* sk = p.subkb + (size_t)(h * 2 + pp) * 16384;
; #pragma unroll
;     for (int mt = 0; mt < 8; ++mt) {
;       f32x4 a = (f32x4){0.f, 0.f, 0.f, 0.f};
; #pragma unroll
;       for (int ks = 0; ks < 4; ++ks) {
;         bf16x8 kf = *(const bf16x8*)&sk[(mt * 16 + r) * 128 + ks * 32 + kg * 8];
;         a = MFMA(kf, qf[ks], a);
;       }
; #pragma unroll
;       for (int j = 0; j < 4; ++j) kk[mt * 4 + j] = (ordf(a[j]) & ~127u) | (unsigned)(mt * 16 + kg * 4 + j);
;     ...
; #pragma unroll
;     for (int rr = 0; rr < 16; ++rr) {
;       unsigned m = 0;
; #pragma unroll
;       for (int i = 0; i < 32; ++i) m = umax(m, kk[i]);
;       m = umax(m, (unsigned)__shfl_xor((int)m, 16));
;       m = umax(m, (unsigned)__shfl_xor((int)m, 32));
;       win[pp][rr] = m;
; #pragma unroll
;       for (int i = 0; i < 32; ++i) kk[i] = (kk[i] == m) ? 0u : kk[i];
;     }
	v_max_u32_e32 v160, v160, v181
	ds_bpermute_b32 v181, v112, v160
	s_waitcnt lgkmcnt(0)
	v_max_u32_e32 v160, v160, v181
	v_cmp_ne_u32_e64 s[0:1], v5, v160
	v_cmp_eq_u32_e32 vcc, v4, v160
	v_cmp_eq_u32_e64 s[2:3], v7, v160
	v_cndmask_b32_e64 v5, 0, v5, s[0:1]
	v_max_u32_e32 v4, v4, v5
	v_cndmask_b32_e32 v4, v4, v5, vcc
	v_cmp_eq_u32_e64 s[0:1], v6, v160
	v_max_u32_e32 v5, v4, v6
	v_cmp_eq_u32_e64 s[14:15], v8, v160
	v_cndmask_b32_e64 v4, v5, v4, s[0:1]
	v_max_u32_e32 v5, v4, v7
	v_cndmask_b32_e64 v4, v5, v4, s[2:3]
	v_max_u32_e32 v5, v4, v8
	v_cndmask_b32_e64 v4, v5, v4, s[14:15]
	v_cmp_eq_u32_e64 s[16:17], v9, v160
	v_max_u32_e32 v5, v4, v9
	v_cmp_eq_u32_e64 s[18:19], v10, v160
	v_cndmask_b32_e64 v4, v5, v4, s[16:17]
	v_max_u32_e32 v5, v4, v10
	v_cndmask_b32_e64 v4, v5, v4, s[18:19]
	v_cmp_eq_u32_e64 s[20:21], v11, v160
	v_max_u32_e32 v5, v4, v11
	v_cmp_eq_u32_e64 s[22:23], v12, v160
	v_cndmask_b32_e64 v4, v5, v4, s[20:21]
	v_max_u32_e32 v5, v4, v12
	v_cndmask_b32_e64 v4, v5, v4, s[22:23]
	v_cmp_eq_u32_e64 s[24:25], v13, v160
	v_max_u32_e32 v5, v4, v13
	v_cmp_eq_u32_e64 s[26:27], v14, v160
	v_cndmask_b32_e64 v4, v5, v4, s[24:25]
	v_max_u32_e32 v5, v4, v14
	v_cndmask_b32_e64 v4, v5, v4, s[26:27]
	v_cmp_eq_u32_e64 s[28:29], v15, v160
	v_max_u32_e32 v5, v4, v15
	v_cmp_eq_u32_e64 s[30:31], v165, v160
	v_cndmask_b32_e64 v4, v5, v4, s[28:29]
	v_max_u32_e32 v5, v4, v165
	v_cndmask_b32_e64 v4, v5, v4, s[30:31]
	v_cmp_eq_u32_e64 s[34:35], v166, v160
	v_max_u32_e32 v5, v4, v166
	v_cmp_eq_u32_e64 s[36:37], v167, v160
	v_cndmask_b32_e64 v4, v5, v4, s[34:35]
	v_max_u32_e32 v5, v4, v167
	v_cndmask_b32_e64 v4, v5, v4, s[36:37]
	v_cmp_eq_u32_e64 s[38:39], v168, v160
	v_max_u32_e32 v5, v4, v168
	v_cmp_eq_u32_e64 s[40:41], v169, v160
	v_cndmask_b32_e64 v4, v5, v4, s[38:39]
	v_max_u32_e32 v5, v4, v169
	v_cndmask_b32_e64 v4, v5, v4, s[40:41]
	v_cmp_eq_u32_e64 s[42:43], v171, v160
	v_max_u32_e32 v5, v4, v171
	v_cmp_eq_u32_e64 s[44:45], v172, v160
	v_cndmask_b32_e64 v4, v5, v4, s[42:43]
	v_max_u32_e32 v5, v4, v172
	v_cndmask_b32_e64 v4, v5, v4, s[44:45]
	v_cmp_eq_u32_e64 s[46:47], v173, v160
	v_max_u32_e32 v5, v4, v173
	v_cmp_eq_u32_e64 s[48:49], v176, v160
	v_cndmask_b32_e64 v4, v5, v4, s[46:47]
	v_max_u32_e32 v5, v4, v176
	v_cndmask_b32_e64 v4, v5, v4, s[48:49]
	v_cmp_eq_u32_e64 s[50:51], v177, v160
	v_max_u32_e32 v5, v4, v177
	v_cmp_eq_u32_e64 s[52:53], v178, v160
	v_cndmask_b32_e64 v4, v5, v4, s[50:51]
	v_max_u32_e32 v5, v4, v178
	v_cndmask_b32_e64 v4, v5, v4, s[52:53]
	v_cmp_eq_u32_e64 s[54:55], v179, v160
	v_max_u32_e32 v5, v4, v179
	v_cmp_eq_u32_e64 s[56:57], v180, v160
	v_cndmask_b32_e64 v4, v5, v4, s[54:55]
	v_max_u32_e32 v5, v4, v180
	v_cndmask_b32_e64 v4, v5, v4, s[56:57]
	v_cmp_eq_u32_e64 s[58:59], v161, v160
	v_max_u32_e32 v5, v4, v161
	v_cmp_eq_u32_e64 s[60:61], v162, v160
	v_cndmask_b32_e64 v4, v5, v4, s[58:59]
	v_max_u32_e32 v5, v4, v162
	v_cndmask_b32_e64 v4, v5, v4, s[60:61]
	v_cmp_eq_u32_e64 s[62:63], v164, v160
	v_max_u32_e32 v5, v4, v164
	v_cmp_eq_u32_e64 s[64:65], v0, v160
	v_cndmask_b32_e64 v4, v5, v4, s[62:63]
	v_max_u32_e32 v0, v4, v0
	v_cndmask_b32_e64 v0, v0, v4, s[64:65]
	v_cmp_eq_u32_e64 s[66:67], v1, v160
	v_max_u32_e32 v1, v0, v1
	v_cmp_eq_u32_e64 s[68:69], v2, v160
	v_cndmask_b32_e64 v0, v1, v0, s[66:67]
	v_max_u32_e32 v1, v0, v2
	v_cndmask_b32_e64 v0, v1, v0, s[68:69]
	v_cmp_eq_u32_e64 s[70:71], v3, v160
	v_max_u32_e32 v1, v0, v3
	v_lshl_add_u64 v[172:173], v[86:87], 0, v[24:25]
	v_cndmask_b32_e64 v0, v1, v0, s[70:71]
	ds_bpermute_b32 v1, v111, v0
	s_waitcnt lgkmcnt(0)
	v_max_u32_e32 v161, v0, v1
	flat_load_dwordx4 v[12:15], v[88:89] offset:256
	flat_load_dwordx4 v[8:11], v[88:89] offset:320
	flat_load_dwordx4 v[4:7], v[88:89] offset:384
	flat_load_dwordx4 v[0:3], v[88:89] offset:448
	ds_bpermute_b32 v162, v112, v161
	v_readfirstlane_b32 s0, v86
	v_readfirstlane_b32 s1, v87
	s_nop 3
	s_add_u32 s0, s0, 0x8000
	s_addc_u32 s1, s1, 0
	s_add_u32 s2, s0, 0x0
	s_addc_u32 s3, s1, 0
	global_load_dwordx4 v[24:27], v20, s[2:3]
	global_load_dwordx4 v[28:31], v20, s[2:3] offset:64
	global_load_dwordx4 v[32:35], v20, s[2:3] offset:128
	global_load_dwordx4 v[36:39], v20, s[2:3] offset:192
	s_add_u32 s2, s0, 0x1000
	s_addc_u32 s3, s1, 0
	global_load_dwordx4 v[40:43], v20, s[2:3]
	global_load_dwordx4 v[44:47], v20, s[2:3] offset:64
	global_load_dwordx4 v[48:51], v20, s[2:3] offset:128
	global_load_dwordx4 v[52:55], v20, s[2:3] offset:192
	s_add_u32 s2, s0, 0x2000
	s_addc_u32 s3, s1, 0
	global_load_dwordx4 v[56:59], v20, s[2:3]
	global_load_dwordx4 v[60:63], v20, s[2:3] offset:64
	global_load_dwordx4 v[64:67], v20, s[2:3] offset:128
	global_load_dwordx4 v[68:71], v20, s[2:3] offset:192
	s_add_u32 s2, s0, 0x3000
	s_addc_u32 s3, s1, 0
	global_load_dwordx4 v[72:75], v20, s[2:3]
	global_load_dwordx4 v[76:79], v20, s[2:3] offset:64
	global_load_dwordx4 v[80:83], v20, s[2:3] offset:128
	s_waitcnt vmcnt(11) lgkmcnt(0)
	v_mfma_f32_16x16x32_bf16 v[190:193], v[24:27], v[12:15], 0
	v_mfma_f32_16x16x32_bf16 v[190:193], v[28:31], v[8:11], v[190:193]
	v_mfma_f32_16x16x32_bf16 v[190:193], v[32:35], v[4:7], v[190:193]
	v_mfma_f32_16x16x32_bf16 v[190:193], v[36:39], v[0:3], v[190:193]
	global_load_dwordx4 v[24:27], v20, s[2:3] offset:192
	s_add_u32 s2, s0, 0x4000
	s_addc_u32 s3, s1, 0
	global_load_dwordx4 v[28:31], v20, s[2:3]
	global_load_dwordx4 v[32:35], v20, s[2:3] offset:64
	global_load_dwordx4 v[36:39], v20, s[2:3] offset:128
	s_waitcnt vmcnt(11)
; #define MFMA(a, b, c) __builtin_amdgcn_mfma_f32_16x16x32_bf16((a), (b), (c), 0, 0, 0)
; DI unsigned ordf(float f) { unsigned u = __float_as_uint(f); return (u & 0x80000000u) ? ~u : (u | 0x80000000u); }
; DI void peer_topk_wave(const Params& p, int item, unsigned* lds  ) {
;     ...
; #pragma unroll
;     for (int mt = 0; mt < 8; ++mt) {
;       f32x4 a = (f32x4){0.f, 0.f, 0.f, 0.f};
; #pragma unroll
;       for (int ks = 0; ks < 4; ++ks) {
;         bf16x8 kf = *(const bf16x8*)&sk[(mt * 16 + r) * 128 + ks * 32 + kg * 8];
;         a = MFMA(kf, qf[ks], a);
;       }
; #pragma unroll
;       for (int j = 0; j < 4; ++j) kk[mt * 4 + j] = (ordf(a[j]) & ~127u) | (unsigned)(mt * 16 + kg * 4 + j);
	v_mfma_f32_16x16x32_bf16 v[198:201], v[40:43], v[12:15], 0
	v_mfma_f32_16x16x32_bf16 v[198:201], v[44:47], v[8:11], v[198:201]
	v_mfma_f32_16x16x32_bf16 v[198:201], v[48:51], v[4:7], v[198:201]
	v_mfma_f32_16x16x32_bf16 v[198:201], v[52:55], v[0:3], v[198:201]
	global_load_dwordx4 v[40:43], v20, s[2:3] offset:192
	s_add_u32 s2, s0, 0x5000
	s_addc_u32 s3, s1, 0
	global_load_dwordx4 v[44:47], v20, s[2:3]
	global_load_dwordx4 v[48:51], v20, s[2:3] offset:64
	global_load_dwordx4 v[52:55], v20, s[2:3] offset:128
	s_nop 7
	s_nop 3
	v_ashrrev_i32_e32 v197, 31, v190
	v_or_b32_e32 v197, 0x80000000, v197
	v_xor_b32_e32 v197, v190, v197
	v_and_or_b32 v88, v197, s80, v170
	v_ashrrev_i32_e32 v202, 31, v191
	v_or_b32_e32 v202, 0x80000000, v202
	v_xor_b32_e32 v202, v191, v202
	v_and_or_b32 v89, v202, s80, v113
	v_ashrrev_i32_e32 v197, 31, v192
	v_or_b32_e32 v197, 0x80000000, v197
	v_xor_b32_e32 v197, v192, v197
	v_and_or_b32 v164, v197, s80, v114
	v_ashrrev_i32_e32 v202, 31, v193
	v_or_b32_e32 v202, 0x80000000, v202
	v_xor_b32_e32 v202, v193, v202
	v_and_or_b32 v165, v202, s80, v115
	s_waitcnt vmcnt(11)
	v_mfma_f32_16x16x32_bf16 v[190:193], v[56:59], v[12:15], 0
	v_mfma_f32_16x16x32_bf16 v[190:193], v[60:63], v[8:11], v[190:193]
	v_mfma_f32_16x16x32_bf16 v[190:193], v[64:67], v[4:7], v[190:193]
	v_mfma_f32_16x16x32_bf16 v[190:193], v[68:71], v[0:3], v[190:193]
	global_load_dwordx4 v[56:59], v20, s[2:3] offset:192
	s_add_u32 s2, s0, 0x6000
	s_addc_u32 s3, s1, 0
	global_load_dwordx4 v[60:63], v20, s[2:3]
	global_load_dwordx4 v[64:67], v20, s[2:3] offset:64
	global_load_dwordx4 v[68:71], v20, s[2:3] offset:128
	s_nop 7
	s_nop 3
	v_ashrrev_i32_e32 v197, 31, v198
	v_or_b32_e32 v197, 0x80000000, v197
	v_xor_b32_e32 v197, v198, v197
	v_and_or_b32 v166, v197, s80, v90
	v_ashrrev_i32_e32 v202, 31, v199
	v_or_b32_e32 v202, 0x80000000, v202
	v_xor_b32_e32 v202, v199, v202
	v_and_or_b32 v167, v202, s80, v116
	v_ashrrev_i32_e32 v197, 31, v200
	v_or_b32_e32 v197, 0x80000000, v197
	v_xor_b32_e32 v197, v200, v197
	v_and_or_b32 v168, v197, s80, v117
	v_ashrrev_i32_e32 v202, 31, v201
	v_or_b32_e32 v202, 0x80000000, v202
	v_xor_b32_e32 v202, v201, v202
	v_and_or_b32 v169, v202, s80, v118
	s_waitcnt vmcnt(11)
	v_mfma_f32_16x16x32_bf16 v[198:201], v[72:75], v[12:15], 0
	v_mfma_f32_16x16x32_bf16 v[198:201], v[76:79], v[8:11], v[198:201]
	v_mfma_f32_16x16x32_bf16 v[198:201], v[80:83], v[4:7], v[198:201]
	v_mfma_f32_16x16x32_bf16 v[198:201], v[24:27], v[0:3], v[198:201]
	global_load_dwordx4 v[72:75], v20, s[2:3] offset:192
	s_add_u32 s2, s0, 0x7000
	s_addc_u32 s3, s1, 0
	global_load_dwordx4 v[76:79], v20, s[2:3]
	global_load_dwordx4 v[80:83], v20, s[2:3] offset:64
	global_load_dwordx4 v[24:27], v20, s[2:3] offset:128
	s_nop 7
	s_nop 3
	v_ashrrev_i32_e32 v197, 31, v190
	v_or_b32_e32 v197, 0x80000000, v197
	v_xor_b32_e32 v197, v190, v197
	v_and_or_b32 v171, v197, s80, v91
	v_ashrrev_i32_e32 v202, 31, v191
	v_or_b32_e32 v202, 0x80000000, v202
	v_xor_b32_e32 v202, v191, v202
	v_and_or_b32 v172, v202, s80, v119
	v_ashrrev_i32_e32 v197, 31, v192
	v_or_b32_e32 v197, 0x80000000, v197
	v_xor_b32_e32 v197, v192, v197
	v_and_or_b32 v173, v197, s80, v120
	v_ashrrev_i32_e32 v202, 31, v193
	v_or_b32_e32 v202, 0x80000000, v202
	v_xor_b32_e32 v202, v193, v202
	v_and_or_b32 v176, v202, s80, v121
	s_waitcnt vmcnt(11)
	v_mfma_f32_16x16x32_bf16 v[190:193], v[28:31], v[12:15], 0
	v_mfma_f32_16x16x32_bf16 v[190:193], v[32:35], v[8:11], v[190:193]
	v_mfma_f32_16x16x32_bf16 v[190:193], v[36:39], v[4:7], v[190:193]
	v_mfma_f32_16x16x32_bf16 v[190:193], v[40:43], v[0:3], v[190:193]
	global_load_dwordx4 v[28:31], v20, s[2:3] offset:192
	s_nop 7
	s_nop 3
	v_ashrrev_i32_e32 v197, 31, v198
	v_or_b32_e32 v197, 0x80000000, v197
	v_xor_b32_e32 v197, v198, v197
	v_and_or_b32 v177, v197, s80, v92
	v_ashrrev_i32_e32 v202, 31, v199
	v_or_b32_e32 v202, 0x80000000, v202
	v_xor_b32_e32 v202, v199, v202
	v_and_or_b32 v178, v202, s80, v122
	v_ashrrev_i32_e32 v197, 31, v200
	v_or_b32_e32 v197, 0x80000000, v197
	v_xor_b32_e32 v197, v200, v197
	v_and_or_b32 v179, v197, s80, v123
	v_ashrrev_i32_e32 v202, 31, v201
	v_or_b32_e32 v202, 0x80000000, v202
	v_xor_b32_e32 v202, v201, v202
	v_and_or_b32 v180, v202, s80, v124
	s_waitcnt vmcnt(8)
	v_mfma_f32_16x16x32_bf16 v[198:201], v[44:47], v[12:15], 0
	v_mfma_f32_16x16x32_bf16 v[198:201], v[48:51], v[8:11], v[198:201]
	v_mfma_f32_16x16x32_bf16 v[198:201], v[52:55], v[4:7], v[198:201]
	v_mfma_f32_16x16x32_bf16 v[198:201], v[56:59], v[0:3], v[198:201]
	s_nop 7
	s_nop 3
	v_ashrrev_i32_e32 v197, 31, v190
	v_or_b32_e32 v197, 0x80000000, v197
	v_xor_b32_e32 v197, v190, v197
	v_and_or_b32 v181, v197, s80, v93
	v_ashrrev_i32_e32 v202, 31, v191
	v_or_b32_e32 v202, 0x80000000, v202
	v_xor_b32_e32 v202, v191, v202
	v_and_or_b32 v182, v202, s80, v125
	v_ashrrev_i32_e32 v197, 31, v192
	v_or_b32_e32 v197, 0x80000000, v197
	v_xor_b32_e32 v197, v192, v197
	v_and_or_b32 v183, v197, s80, v126
	v_ashrrev_i32_e32 v202, 31, v193
	v_or_b32_e32 v202, 0x80000000, v202
	v_xor_b32_e32 v202, v193, v202
	v_and_or_b32 v184, v202, s80, v127
	s_waitcnt vmcnt(4)
	v_mfma_f32_16x16x32_bf16 v[190:193], v[60:63], v[12:15], 0
	v_mfma_f32_16x16x32_bf16 v[190:193], v[64:67], v[8:11], v[190:193]
	v_mfma_f32_16x16x32_bf16 v[190:193], v[68:71], v[4:7], v[190:193]
	v_mfma_f32_16x16x32_bf16 v[190:193], v[72:75], v[0:3], v[190:193]
	s_nop 7
	s_nop 3
	v_ashrrev_i32_e32 v197, 31, v198
	v_or_b32_e32 v197, 0x80000000, v197
	v_xor_b32_e32 v197, v198, v197
	v_and_or_b32 v185, v197, s80, v94
	v_ashrrev_i32_e32 v202, 31, v199
	v_or_b32_e32 v202, 0x80000000, v202
	v_xor_b32_e32 v202, v199, v202
	v_and_or_b32 v186, v202, s80, v129
	v_ashrrev_i32_e32 v197, 31, v200
	v_or_b32_e32 v197, 0x80000000, v197
	v_xor_b32_e32 v197, v200, v197
	v_and_or_b32 v187, v197, s80, v130
	v_ashrrev_i32_e32 v202, 31, v201
	v_or_b32_e32 v202, 0x80000000, v202
	v_xor_b32_e32 v202, v201, v202
	v_and_or_b32 v188, v202, s80, v131
	s_waitcnt vmcnt(0)
; #define MFMA(a, b, c) __builtin_amdgcn_mfma_f32_16x16x32_bf16((a), (b), (c), 0, 0, 0)
; DI unsigned ordf(float f) { unsigned u = __float_as_uint(f); return (u & 0x80000000u) ? ~u : (u | 0x80000000u); }
; DI void peer_topk_wave(const Params& p, int item, unsigned* lds  ) {
;     ...
;     for (int mt = 0; mt < 8; ++mt) {
;       f32x4 a = (f32x4){0.f, 0.f, 0.f, 0.f};
; #pragma unroll
;       for (int ks = 0; ks < 4; ++ks) {
;         bf16x8 kf = *(const bf16x8*)&sk[(mt * 16 + r) * 128 + ks * 32 + kg * 8];
;         a = MFMA(kf, qf[ks], a);
;       }
; #pragma unroll
;       for (int j = 0; j < 4; ++j) kk[mt * 4 + j] = (ordf(a[j]) & ~127u) | (unsigned)(mt * 16 + kg * 4 + j);
;     }
; #pragma unroll
;     for (int rr = 0; rr < 16; ++rr) {
;       unsigned m = 0;
; #pragma unroll
;       for (int i = 0; i < 32; ++i) m = umax(m, kk[i]);
;       m = umax(m, (unsigned)__shfl_xor((int)m, 16));
;       m = umax(m, (unsigned)__shfl_xor((int)m, 32));
	v_mfma_f32_16x16x32_bf16 v[198:201], v[76:79], v[12:15], 0
	v_mfma_f32_16x16x32_bf16 v[198:201], v[80:83], v[8:11], v[198:201]
	v_mfma_f32_16x16x32_bf16 v[198:201], v[24:27], v[4:7], v[198:201]
	v_mfma_f32_16x16x32_bf16 v[198:201], v[28:31], v[0:3], v[198:201]
	s_nop 7
	s_nop 3
	v_ashrrev_i32_e32 v197, 31, v190
	v_or_b32_e32 v197, 0x80000000, v197
	v_xor_b32_e32 v197, v190, v197
	v_and_or_b32 v189, v197, s80, v95
	v_ashrrev_i32_e32 v202, 31, v191
	v_or_b32_e32 v202, 0x80000000, v202
	v_xor_b32_e32 v202, v191, v202
	v_and_or_b32 v194, v202, s80, v135
	v_ashrrev_i32_e32 v197, 31, v192
	v_or_b32_e32 v197, 0x80000000, v197
	v_xor_b32_e32 v197, v192, v197
	v_and_or_b32 v195, v197, s80, v136
	v_ashrrev_i32_e32 v202, 31, v193
	v_or_b32_e32 v202, 0x80000000, v202
	v_xor_b32_e32 v202, v193, v202
	v_and_or_b32 v196, v202, s80, v137
	s_nop 7
	s_nop 3
	v_ashrrev_i32_e32 v197, 31, v198
	v_or_b32_e32 v197, 0x80000000, v197
	v_xor_b32_e32 v197, v198, v197
	v_and_or_b32 v4, v197, s80, v96
	v_ashrrev_i32_e32 v202, 31, v199
	v_or_b32_e32 v202, 0x80000000, v202
	v_xor_b32_e32 v202, v199, v202
	v_and_or_b32 v1, v202, s80, v138
	v_ashrrev_i32_e32 v197, 31, v200
	v_or_b32_e32 v197, 0x80000000, v197
	v_xor_b32_e32 v197, v200, v197
	v_and_or_b32 v2, v197, s80, v139
	v_ashrrev_i32_e32 v202, 31, v201
	v_or_b32_e32 v202, 0x80000000, v202
	v_xor_b32_e32 v202, v201, v202
	v_and_or_b32 v3, v202, s80, v140
	v_max_u32_e32 v0, v88, v89
	v_max3_u32 v0, v0, v164, v165
	v_max3_u32 v0, v0, v166, v167
	v_max3_u32 v0, v0, v168, v169
	v_max3_u32 v0, v0, v171, v172
	v_max3_u32 v0, v0, v173, v176
	v_max3_u32 v0, v0, v177, v178
	v_max3_u32 v0, v0, v179, v180
	v_max3_u32 v0, v0, v181, v182
	v_max3_u32 v0, v0, v183, v184
	v_max3_u32 v0, v0, v185, v186
	v_max3_u32 v0, v0, v187, v188
	v_max3_u32 v0, v0, v189, v194
	v_max3_u32 v0, v0, v195, v196
	v_max3_u32 v0, v0, v4, v1
	v_max3_u32 v0, v0, v2, v3
	ds_bpermute_b32 v5, v111, v0
	s_waitcnt lgkmcnt(0)
	v_max_u32_e32 v0, v0, v5
	ds_bpermute_b32 v5, v112, v0
	s_waitcnt lgkmcnt(0)
	v_max_u32_e32 v0, v0, v5
	v_cmp_ne_u32_e32 vcc, v88, v0
	v_cmp_ne_u32_e64 s[98:99], v89, v0
	v_cmp_ne_u32_e64 s[100:101], v164, v0
	v_cndmask_b32_e32 v5, 0, v88, vcc
	v_cndmask_b32_e64 v6, 0, v89, s[98:99]
	v_cndmask_b32_e64 v7, 0, v164, s[100:101]
	v_cmp_ne_u32_e32 vcc, v165, v0
	v_cmp_ne_u32_e64 s[98:99], v166, v0
	v_cmp_ne_u32_e64 s[100:101], v167, v0
	v_cndmask_b32_e32 v8, 0, v165, vcc
	v_cndmask_b32_e64 v9, 0, v166, s[98:99]
	v_cndmask_b32_e64 v10, 0, v167, s[100:101]
	v_cmp_ne_u32_e32 vcc, v168, v0
	v_cmp_ne_u32_e64 s[98:99], v169, v0
	v_cmp_ne_u32_e64 s[100:101], v171, v0
	v_cndmask_b32_e32 v11, 0, v168, vcc
	v_cndmask_b32_e64 v12, 0, v169, s[98:99]
	v_cndmask_b32_e64 v13, 0, v171, s[100:101]
	v_cmp_ne_u32_e32 vcc, v172, v0
	v_cmp_ne_u32_e64 s[98:99], v173, v0
	v_cmp_ne_u32_e64 s[100:101], v176, v0
	v_cndmask_b32_e32 v14, 0, v172, vcc
	v_cndmask_b32_e64 v15, 0, v173, s[98:99]
	v_cndmask_b32_e64 v86, 0, v176, s[100:101]
	v_cmp_ne_u32_e32 vcc, v177, v0
	v_cmp_ne_u32_e64 s[98:99], v178, v0
	v_cmp_ne_u32_e64 s[100:101], v179, v0
	v_cndmask_b32_e32 v87, 0, v177, vcc
	v_cndmask_b32_e64 v88, 0, v178, s[98:99]
	v_cndmask_b32_e64 v89, 0, v179, s[100:101]
	v_cmp_ne_u32_e32 vcc, v180, v0
	v_cmp_ne_u32_e64 s[98:99], v181, v0
	v_cmp_ne_u32_e64 s[100:101], v182, v0
	v_cndmask_b32_e32 v164, 0, v180, vcc
	v_cndmask_b32_e64 v165, 0, v181, s[98:99]
	v_cndmask_b32_e64 v166, 0, v182, s[100:101]
	v_cmp_ne_u32_e32 vcc, v183, v0
	v_cmp_ne_u32_e64 s[98:99], v184, v0
	v_cmp_ne_u32_e64 s[100:101], v185, v0
	v_cndmask_b32_e32 v167, 0, v183, vcc
	v_cndmask_b32_e64 v168, 0, v184, s[98:99]
	v_cndmask_b32_e64 v169, 0, v185, s[100:101]
	v_cmp_ne_u32_e32 vcc, v186, v0
	v_cmp_ne_u32_e64 s[98:99], v187, v0
	v_cmp_ne_u32_e64 s[100:101], v188, v0
	v_cndmask_b32_e32 v171, 0, v186, vcc
	v_cndmask_b32_e64 v172, 0, v187, s[98:99]
	v_cndmask_b32_e64 v173, 0, v188, s[100:101]
	v_cmp_ne_u32_e32 vcc, v189, v0
	v_cmp_ne_u32_e64 s[98:99], v194, v0
	v_cmp_ne_u32_e64 s[100:101], v195, v0
	v_cndmask_b32_e32 v176, 0, v189, vcc
	v_cndmask_b32_e64 v177, 0, v194, s[98:99]
	v_cndmask_b32_e64 v178, 0, v195, s[100:101]
	v_cmp_ne_u32_e32 vcc, v196, v0
	v_cmp_ne_u32_e64 s[98:99], v4, v0
	v_cmp_ne_u32_e64 s[100:101], v1, v0
	v_cndmask_b32_e32 v179, 0, v196, vcc
	v_cndmask_b32_e64 v4, 0, v4, s[98:99]
	v_cndmask_b32_e64 v180, 0, v1, s[100:101]
	v_max_u32_e32 v1, v5, v6
	v_max3_u32 v1, v1, v7, v8
	v_max3_u32 v1, v1, v9, v10
	v_max3_u32 v1, v1, v11, v12
	v_max3_u32 v1, v1, v13, v14
	v_max3_u32 v1, v1, v15, v86
	v_max3_u32 v1, v1, v87, v88
	v_max3_u32 v1, v1, v89, v164
	v_max3_u32 v1, v1, v165, v166
	v_max3_u32 v1, v1, v167, v168
	v_max3_u32 v1, v1, v169, v171
	v_max3_u32 v1, v1, v172, v173
	v_cmp_ne_u32_e32 vcc, v2, v0
	v_max3_u32 v1, v1, v176, v177
	v_max3_u32 v1, v1, v178, v179
	v_cndmask_b32_e32 v2, 0, v2, vcc
	v_cmp_ne_u32_e64 s[98:99], v3, v0
	v_max3_u32 v1, v1, v4, v180
	s_nop 0
	v_cndmask_b32_e64 v3, 0, v3, s[98:99]
	v_max3_u32 v1, v1, v2, v3
	ds_bpermute_b32 v181, v111, v1
	s_waitcnt lgkmcnt(0)
	v_max_u32_e32 v1, v1, v181
	ds_bpermute_b32 v181, v112, v1
	s_waitcnt lgkmcnt(0)
; DI void peer_topk_wave(const Params& p, int item, unsigned* lds  ) {
;     ...
; #pragma unroll
;     for (int rr = 0; rr < 16; ++rr) {
;       unsigned m = 0;
; #pragma unroll
;       for (int i = 0; i < 32; ++i) m = umax(m, kk[i]);
;       m = umax(m, (unsigned)__shfl_xor((int)m, 16));
;       m = umax(m, (unsigned)__shfl_xor((int)m, 32));
;       win[pp][rr] = m;
; #pragma unroll
;       for (int i = 0; i < 32; ++i) kk[i] = (kk[i] == m) ? 0u : kk[i];
;     }
	v_max_u32_e32 v1, v1, v181
	v_cmp_ne_u32_e32 vcc, v5, v1
	v_cmp_ne_u32_e64 s[98:99], v6, v1
	v_cmp_ne_u32_e64 s[100:101], v7, v1
	v_cndmask_b32_e32 v5, 0, v5, vcc
	v_cndmask_b32_e64 v6, 0, v6, s[98:99]
	v_cndmask_b32_e64 v7, 0, v7, s[100:101]
	v_cmp_ne_u32_e32 vcc, v8, v1
	v_cmp_ne_u32_e64 s[98:99], v9, v1
	v_cmp_ne_u32_e64 s[100:101], v10, v1
	v_cndmask_b32_e32 v8, 0, v8, vcc
	v_cndmask_b32_e64 v9, 0, v9, s[98:99]
	v_cndmask_b32_e64 v10, 0, v10, s[100:101]
	v_cmp_ne_u32_e32 vcc, v11, v1
	v_cmp_ne_u32_e64 s[98:99], v12, v1
	v_cmp_ne_u32_e64 s[100:101], v13, v1
	v_cndmask_b32_e32 v11, 0, v11, vcc
	v_cndmask_b32_e64 v12, 0, v12, s[98:99]
	v_cndmask_b32_e64 v13, 0, v13, s[100:101]
	v_cmp_ne_u32_e32 vcc, v14, v1
	v_cmp_ne_u32_e64 s[98:99], v15, v1
	v_cmp_ne_u32_e64 s[100:101], v86, v1
	v_cndmask_b32_e32 v14, 0, v14, vcc
	v_cndmask_b32_e64 v15, 0, v15, s[98:99]
	v_cndmask_b32_e64 v86, 0, v86, s[100:101]
	v_cmp_ne_u32_e32 vcc, v87, v1
	v_cmp_ne_u32_e64 s[98:99], v88, v1
	v_cmp_ne_u32_e64 s[100:101], v89, v1
	v_cndmask_b32_e32 v87, 0, v87, vcc
	v_cndmask_b32_e64 v88, 0, v88, s[98:99]
	v_cndmask_b32_e64 v89, 0, v89, s[100:101]
	v_cmp_ne_u32_e32 vcc, v164, v1
	v_cmp_ne_u32_e64 s[98:99], v165, v1
	v_cmp_ne_u32_e64 s[100:101], v166, v1
	v_cndmask_b32_e32 v164, 0, v164, vcc
	v_cndmask_b32_e64 v165, 0, v165, s[98:99]
	v_cndmask_b32_e64 v166, 0, v166, s[100:101]
	v_cmp_ne_u32_e32 vcc, v167, v1
	v_cmp_ne_u32_e64 s[98:99], v168, v1
	v_cmp_ne_u32_e64 s[100:101], v169, v1
	v_cndmask_b32_e32 v167, 0, v167, vcc
	v_cndmask_b32_e64 v168, 0, v168, s[98:99]
	v_cndmask_b32_e64 v169, 0, v169, s[100:101]
	v_cmp_ne_u32_e32 vcc, v171, v1
	v_cmp_ne_u32_e64 s[98:99], v172, v1
	v_cmp_ne_u32_e64 s[100:101], v173, v1
	v_cndmask_b32_e32 v171, 0, v171, vcc
	v_cndmask_b32_e64 v172, 0, v172, s[98:99]
	v_cndmask_b32_e64 v173, 0, v173, s[100:101]
	v_cmp_ne_u32_e32 vcc, v176, v1
	v_cmp_ne_u32_e64 s[98:99], v177, v1
	v_cmp_ne_u32_e64 s[100:101], v178, v1
	v_cndmask_b32_e32 v176, 0, v176, vcc
	v_cndmask_b32_e64 v177, 0, v177, s[98:99]
	v_cndmask_b32_e64 v178, 0, v178, s[100:101]
	v_cmp_ne_u32_e32 vcc, v179, v1
	v_cmp_ne_u32_e64 s[98:99], v4, v1
	v_cmp_ne_u32_e64 s[100:101], v180, v1
	v_cndmask_b32_e32 v179, 0, v179, vcc
	v_cndmask_b32_e64 v4, 0, v4, s[98:99]
	v_cndmask_b32_e64 v180, 0, v180, s[100:101]
	v_cmp_ne_u32_e32 vcc, v2, v1
	v_cmp_ne_u32_e64 s[98:99], v3, v1
	s_nop 0
	v_cndmask_b32_e32 v181, 0, v2, vcc
	v_max_u32_e32 v2, v5, v6
	v_max3_u32 v2, v2, v7, v8
	v_max3_u32 v2, v2, v9, v10
	v_max3_u32 v2, v2, v11, v12
	v_max3_u32 v2, v2, v13, v14
	v_max3_u32 v2, v2, v15, v86
	v_max3_u32 v2, v2, v87, v88
	v_max3_u32 v2, v2, v89, v164
	v_max3_u32 v2, v2, v165, v166
	v_max3_u32 v2, v2, v167, v168
	v_max3_u32 v2, v2, v169, v171
	v_max3_u32 v2, v2, v172, v173
	v_max3_u32 v2, v2, v176, v177
	v_max3_u32 v2, v2, v178, v179
	v_max3_u32 v2, v2, v4, v180
	v_cndmask_b32_e64 v3, 0, v3, s[98:99]
	v_max3_u32 v2, v2, v181, v3
	ds_bpermute_b32 v182, v111, v2
	s_waitcnt lgkmcnt(0)
	v_max_u32_e32 v2, v2, v182
	ds_bpermute_b32 v182, v112, v2
	s_waitcnt lgkmcnt(0)
	v_max_u32_e32 v2, v2, v182
	v_cmp_ne_u32_e32 vcc, v5, v2
	v_cmp_ne_u32_e64 s[98:99], v6, v2
	v_cmp_ne_u32_e64 s[100:101], v7, v2
	v_cndmask_b32_e32 v5, 0, v5, vcc
	v_cndmask_b32_e64 v6, 0, v6, s[98:99]
	v_cndmask_b32_e64 v7, 0, v7, s[100:101]
	v_cmp_ne_u32_e32 vcc, v8, v2
	v_cmp_ne_u32_e64 s[98:99], v9, v2
	v_cmp_ne_u32_e64 s[100:101], v10, v2
	v_cndmask_b32_e32 v8, 0, v8, vcc
	v_cndmask_b32_e64 v9, 0, v9, s[98:99]
	v_cndmask_b32_e64 v10, 0, v10, s[100:101]
	v_cmp_ne_u32_e32 vcc, v11, v2
	v_cmp_ne_u32_e64 s[98:99], v12, v2
	v_cmp_ne_u32_e64 s[100:101], v13, v2
	v_cndmask_b32_e32 v11, 0, v11, vcc
	v_cndmask_b32_e64 v12, 0, v12, s[98:99]
	v_cndmask_b32_e64 v13, 0, v13, s[100:101]
	v_cmp_ne_u32_e32 vcc, v14, v2
	v_cmp_ne_u32_e64 s[98:99], v15, v2
	v_cmp_ne_u32_e64 s[100:101], v86, v2
	v_cndmask_b32_e32 v14, 0, v14, vcc
	v_cndmask_b32_e64 v15, 0, v15, s[98:99]
	v_cndmask_b32_e64 v86, 0, v86, s[100:101]
	v_cmp_ne_u32_e32 vcc, v87, v2
	v_cmp_ne_u32_e64 s[98:99], v88, v2
	v_cmp_ne_u32_e64 s[100:101], v89, v2
	v_cndmask_b32_e32 v87, 0, v87, vcc
	v_cndmask_b32_e64 v88, 0, v88, s[98:99]
	v_cndmask_b32_e64 v89, 0, v89, s[100:101]
	v_cmp_ne_u32_e32 vcc, v164, v2
	v_cmp_ne_u32_e64 s[98:99], v165, v2
	v_cmp_ne_u32_e64 s[100:101], v166, v2
	v_cndmask_b32_e32 v164, 0, v164, vcc
	v_cndmask_b32_e64 v165, 0, v165, s[98:99]
	v_cndmask_b32_e64 v166, 0, v166, s[100:101]
	v_cmp_ne_u32_e32 vcc, v167, v2
	v_cmp_ne_u32_e64 s[98:99], v168, v2
	v_cmp_ne_u32_e64 s[100:101], v169, v2
	v_cndmask_b32_e32 v167, 0, v167, vcc
	v_cndmask_b32_e64 v168, 0, v168, s[98:99]
	v_cndmask_b32_e64 v169, 0, v169, s[100:101]
	v_cmp_ne_u32_e32 vcc, v171, v2
	v_cmp_ne_u32_e64 s[98:99], v172, v2
	v_cmp_ne_u32_e64 s[100:101], v173, v2
	v_cndmask_b32_e32 v171, 0, v171, vcc
	v_cndmask_b32_e64 v172, 0, v172, s[98:99]
	v_cndmask_b32_e64 v173, 0, v173, s[100:101]
	v_cmp_ne_u32_e32 vcc, v176, v2
	v_cmp_ne_u32_e64 s[98:99], v177, v2
	v_cmp_ne_u32_e64 s[100:101], v178, v2
	v_cndmask_b32_e32 v176, 0, v176, vcc
	v_cndmask_b32_e64 v177, 0, v177, s[98:99]
	v_cndmask_b32_e64 v178, 0, v178, s[100:101]
	v_cmp_ne_u32_e32 vcc, v179, v2
	v_cmp_ne_u32_e64 s[98:99], v4, v2
	v_cmp_ne_u32_e64 s[100:101], v180, v2
	v_cndmask_b32_e32 v179, 0, v179, vcc
	v_cndmask_b32_e64 v4, 0, v4, s[98:99]
	v_cndmask_b32_e64 v180, 0, v180, s[100:101]
	v_cmp_ne_u32_e32 vcc, v181, v2
	v_cmp_ne_u32_e64 s[98:99], v3, v2
	s_nop 0
	v_cndmask_b32_e32 v181, 0, v181, vcc
	v_cndmask_b32_e64 v182, 0, v3, s[98:99]
	v_max_u32_e32 v3, v5, v6
	v_max3_u32 v3, v3, v7, v8
	v_max3_u32 v3, v3, v9, v10
	v_max3_u32 v3, v3, v11, v12
	v_max3_u32 v3, v3, v13, v14
	v_max3_u32 v3, v3, v15, v86
	v_max3_u32 v3, v3, v87, v88
	v_max3_u32 v3, v3, v89, v164
	v_max3_u32 v3, v3, v165, v166
	v_max3_u32 v3, v3, v167, v168
	v_max3_u32 v3, v3, v169, v171
	v_max3_u32 v3, v3, v172, v173
	v_max3_u32 v3, v3, v176, v177
	v_max3_u32 v3, v3, v178, v179
	v_max3_u32 v3, v3, v4, v180
	v_max3_u32 v3, v3, v181, v182
	ds_bpermute_b32 v183, v111, v3
	s_waitcnt lgkmcnt(0)
; DI void peer_topk_wave(const Params& p, int item, unsigned* lds  ) {
;     ...
; #pragma unroll
;     for (int rr = 0; rr < 16; ++rr) {
;       unsigned m = 0;
; #pragma unroll
;       for (int i = 0; i < 32; ++i) m = umax(m, kk[i]);
;       m = umax(m, (unsigned)__shfl_xor((int)m, 16));
;       m = umax(m, (unsigned)__shfl_xor((int)m, 32));
;       win[pp][rr] = m;
; #pragma unroll
;       for (int i = 0; i < 32; ++i) kk[i] = (kk[i] == m) ? 0u : kk[i];
;     }
	v_max_u32_e32 v3, v3, v183
	ds_bpermute_b32 v183, v112, v3
	s_waitcnt lgkmcnt(0)
	v_max_u32_e32 v3, v3, v183
	v_cmp_ne_u32_e32 vcc, v5, v3
	v_cmp_ne_u32_e64 s[98:99], v6, v3
	v_cmp_ne_u32_e64 s[100:101], v7, v3
	v_cndmask_b32_e32 v5, 0, v5, vcc
	v_cndmask_b32_e64 v6, 0, v6, s[98:99]
	v_cndmask_b32_e64 v7, 0, v7, s[100:101]
	v_cmp_ne_u32_e32 vcc, v8, v3
	v_cmp_ne_u32_e64 s[98:99], v9, v3
	v_cmp_ne_u32_e64 s[100:101], v10, v3
	v_cndmask_b32_e32 v8, 0, v8, vcc
	v_cndmask_b32_e64 v9, 0, v9, s[98:99]
	v_cndmask_b32_e64 v10, 0, v10, s[100:101]
	v_cmp_ne_u32_e32 vcc, v11, v3
	v_cmp_ne_u32_e64 s[98:99], v12, v3
	v_cmp_ne_u32_e64 s[100:101], v13, v3
	v_cndmask_b32_e32 v11, 0, v11, vcc
	v_cndmask_b32_e64 v12, 0, v12, s[98:99]
	v_cndmask_b32_e64 v13, 0, v13, s[100:101]
	v_cmp_ne_u32_e32 vcc, v14, v3
	v_cmp_ne_u32_e64 s[98:99], v15, v3
	v_cmp_ne_u32_e64 s[100:101], v86, v3
	v_cndmask_b32_e32 v14, 0, v14, vcc
	v_cndmask_b32_e64 v15, 0, v15, s[98:99]
	v_cndmask_b32_e64 v86, 0, v86, s[100:101]
	v_cmp_ne_u32_e32 vcc, v87, v3
	v_cmp_ne_u32_e64 s[98:99], v88, v3
	v_cmp_ne_u32_e64 s[100:101], v89, v3
	v_cndmask_b32_e32 v87, 0, v87, vcc
	v_cndmask_b32_e64 v88, 0, v88, s[98:99]
	v_cndmask_b32_e64 v89, 0, v89, s[100:101]
	v_cmp_ne_u32_e32 vcc, v164, v3
	v_cmp_ne_u32_e64 s[98:99], v165, v3
	v_cmp_ne_u32_e64 s[100:101], v166, v3
	v_cndmask_b32_e32 v164, 0, v164, vcc
	v_cndmask_b32_e64 v165, 0, v165, s[98:99]
	v_cndmask_b32_e64 v166, 0, v166, s[100:101]
	v_cmp_ne_u32_e32 vcc, v167, v3
	v_cmp_ne_u32_e64 s[98:99], v168, v3
	v_cmp_ne_u32_e64 s[100:101], v169, v3
	v_cndmask_b32_e32 v167, 0, v167, vcc
	v_cndmask_b32_e64 v168, 0, v168, s[98:99]
	v_cndmask_b32_e64 v169, 0, v169, s[100:101]
	v_cmp_ne_u32_e32 vcc, v171, v3
	v_cmp_ne_u32_e64 s[98:99], v172, v3
	v_cmp_ne_u32_e64 s[100:101], v173, v3
	v_cndmask_b32_e32 v171, 0, v171, vcc
	v_cndmask_b32_e64 v172, 0, v172, s[98:99]
	v_cndmask_b32_e64 v173, 0, v173, s[100:101]
	v_cmp_ne_u32_e32 vcc, v176, v3
	v_cmp_ne_u32_e64 s[98:99], v177, v3
	v_cmp_ne_u32_e64 s[100:101], v178, v3
	v_cndmask_b32_e32 v176, 0, v176, vcc
	v_cndmask_b32_e64 v177, 0, v177, s[98:99]
	v_cndmask_b32_e64 v178, 0, v178, s[100:101]
	v_cmp_ne_u32_e32 vcc, v179, v3
	v_cmp_ne_u32_e64 s[98:99], v4, v3
	v_cmp_ne_u32_e64 s[100:101], v180, v3
	v_cndmask_b32_e32 v179, 0, v179, vcc
	v_cndmask_b32_e64 v183, 0, v4, s[98:99]
	v_max_u32_e32 v4, v5, v6
	v_max3_u32 v4, v4, v7, v8
	v_max3_u32 v4, v4, v9, v10
	v_max3_u32 v4, v4, v11, v12
	v_max3_u32 v4, v4, v13, v14
	v_max3_u32 v4, v4, v15, v86
	v_max3_u32 v4, v4, v87, v88
	v_max3_u32 v4, v4, v89, v164
	v_max3_u32 v4, v4, v165, v166
	v_max3_u32 v4, v4, v167, v168
	v_max3_u32 v4, v4, v169, v171
	v_max3_u32 v4, v4, v172, v173
	v_max3_u32 v4, v4, v176, v177
	v_cndmask_b32_e64 v180, 0, v180, s[100:101]
	v_cmp_ne_u32_e32 vcc, v181, v3
	v_max3_u32 v4, v4, v178, v179
	v_max3_u32 v4, v4, v183, v180
	v_cndmask_b32_e32 v181, 0, v181, vcc
	v_cmp_ne_u32_e64 s[98:99], v182, v3
	s_nop 0
	s_nop 0
	v_cndmask_b32_e64 v182, 0, v182, s[98:99]
	v_max3_u32 v4, v4, v181, v182
	ds_bpermute_b32 v184, v111, v4
	s_waitcnt lgkmcnt(0)
	v_max_u32_e32 v4, v4, v184
	ds_bpermute_b32 v184, v112, v4
	s_waitcnt lgkmcnt(0)
	v_max_u32_e32 v4, v4, v184
	v_cmp_ne_u32_e32 vcc, v5, v4
	v_cmp_ne_u32_e64 s[98:99], v6, v4
	v_cmp_ne_u32_e64 s[100:101], v7, v4
	v_cndmask_b32_e32 v184, 0, v5, vcc
	v_cndmask_b32_e64 v6, 0, v6, s[98:99]
	v_max_u32_e32 v5, v184, v6
	v_cndmask_b32_e64 v7, 0, v7, s[100:101]
	v_cmp_ne_u32_e32 vcc, v8, v4
	v_cmp_ne_u32_e64 s[98:99], v9, v4
	v_cmp_ne_u32_e64 s[100:101], v10, v4
	v_cndmask_b32_e32 v8, 0, v8, vcc
	v_max3_u32 v5, v5, v7, v8
	v_cndmask_b32_e64 v9, 0, v9, s[98:99]
	v_cndmask_b32_e64 v10, 0, v10, s[100:101]
	v_cmp_ne_u32_e32 vcc, v11, v4
	v_max3_u32 v5, v5, v9, v10
	v_cmp_ne_u32_e64 s[98:99], v12, v4
	v_cndmask_b32_e32 v11, 0, v11, vcc
	v_cmp_ne_u32_e64 s[100:101], v13, v4
	v_cndmask_b32_e64 v12, 0, v12, s[98:99]
	v_max3_u32 v5, v5, v11, v12
	v_cndmask_b32_e64 v13, 0, v13, s[100:101]
	v_cmp_ne_u32_e32 vcc, v14, v4
	v_cmp_ne_u32_e64 s[98:99], v15, v4
	v_cmp_ne_u32_e64 s[100:101], v86, v4
	v_cndmask_b32_e32 v14, 0, v14, vcc
	v_max3_u32 v5, v5, v13, v14
	v_cndmask_b32_e64 v15, 0, v15, s[98:99]
	v_cndmask_b32_e64 v86, 0, v86, s[100:101]
	v_cmp_ne_u32_e32 vcc, v87, v4
	v_max3_u32 v5, v5, v15, v86
	v_cmp_ne_u32_e64 s[98:99], v88, v4
	v_cndmask_b32_e32 v87, 0, v87, vcc
	v_cmp_ne_u32_e64 s[100:101], v89, v4
	v_cndmask_b32_e64 v88, 0, v88, s[98:99]
	v_max3_u32 v5, v5, v87, v88
	v_cndmask_b32_e64 v89, 0, v89, s[100:101]
	v_cmp_ne_u32_e32 vcc, v164, v4
	v_cmp_ne_u32_e64 s[98:99], v165, v4
	v_cmp_ne_u32_e64 s[100:101], v166, v4
	v_cndmask_b32_e32 v164, 0, v164, vcc
	v_max3_u32 v5, v5, v89, v164
	v_cndmask_b32_e64 v165, 0, v165, s[98:99]
	v_cndmask_b32_e64 v166, 0, v166, s[100:101]
	v_cmp_ne_u32_e32 vcc, v167, v4
	v_max3_u32 v5, v5, v165, v166
	v_cmp_ne_u32_e64 s[98:99], v168, v4
	v_cndmask_b32_e32 v167, 0, v167, vcc
	v_cmp_ne_u32_e64 s[100:101], v169, v4
	v_cndmask_b32_e64 v168, 0, v168, s[98:99]
	v_max3_u32 v5, v5, v167, v168
	v_cndmask_b32_e64 v169, 0, v169, s[100:101]
	v_cmp_ne_u32_e32 vcc, v171, v4
	v_cmp_ne_u32_e64 s[98:99], v172, v4
	v_cmp_ne_u32_e64 s[100:101], v173, v4
	v_cndmask_b32_e32 v171, 0, v171, vcc
	v_max3_u32 v5, v5, v169, v171
	v_cndmask_b32_e64 v172, 0, v172, s[98:99]
	v_cndmask_b32_e64 v173, 0, v173, s[100:101]
	v_cmp_ne_u32_e32 vcc, v176, v4
	v_max3_u32 v5, v5, v172, v173
	v_cmp_ne_u32_e64 s[98:99], v177, v4
	v_cndmask_b32_e32 v176, 0, v176, vcc
	v_cmp_ne_u32_e64 s[100:101], v178, v4
	v_cndmask_b32_e64 v177, 0, v177, s[98:99]
	v_max3_u32 v5, v5, v176, v177
	v_cndmask_b32_e64 v178, 0, v178, s[100:101]
	v_cmp_ne_u32_e32 vcc, v179, v4
	v_cmp_ne_u32_e64 s[98:99], v183, v4
	v_cmp_ne_u32_e64 s[100:101], v180, v4
	v_cndmask_b32_e32 v179, 0, v179, vcc
	v_max3_u32 v5, v5, v178, v179
	v_cndmask_b32_e64 v183, 0, v183, s[98:99]
	v_cndmask_b32_e64 v180, 0, v180, s[100:101]
	v_cmp_ne_u32_e32 vcc, v181, v4
	v_max3_u32 v5, v5, v183, v180
	v_cmp_ne_u32_e64 s[98:99], v182, v4
	v_cndmask_b32_e32 v181, 0, v181, vcc
	s_nop 0
	v_cndmask_b32_e64 v182, 0, v182, s[98:99]
	v_max3_u32 v5, v5, v181, v182
	ds_bpermute_b32 v185, v111, v5
	s_waitcnt lgkmcnt(0)
; DI void peer_topk_wave(const Params& p, int item, unsigned* lds  ) {
;     ...
; #pragma unroll
;     for (int rr = 0; rr < 16; ++rr) {
;       unsigned m = 0;
; #pragma unroll
;       for (int i = 0; i < 32; ++i) m = umax(m, kk[i]);
;       m = umax(m, (unsigned)__shfl_xor((int)m, 16));
;       m = umax(m, (unsigned)__shfl_xor((int)m, 32));
;       win[pp][rr] = m;
; #pragma unroll
;       for (int i = 0; i < 32; ++i) kk[i] = (kk[i] == m) ? 0u : kk[i];
;     }
	v_max_u32_e32 v5, v5, v185
	ds_bpermute_b32 v185, v112, v5
	s_waitcnt lgkmcnt(0)
	v_max_u32_e32 v5, v5, v185
	v_cmp_ne_u32_e32 vcc, v184, v5
	v_cmp_ne_u32_e64 s[98:99], v6, v5
	v_cmp_ne_u32_e64 s[100:101], v7, v5
	v_cndmask_b32_e32 v184, 0, v184, vcc
	v_cndmask_b32_e64 v185, 0, v6, s[98:99]
	v_max_u32_e32 v6, v184, v185
	v_cndmask_b32_e64 v7, 0, v7, s[100:101]
	v_cmp_ne_u32_e32 vcc, v8, v5
	v_cmp_ne_u32_e64 s[98:99], v9, v5
	v_cmp_ne_u32_e64 s[100:101], v10, v5
	v_cndmask_b32_e32 v8, 0, v8, vcc
	v_max3_u32 v6, v6, v7, v8
	v_cndmask_b32_e64 v9, 0, v9, s[98:99]
	v_cndmask_b32_e64 v10, 0, v10, s[100:101]
	v_cmp_ne_u32_e32 vcc, v11, v5
	v_max3_u32 v6, v6, v9, v10
	v_cmp_ne_u32_e64 s[98:99], v12, v5
	v_cndmask_b32_e32 v11, 0, v11, vcc
	v_cmp_ne_u32_e64 s[100:101], v13, v5
	v_cndmask_b32_e64 v12, 0, v12, s[98:99]
	v_max3_u32 v6, v6, v11, v12
	v_cndmask_b32_e64 v13, 0, v13, s[100:101]
	v_cmp_ne_u32_e32 vcc, v14, v5
	v_cmp_ne_u32_e64 s[98:99], v15, v5
	v_cmp_ne_u32_e64 s[100:101], v86, v5
	v_cndmask_b32_e32 v14, 0, v14, vcc
	v_max3_u32 v6, v6, v13, v14
	v_cndmask_b32_e64 v15, 0, v15, s[98:99]
	v_cndmask_b32_e64 v86, 0, v86, s[100:101]
	v_cmp_ne_u32_e32 vcc, v87, v5
	v_max3_u32 v6, v6, v15, v86
	v_cmp_ne_u32_e64 s[98:99], v88, v5
	v_cndmask_b32_e32 v87, 0, v87, vcc
	v_cmp_ne_u32_e64 s[100:101], v89, v5
	v_cndmask_b32_e64 v88, 0, v88, s[98:99]
	v_max3_u32 v6, v6, v87, v88
	v_cndmask_b32_e64 v89, 0, v89, s[100:101]
	v_cmp_ne_u32_e32 vcc, v164, v5
	v_cmp_ne_u32_e64 s[98:99], v165, v5
	v_cmp_ne_u32_e64 s[100:101], v166, v5
	v_cndmask_b32_e32 v164, 0, v164, vcc
	v_max3_u32 v6, v6, v89, v164
	v_cndmask_b32_e64 v165, 0, v165, s[98:99]
	v_cndmask_b32_e64 v166, 0, v166, s[100:101]
	v_cmp_ne_u32_e32 vcc, v167, v5
	v_max3_u32 v6, v6, v165, v166
	v_cmp_ne_u32_e64 s[98:99], v168, v5
	v_cndmask_b32_e32 v167, 0, v167, vcc
	v_cmp_ne_u32_e64 s[100:101], v169, v5
	v_cndmask_b32_e64 v168, 0, v168, s[98:99]
	v_max3_u32 v6, v6, v167, v168
	v_cndmask_b32_e64 v169, 0, v169, s[100:101]
	v_cmp_ne_u32_e32 vcc, v171, v5
	v_cmp_ne_u32_e64 s[98:99], v172, v5
	v_cmp_ne_u32_e64 s[100:101], v173, v5
	v_cndmask_b32_e32 v171, 0, v171, vcc
	v_max3_u32 v6, v6, v169, v171
	v_cndmask_b32_e64 v172, 0, v172, s[98:99]
	v_cndmask_b32_e64 v173, 0, v173, s[100:101]
	v_cmp_ne_u32_e32 vcc, v176, v5
	v_max3_u32 v6, v6, v172, v173
	v_cmp_ne_u32_e64 s[98:99], v177, v5
	v_cndmask_b32_e32 v176, 0, v176, vcc
	v_cmp_ne_u32_e64 s[100:101], v178, v5
	v_cndmask_b32_e64 v177, 0, v177, s[98:99]
	v_max3_u32 v6, v6, v176, v177
	v_cndmask_b32_e64 v178, 0, v178, s[100:101]
	v_cmp_ne_u32_e32 vcc, v179, v5
	v_cmp_ne_u32_e64 s[98:99], v183, v5
	v_cmp_ne_u32_e64 s[100:101], v180, v5
	v_cndmask_b32_e32 v179, 0, v179, vcc
	v_max3_u32 v6, v6, v178, v179
	v_cndmask_b32_e64 v183, 0, v183, s[98:99]
	v_cndmask_b32_e64 v180, 0, v180, s[100:101]
	v_cmp_ne_u32_e32 vcc, v181, v5
	v_max3_u32 v6, v6, v183, v180
	v_cmp_ne_u32_e64 s[98:99], v182, v5
	v_cndmask_b32_e32 v181, 0, v181, vcc
	s_nop 0
	v_cndmask_b32_e64 v182, 0, v182, s[98:99]
	v_max3_u32 v6, v6, v181, v182
	ds_bpermute_b32 v186, v111, v6
	s_waitcnt lgkmcnt(0)
	v_max_u32_e32 v6, v6, v186
	ds_bpermute_b32 v186, v112, v6
	s_waitcnt lgkmcnt(0)
	v_max_u32_e32 v6, v6, v186
	v_cmp_ne_u32_e32 vcc, v184, v6
	v_cmp_ne_u32_e64 s[98:99], v185, v6
	v_cmp_ne_u32_e64 s[100:101], v7, v6
	v_cndmask_b32_e32 v184, 0, v184, vcc
	v_cndmask_b32_e64 v185, 0, v185, s[98:99]
	v_cndmask_b32_e64 v186, 0, v7, s[100:101]
	v_cmp_ne_u32_e32 vcc, v8, v6
	v_max_u32_e32 v7, v184, v185
	v_cmp_ne_u32_e64 s[98:99], v9, v6
	v_cndmask_b32_e32 v8, 0, v8, vcc
	v_max3_u32 v7, v7, v186, v8
	v_cndmask_b32_e64 v9, 0, v9, s[98:99]
	v_cmp_ne_u32_e64 s[100:101], v10, v6
	v_cmp_ne_u32_e32 vcc, v11, v6
	v_cmp_ne_u32_e64 s[98:99], v12, v6
	v_cndmask_b32_e64 v10, 0, v10, s[100:101]
	v_max3_u32 v7, v7, v9, v10
	v_cndmask_b32_e32 v11, 0, v11, vcc
	v_cndmask_b32_e64 v12, 0, v12, s[98:99]
	v_cmp_ne_u32_e64 s[100:101], v13, v6
	v_max3_u32 v7, v7, v11, v12
	v_cmp_ne_u32_e32 vcc, v14, v6
	v_cndmask_b32_e64 v13, 0, v13, s[100:101]
	v_cmp_ne_u32_e64 s[98:99], v15, v6
	v_cndmask_b32_e32 v14, 0, v14, vcc
	v_max3_u32 v7, v7, v13, v14
	v_cndmask_b32_e64 v15, 0, v15, s[98:99]
	v_cmp_ne_u32_e64 s[100:101], v86, v6
	v_cmp_ne_u32_e32 vcc, v87, v6
	v_cmp_ne_u32_e64 s[98:99], v88, v6
	v_cndmask_b32_e64 v86, 0, v86, s[100:101]
	v_max3_u32 v7, v7, v15, v86
	v_cndmask_b32_e32 v87, 0, v87, vcc
	v_cndmask_b32_e64 v88, 0, v88, s[98:99]
	v_cmp_ne_u32_e64 s[100:101], v89, v6
	v_max3_u32 v7, v7, v87, v88
	v_cmp_ne_u32_e32 vcc, v164, v6
	v_cndmask_b32_e64 v89, 0, v89, s[100:101]
	v_cmp_ne_u32_e64 s[98:99], v165, v6
	v_cndmask_b32_e32 v164, 0, v164, vcc
	v_max3_u32 v7, v7, v89, v164
	v_cndmask_b32_e64 v165, 0, v165, s[98:99]
	v_cmp_ne_u32_e64 s[100:101], v166, v6
	v_cmp_ne_u32_e32 vcc, v167, v6
	v_cmp_ne_u32_e64 s[98:99], v168, v6
	v_cndmask_b32_e64 v166, 0, v166, s[100:101]
	v_max3_u32 v7, v7, v165, v166
	v_cndmask_b32_e32 v167, 0, v167, vcc
	v_cndmask_b32_e64 v168, 0, v168, s[98:99]
	v_cmp_ne_u32_e64 s[100:101], v169, v6
	v_max3_u32 v7, v7, v167, v168
	v_cmp_ne_u32_e32 vcc, v171, v6
	v_cndmask_b32_e64 v169, 0, v169, s[100:101]
	v_cmp_ne_u32_e64 s[98:99], v172, v6
	v_cndmask_b32_e32 v171, 0, v171, vcc
	v_max3_u32 v7, v7, v169, v171
	v_cndmask_b32_e64 v172, 0, v172, s[98:99]
	v_cmp_ne_u32_e64 s[100:101], v173, v6
	v_cmp_ne_u32_e32 vcc, v176, v6
	v_cmp_ne_u32_e64 s[98:99], v177, v6
	v_cndmask_b32_e64 v173, 0, v173, s[100:101]
	v_max3_u32 v7, v7, v172, v173
	v_cndmask_b32_e32 v176, 0, v176, vcc
	v_cndmask_b32_e64 v177, 0, v177, s[98:99]
	v_cmp_ne_u32_e64 s[100:101], v178, v6
	v_max3_u32 v7, v7, v176, v177
	v_cmp_ne_u32_e32 vcc, v179, v6
	v_cndmask_b32_e64 v178, 0, v178, s[100:101]
	v_cmp_ne_u32_e64 s[98:99], v183, v6
	v_cndmask_b32_e32 v179, 0, v179, vcc
	v_max3_u32 v7, v7, v178, v179
	v_cndmask_b32_e64 v183, 0, v183, s[98:99]
	v_cmp_ne_u32_e64 s[100:101], v180, v6
	v_cmp_ne_u32_e32 vcc, v181, v6
	v_cmp_ne_u32_e64 s[98:99], v182, v6
	v_cndmask_b32_e64 v180, 0, v180, s[100:101]
	v_max3_u32 v7, v7, v183, v180
	v_cndmask_b32_e32 v181, 0, v181, vcc
	v_cndmask_b32_e64 v182, 0, v182, s[98:99]
	v_max3_u32 v7, v7, v181, v182
	ds_bpermute_b32 v187, v111, v7
	s_waitcnt lgkmcnt(0)
; DI void peer_topk_wave(const Params& p, int item, unsigned* lds  ) {
;     ...
; #pragma unroll
;     for (int rr = 0; rr < 16; ++rr) {
;       unsigned m = 0;
; #pragma unroll
;       for (int i = 0; i < 32; ++i) m = umax(m, kk[i]);
;       m = umax(m, (unsigned)__shfl_xor((int)m, 16));
;       m = umax(m, (unsigned)__shfl_xor((int)m, 32));
;       win[pp][rr] = m;
; #pragma unroll
;       for (int i = 0; i < 32; ++i) kk[i] = (kk[i] == m) ? 0u : kk[i];
;     }
	v_max_u32_e32 v7, v7, v187
	ds_bpermute_b32 v187, v112, v7
	s_waitcnt lgkmcnt(0)
	v_max_u32_e32 v7, v7, v187
	v_cmp_ne_u32_e32 vcc, v184, v7
	v_cmp_ne_u32_e64 s[98:99], v185, v7
	v_cmp_ne_u32_e64 s[100:101], v186, v7
	v_cndmask_b32_e32 v184, 0, v184, vcc
	v_cndmask_b32_e64 v185, 0, v185, s[98:99]
	v_cndmask_b32_e64 v186, 0, v186, s[100:101]
	v_cmp_ne_u32_e32 vcc, v8, v7
	v_cmp_ne_u32_e64 s[98:99], v9, v7
	v_cmp_ne_u32_e64 s[100:101], v10, v7
	v_cndmask_b32_e32 v187, 0, v8, vcc
	v_max_u32_e32 v8, v184, v185
	v_max3_u32 v8, v8, v186, v187
	v_cndmask_b32_e64 v9, 0, v9, s[98:99]
	v_cndmask_b32_e64 v10, 0, v10, s[100:101]
	v_cmp_ne_u32_e32 vcc, v11, v7
	v_max3_u32 v8, v8, v9, v10
	v_cmp_ne_u32_e64 s[98:99], v12, v7
	v_cndmask_b32_e32 v11, 0, v11, vcc
	v_cmp_ne_u32_e64 s[100:101], v13, v7
	v_cndmask_b32_e64 v12, 0, v12, s[98:99]
	v_max3_u32 v8, v8, v11, v12
	v_cndmask_b32_e64 v13, 0, v13, s[100:101]
	v_cmp_ne_u32_e32 vcc, v14, v7
	v_cmp_ne_u32_e64 s[98:99], v15, v7
	v_cmp_ne_u32_e64 s[100:101], v86, v7
	v_cndmask_b32_e32 v14, 0, v14, vcc
	v_max3_u32 v8, v8, v13, v14
	v_cndmask_b32_e64 v15, 0, v15, s[98:99]
	v_cndmask_b32_e64 v86, 0, v86, s[100:101]
	v_cmp_ne_u32_e32 vcc, v87, v7
	v_max3_u32 v8, v8, v15, v86
	v_cmp_ne_u32_e64 s[98:99], v88, v7
	v_cndmask_b32_e32 v87, 0, v87, vcc
	v_cmp_ne_u32_e64 s[100:101], v89, v7
	v_cndmask_b32_e64 v88, 0, v88, s[98:99]
	v_max3_u32 v8, v8, v87, v88
	v_cndmask_b32_e64 v89, 0, v89, s[100:101]
	v_cmp_ne_u32_e32 vcc, v164, v7
	v_cmp_ne_u32_e64 s[98:99], v165, v7
	v_cmp_ne_u32_e64 s[100:101], v166, v7
	v_cndmask_b32_e32 v164, 0, v164, vcc
	v_max3_u32 v8, v8, v89, v164
	v_cndmask_b32_e64 v165, 0, v165, s[98:99]
	v_cndmask_b32_e64 v166, 0, v166, s[100:101]
	v_cmp_ne_u32_e32 vcc, v167, v7
	v_max3_u32 v8, v8, v165, v166
	v_cmp_ne_u32_e64 s[98:99], v168, v7
	v_cndmask_b32_e32 v167, 0, v167, vcc
	v_cmp_ne_u32_e64 s[100:101], v169, v7
	v_cndmask_b32_e64 v168, 0, v168, s[98:99]
	v_max3_u32 v8, v8, v167, v168
	v_cndmask_b32_e64 v169, 0, v169, s[100:101]
	v_cmp_ne_u32_e32 vcc, v171, v7
	v_cmp_ne_u32_e64 s[98:99], v172, v7
	v_cmp_ne_u32_e64 s[100:101], v173, v7
	v_cndmask_b32_e32 v171, 0, v171, vcc
	v_max3_u32 v8, v8, v169, v171
	v_cndmask_b32_e64 v172, 0, v172, s[98:99]
	v_cndmask_b32_e64 v173, 0, v173, s[100:101]
	v_cmp_ne_u32_e32 vcc, v176, v7
	v_max3_u32 v8, v8, v172, v173
	v_cmp_ne_u32_e64 s[98:99], v177, v7
	v_cndmask_b32_e32 v176, 0, v176, vcc
	v_cmp_ne_u32_e64 s[100:101], v178, v7
	v_cndmask_b32_e64 v177, 0, v177, s[98:99]
	v_max3_u32 v8, v8, v176, v177
	v_cndmask_b32_e64 v178, 0, v178, s[100:101]
	v_cmp_ne_u32_e32 vcc, v179, v7
	v_cmp_ne_u32_e64 s[98:99], v183, v7
	v_cmp_ne_u32_e64 s[100:101], v180, v7
	v_cndmask_b32_e32 v179, 0, v179, vcc
	v_max3_u32 v8, v8, v178, v179
	v_cndmask_b32_e64 v183, 0, v183, s[98:99]
	v_cndmask_b32_e64 v180, 0, v180, s[100:101]
	v_cmp_ne_u32_e32 vcc, v181, v7
	v_max3_u32 v8, v8, v183, v180
	v_cmp_ne_u32_e64 s[98:99], v182, v7
	v_cndmask_b32_e32 v181, 0, v181, vcc
	s_nop 0
	v_cndmask_b32_e64 v182, 0, v182, s[98:99]
	v_max3_u32 v8, v8, v181, v182
	ds_bpermute_b32 v188, v111, v8
	s_waitcnt lgkmcnt(0)
	v_max_u32_e32 v8, v8, v188
	ds_bpermute_b32 v188, v112, v8
	s_waitcnt lgkmcnt(0)
	v_max_u32_e32 v8, v8, v188
	v_cmp_ne_u32_e32 vcc, v184, v8
	v_cmp_ne_u32_e64 s[98:99], v185, v8
	v_cmp_ne_u32_e64 s[100:101], v186, v8
	v_cndmask_b32_e32 v184, 0, v184, vcc
	v_cndmask_b32_e64 v185, 0, v185, s[98:99]
	v_cndmask_b32_e64 v186, 0, v186, s[100:101]
	v_cmp_ne_u32_e32 vcc, v187, v8
	v_cmp_ne_u32_e64 s[98:99], v9, v8
	v_cmp_ne_u32_e64 s[100:101], v10, v8
	v_cndmask_b32_e32 v187, 0, v187, vcc
	v_cndmask_b32_e64 v188, 0, v9, s[98:99]
	v_max_u32_e32 v9, v184, v185
	v_max3_u32 v9, v9, v186, v187
	v_cndmask_b32_e64 v10, 0, v10, s[100:101]
	v_cmp_ne_u32_e32 vcc, v11, v8
	v_max3_u32 v9, v9, v188, v10
	v_cmp_ne_u32_e64 s[98:99], v12, v8
	v_cndmask_b32_e32 v11, 0, v11, vcc
	v_cmp_ne_u32_e64 s[100:101], v13, v8
	v_cndmask_b32_e64 v12, 0, v12, s[98:99]
	v_max3_u32 v9, v9, v11, v12
	v_cndmask_b32_e64 v13, 0, v13, s[100:101]
	v_cmp_ne_u32_e32 vcc, v14, v8
	v_cmp_ne_u32_e64 s[98:99], v15, v8
	v_cmp_ne_u32_e64 s[100:101], v86, v8
	v_cndmask_b32_e32 v14, 0, v14, vcc
	v_max3_u32 v9, v9, v13, v14
	v_cndmask_b32_e64 v15, 0, v15, s[98:99]
	v_cndmask_b32_e64 v86, 0, v86, s[100:101]
	v_cmp_ne_u32_e32 vcc, v87, v8
	v_max3_u32 v9, v9, v15, v86
	v_cmp_ne_u32_e64 s[98:99], v88, v8
	v_cndmask_b32_e32 v87, 0, v87, vcc
	v_cmp_ne_u32_e64 s[100:101], v89, v8
	v_cndmask_b32_e64 v88, 0, v88, s[98:99]
	v_max3_u32 v9, v9, v87, v88
	v_cndmask_b32_e64 v89, 0, v89, s[100:101]
	v_cmp_ne_u32_e32 vcc, v164, v8
	v_cmp_ne_u32_e64 s[98:99], v165, v8
	v_cmp_ne_u32_e64 s[100:101], v166, v8
	v_cndmask_b32_e32 v164, 0, v164, vcc
	v_max3_u32 v9, v9, v89, v164
	v_cndmask_b32_e64 v165, 0, v165, s[98:99]
	v_cndmask_b32_e64 v166, 0, v166, s[100:101]
	v_cmp_ne_u32_e32 vcc, v167, v8
	v_max3_u32 v9, v9, v165, v166
	v_cmp_ne_u32_e64 s[98:99], v168, v8
	v_cndmask_b32_e32 v167, 0, v167, vcc
	v_cmp_ne_u32_e64 s[100:101], v169, v8
	v_cndmask_b32_e64 v168, 0, v168, s[98:99]
	v_max3_u32 v9, v9, v167, v168
	v_cndmask_b32_e64 v169, 0, v169, s[100:101]
	v_cmp_ne_u32_e32 vcc, v171, v8
	v_cmp_ne_u32_e64 s[98:99], v172, v8
	v_cmp_ne_u32_e64 s[100:101], v173, v8
	v_cndmask_b32_e32 v171, 0, v171, vcc
	v_max3_u32 v9, v9, v169, v171
	v_cndmask_b32_e64 v172, 0, v172, s[98:99]
	v_cndmask_b32_e64 v173, 0, v173, s[100:101]
	v_cmp_ne_u32_e32 vcc, v176, v8
	v_max3_u32 v9, v9, v172, v173
	v_cmp_ne_u32_e64 s[98:99], v177, v8
	v_cndmask_b32_e32 v176, 0, v176, vcc
	v_cmp_ne_u32_e64 s[100:101], v178, v8
	v_cndmask_b32_e64 v177, 0, v177, s[98:99]
	v_max3_u32 v9, v9, v176, v177
	v_cndmask_b32_e64 v178, 0, v178, s[100:101]
	v_cmp_ne_u32_e32 vcc, v179, v8
	v_cmp_ne_u32_e64 s[98:99], v183, v8
	v_cmp_ne_u32_e64 s[100:101], v180, v8
	v_cndmask_b32_e32 v179, 0, v179, vcc
	v_max3_u32 v9, v9, v178, v179
	v_cndmask_b32_e64 v183, 0, v183, s[98:99]
	v_cndmask_b32_e64 v180, 0, v180, s[100:101]
	v_cmp_ne_u32_e32 vcc, v181, v8
	v_max3_u32 v9, v9, v183, v180
	v_cmp_ne_u32_e64 s[98:99], v182, v8
	v_cndmask_b32_e32 v181, 0, v181, vcc
	s_nop 0
	v_cndmask_b32_e64 v182, 0, v182, s[98:99]
	v_max3_u32 v9, v9, v181, v182
	ds_bpermute_b32 v189, v111, v9
	s_waitcnt lgkmcnt(0)
; DI void peer_topk_wave(const Params& p, int item, unsigned* lds  ) {
;     ...
; #pragma unroll
;     for (int rr = 0; rr < 16; ++rr) {
;       unsigned m = 0;
; #pragma unroll
;       for (int i = 0; i < 32; ++i) m = umax(m, kk[i]);
;       m = umax(m, (unsigned)__shfl_xor((int)m, 16));
;       m = umax(m, (unsigned)__shfl_xor((int)m, 32));
;       win[pp][rr] = m;
; #pragma unroll
;       for (int i = 0; i < 32; ++i) kk[i] = (kk[i] == m) ? 0u : kk[i];
;     }
	v_max_u32_e32 v9, v9, v189
	ds_bpermute_b32 v189, v112, v9
	s_waitcnt lgkmcnt(0)
	v_max_u32_e32 v9, v9, v189
	v_cmp_ne_u32_e32 vcc, v184, v9
	v_cmp_ne_u32_e64 s[98:99], v185, v9
	v_cmp_ne_u32_e64 s[100:101], v186, v9
	v_cndmask_b32_e32 v184, 0, v184, vcc
	v_cndmask_b32_e64 v185, 0, v185, s[98:99]
	v_cndmask_b32_e64 v186, 0, v186, s[100:101]
	v_cmp_ne_u32_e32 vcc, v187, v9
	v_cmp_ne_u32_e64 s[98:99], v188, v9
	v_cmp_ne_u32_e64 s[100:101], v10, v9
	v_cndmask_b32_e32 v187, 0, v187, vcc
	v_cndmask_b32_e64 v188, 0, v188, s[98:99]
	v_cndmask_b32_e64 v189, 0, v10, s[100:101]
	v_cmp_ne_u32_e32 vcc, v11, v9
	v_max_u32_e32 v10, v184, v185
	v_max3_u32 v10, v10, v186, v187
	v_cndmask_b32_e32 v11, 0, v11, vcc
	v_cmp_ne_u32_e64 s[98:99], v12, v9
	v_max3_u32 v10, v10, v188, v189
	v_cmp_ne_u32_e64 s[100:101], v13, v9
	v_cndmask_b32_e64 v12, 0, v12, s[98:99]
	v_max3_u32 v10, v10, v11, v12
	v_cndmask_b32_e64 v13, 0, v13, s[100:101]
	v_cmp_ne_u32_e32 vcc, v14, v9
	v_cmp_ne_u32_e64 s[98:99], v15, v9
	v_cmp_ne_u32_e64 s[100:101], v86, v9
	v_cndmask_b32_e32 v14, 0, v14, vcc
	v_max3_u32 v10, v10, v13, v14
	v_cndmask_b32_e64 v15, 0, v15, s[98:99]
	v_cndmask_b32_e64 v86, 0, v86, s[100:101]
	v_cmp_ne_u32_e32 vcc, v87, v9
	v_max3_u32 v10, v10, v15, v86
	v_cmp_ne_u32_e64 s[98:99], v88, v9
	v_cndmask_b32_e32 v87, 0, v87, vcc
	v_cmp_ne_u32_e64 s[100:101], v89, v9
	v_cndmask_b32_e64 v88, 0, v88, s[98:99]
	v_max3_u32 v10, v10, v87, v88
	v_cndmask_b32_e64 v89, 0, v89, s[100:101]
	v_cmp_ne_u32_e32 vcc, v164, v9
	v_cmp_ne_u32_e64 s[98:99], v165, v9
	v_cmp_ne_u32_e64 s[100:101], v166, v9
	v_cndmask_b32_e32 v164, 0, v164, vcc
	v_max3_u32 v10, v10, v89, v164
	v_cndmask_b32_e64 v165, 0, v165, s[98:99]
	v_cndmask_b32_e64 v166, 0, v166, s[100:101]
	v_cmp_ne_u32_e32 vcc, v167, v9
	v_max3_u32 v10, v10, v165, v166
	v_cmp_ne_u32_e64 s[98:99], v168, v9
	v_cndmask_b32_e32 v167, 0, v167, vcc
	v_cmp_ne_u32_e64 s[100:101], v169, v9
	v_cndmask_b32_e64 v168, 0, v168, s[98:99]
	v_max3_u32 v10, v10, v167, v168
	v_cndmask_b32_e64 v169, 0, v169, s[100:101]
	v_cmp_ne_u32_e32 vcc, v171, v9
	v_cmp_ne_u32_e64 s[98:99], v172, v9
	v_cmp_ne_u32_e64 s[100:101], v173, v9
	v_cndmask_b32_e32 v171, 0, v171, vcc
	v_max3_u32 v10, v10, v169, v171
	v_cndmask_b32_e64 v172, 0, v172, s[98:99]
	v_cndmask_b32_e64 v173, 0, v173, s[100:101]
	v_cmp_ne_u32_e32 vcc, v176, v9
	v_max3_u32 v10, v10, v172, v173
	v_cmp_ne_u32_e64 s[98:99], v177, v9
	v_cndmask_b32_e32 v176, 0, v176, vcc
	v_cmp_ne_u32_e64 s[100:101], v178, v9
	v_cndmask_b32_e64 v177, 0, v177, s[98:99]
	v_max3_u32 v10, v10, v176, v177
	v_cndmask_b32_e64 v178, 0, v178, s[100:101]
	v_cmp_ne_u32_e32 vcc, v179, v9
	v_cmp_ne_u32_e64 s[98:99], v183, v9
	v_cmp_ne_u32_e64 s[100:101], v180, v9
	v_cndmask_b32_e32 v179, 0, v179, vcc
	v_max3_u32 v10, v10, v178, v179
	v_cndmask_b32_e64 v183, 0, v183, s[98:99]
	v_cndmask_b32_e64 v180, 0, v180, s[100:101]
	v_cmp_ne_u32_e32 vcc, v181, v9
	v_max3_u32 v10, v10, v183, v180
	v_cmp_ne_u32_e64 s[98:99], v182, v9
	v_cndmask_b32_e32 v181, 0, v181, vcc
	s_nop 0
	v_cndmask_b32_e64 v182, 0, v182, s[98:99]
	v_max3_u32 v10, v10, v181, v182
	ds_bpermute_b32 v190, v111, v10
	s_waitcnt lgkmcnt(0)
	v_max_u32_e32 v10, v10, v190
	ds_bpermute_b32 v190, v112, v10
	s_waitcnt lgkmcnt(0)
	v_max_u32_e32 v10, v10, v190
	v_cmp_ne_u32_e32 vcc, v184, v10
	v_cmp_ne_u32_e64 s[98:99], v185, v10
	v_cmp_ne_u32_e64 s[100:101], v186, v10
	v_cndmask_b32_e32 v184, 0, v184, vcc
	v_cndmask_b32_e64 v185, 0, v185, s[98:99]
	v_cndmask_b32_e64 v186, 0, v186, s[100:101]
	v_cmp_ne_u32_e32 vcc, v187, v10
	v_cmp_ne_u32_e64 s[98:99], v188, v10
	v_cmp_ne_u32_e64 s[100:101], v189, v10
	v_cndmask_b32_e32 v187, 0, v187, vcc
	v_cndmask_b32_e64 v188, 0, v188, s[98:99]
	v_cndmask_b32_e64 v189, 0, v189, s[100:101]
	v_cmp_ne_u32_e32 vcc, v11, v10
	v_cmp_ne_u32_e64 s[98:99], v12, v10
	v_cmp_ne_u32_e64 s[100:101], v13, v10
	v_cndmask_b32_e32 v190, 0, v11, vcc
	v_max_u32_e32 v11, v184, v185
	v_max3_u32 v11, v11, v186, v187
	v_cndmask_b32_e64 v12, 0, v12, s[98:99]
	v_max3_u32 v11, v11, v188, v189
	v_max3_u32 v11, v11, v190, v12
	v_cndmask_b32_e64 v13, 0, v13, s[100:101]
	v_cmp_ne_u32_e32 vcc, v14, v10
	v_cmp_ne_u32_e64 s[98:99], v15, v10
	v_cmp_ne_u32_e64 s[100:101], v86, v10
	v_cndmask_b32_e32 v14, 0, v14, vcc
	v_max3_u32 v11, v11, v13, v14
	v_cndmask_b32_e64 v15, 0, v15, s[98:99]
	v_cndmask_b32_e64 v86, 0, v86, s[100:101]
	v_cmp_ne_u32_e32 vcc, v87, v10
	v_max3_u32 v11, v11, v15, v86
	v_cmp_ne_u32_e64 s[98:99], v88, v10
	v_cndmask_b32_e32 v87, 0, v87, vcc
	v_cmp_ne_u32_e64 s[100:101], v89, v10
	v_cndmask_b32_e64 v88, 0, v88, s[98:99]
	v_max3_u32 v11, v11, v87, v88
	v_cndmask_b32_e64 v89, 0, v89, s[100:101]
	v_cmp_ne_u32_e32 vcc, v164, v10
	v_cmp_ne_u32_e64 s[98:99], v165, v10
	v_cmp_ne_u32_e64 s[100:101], v166, v10
	v_cndmask_b32_e32 v164, 0, v164, vcc
	v_max3_u32 v11, v11, v89, v164
	v_cndmask_b32_e64 v165, 0, v165, s[98:99]
	v_cndmask_b32_e64 v166, 0, v166, s[100:101]
	v_cmp_ne_u32_e32 vcc, v167, v10
	v_max3_u32 v11, v11, v165, v166
	v_cmp_ne_u32_e64 s[98:99], v168, v10
	v_cndmask_b32_e32 v167, 0, v167, vcc
	v_cmp_ne_u32_e64 s[100:101], v169, v10
	v_cndmask_b32_e64 v168, 0, v168, s[98:99]
	v_max3_u32 v11, v11, v167, v168
	v_cndmask_b32_e64 v169, 0, v169, s[100:101]
	v_cmp_ne_u32_e32 vcc, v171, v10
	v_cmp_ne_u32_e64 s[98:99], v172, v10
	v_cmp_ne_u32_e64 s[100:101], v173, v10
	v_cndmask_b32_e32 v171, 0, v171, vcc
	v_max3_u32 v11, v11, v169, v171
	v_cndmask_b32_e64 v172, 0, v172, s[98:99]
	v_cndmask_b32_e64 v173, 0, v173, s[100:101]
	v_cmp_ne_u32_e32 vcc, v176, v10
	v_max3_u32 v11, v11, v172, v173
	v_cmp_ne_u32_e64 s[98:99], v177, v10
	v_cndmask_b32_e32 v176, 0, v176, vcc
	v_cmp_ne_u32_e64 s[100:101], v178, v10
	v_cndmask_b32_e64 v177, 0, v177, s[98:99]
	v_max3_u32 v11, v11, v176, v177
	v_cndmask_b32_e64 v178, 0, v178, s[100:101]
	v_cmp_ne_u32_e32 vcc, v179, v10
	v_cmp_ne_u32_e64 s[98:99], v183, v10
	v_cmp_ne_u32_e64 s[100:101], v180, v10
	v_cndmask_b32_e32 v179, 0, v179, vcc
	v_max3_u32 v11, v11, v178, v179
	v_cndmask_b32_e64 v183, 0, v183, s[98:99]
	v_cndmask_b32_e64 v180, 0, v180, s[100:101]
	v_cmp_ne_u32_e32 vcc, v181, v10
	v_max3_u32 v11, v11, v183, v180
	v_cmp_ne_u32_e64 s[98:99], v182, v10
	v_cndmask_b32_e32 v181, 0, v181, vcc
	s_nop 0
	v_cndmask_b32_e64 v182, 0, v182, s[98:99]
	v_max3_u32 v11, v11, v181, v182
	ds_bpermute_b32 v191, v111, v11
	s_waitcnt lgkmcnt(0)
; DI void peer_topk_wave(const Params& p, int item, unsigned* lds  ) {
;     ...
; #pragma unroll
;     for (int rr = 0; rr < 16; ++rr) {
;       unsigned m = 0;
; #pragma unroll
;       for (int i = 0; i < 32; ++i) m = umax(m, kk[i]);
;       m = umax(m, (unsigned)__shfl_xor((int)m, 16));
;       m = umax(m, (unsigned)__shfl_xor((int)m, 32));
;       win[pp][rr] = m;
; #pragma unroll
;       for (int i = 0; i < 32; ++i) kk[i] = (kk[i] == m) ? 0u : kk[i];
;     }
	v_max_u32_e32 v11, v11, v191
	ds_bpermute_b32 v191, v112, v11
	s_waitcnt lgkmcnt(0)
	v_max_u32_e32 v11, v11, v191
	v_cmp_ne_u32_e32 vcc, v184, v11
	v_cmp_ne_u32_e64 s[98:99], v185, v11
	v_cmp_ne_u32_e64 s[100:101], v186, v11
	v_cndmask_b32_e32 v184, 0, v184, vcc
	v_cndmask_b32_e64 v185, 0, v185, s[98:99]
	v_cndmask_b32_e64 v186, 0, v186, s[100:101]
	v_cmp_ne_u32_e32 vcc, v187, v11
	v_cmp_ne_u32_e64 s[98:99], v188, v11
	v_cmp_ne_u32_e64 s[100:101], v189, v11
	v_cndmask_b32_e32 v187, 0, v187, vcc
	v_cndmask_b32_e64 v188, 0, v188, s[98:99]
	v_cndmask_b32_e64 v189, 0, v189, s[100:101]
	v_cmp_ne_u32_e32 vcc, v190, v11
	v_cmp_ne_u32_e64 s[98:99], v12, v11
	v_cmp_ne_u32_e64 s[100:101], v13, v11
	v_cndmask_b32_e32 v190, 0, v190, vcc
	v_cndmask_b32_e64 v191, 0, v12, s[98:99]
	v_max_u32_e32 v12, v184, v185
	v_max3_u32 v12, v12, v186, v187
	v_cndmask_b32_e64 v13, 0, v13, s[100:101]
	v_cmp_ne_u32_e32 vcc, v14, v11
	v_max3_u32 v12, v12, v188, v189
	v_max3_u32 v12, v12, v190, v191
	v_cndmask_b32_e32 v14, 0, v14, vcc
	v_cmp_ne_u32_e64 s[98:99], v15, v11
	v_max3_u32 v12, v12, v13, v14
	v_cmp_ne_u32_e64 s[100:101], v86, v11
	v_cndmask_b32_e64 v15, 0, v15, s[98:99]
	v_cmp_ne_u32_e32 vcc, v87, v11
	v_cndmask_b32_e64 v86, 0, v86, s[100:101]
	v_max3_u32 v12, v12, v15, v86
	v_cndmask_b32_e32 v87, 0, v87, vcc
	v_cmp_ne_u32_e64 s[98:99], v88, v11
	v_cmp_ne_u32_e64 s[100:101], v89, v11
	v_cmp_ne_u32_e32 vcc, v164, v11
	v_cndmask_b32_e64 v88, 0, v88, s[98:99]
	v_max3_u32 v12, v12, v87, v88
	v_cndmask_b32_e64 v89, 0, v89, s[100:101]
	v_cndmask_b32_e32 v164, 0, v164, vcc
	v_cmp_ne_u32_e64 s[98:99], v165, v11
	v_max3_u32 v12, v12, v89, v164
	v_cmp_ne_u32_e64 s[100:101], v166, v11
	v_cndmask_b32_e64 v165, 0, v165, s[98:99]
	v_cmp_ne_u32_e32 vcc, v167, v11
	v_cndmask_b32_e64 v166, 0, v166, s[100:101]
	v_max3_u32 v12, v12, v165, v166
	v_cndmask_b32_e32 v167, 0, v167, vcc
	v_cmp_ne_u32_e64 s[98:99], v168, v11
	v_cmp_ne_u32_e64 s[100:101], v169, v11
	v_cmp_ne_u32_e32 vcc, v171, v11
	v_cndmask_b32_e64 v168, 0, v168, s[98:99]
	v_max3_u32 v12, v12, v167, v168
	v_cndmask_b32_e64 v169, 0, v169, s[100:101]
	v_cndmask_b32_e32 v171, 0, v171, vcc
	v_cmp_ne_u32_e64 s[98:99], v172, v11
	v_max3_u32 v12, v12, v169, v171
	v_cmp_ne_u32_e64 s[100:101], v173, v11
	v_cndmask_b32_e64 v172, 0, v172, s[98:99]
	v_cmp_ne_u32_e32 vcc, v176, v11
	v_cndmask_b32_e64 v173, 0, v173, s[100:101]
	v_max3_u32 v12, v12, v172, v173
	v_cndmask_b32_e32 v176, 0, v176, vcc
	v_cmp_ne_u32_e64 s[98:99], v177, v11
	v_cmp_ne_u32_e64 s[100:101], v178, v11
	v_cmp_ne_u32_e32 vcc, v179, v11
	v_cndmask_b32_e64 v177, 0, v177, s[98:99]
	v_max3_u32 v12, v12, v176, v177
	v_cndmask_b32_e64 v178, 0, v178, s[100:101]
	v_cndmask_b32_e32 v179, 0, v179, vcc
	v_cmp_ne_u32_e64 s[98:99], v183, v11
	v_max3_u32 v12, v12, v178, v179
	v_cmp_ne_u32_e64 s[100:101], v180, v11
	v_cndmask_b32_e64 v183, 0, v183, s[98:99]
	v_cmp_ne_u32_e32 vcc, v181, v11
	v_cndmask_b32_e64 v180, 0, v180, s[100:101]
	v_max3_u32 v12, v12, v183, v180
	v_cndmask_b32_e32 v181, 0, v181, vcc
	v_cmp_ne_u32_e64 s[98:99], v182, v11
	s_nop 0
	s_nop 0
	v_cndmask_b32_e64 v182, 0, v182, s[98:99]
	v_max3_u32 v12, v12, v181, v182
	ds_bpermute_b32 v192, v111, v12
	s_waitcnt lgkmcnt(0)
	v_max_u32_e32 v12, v12, v192
	ds_bpermute_b32 v192, v112, v12
	s_waitcnt lgkmcnt(0)
	v_max_u32_e32 v12, v12, v192
	v_cmp_ne_u32_e32 vcc, v184, v12
	v_cmp_ne_u32_e64 s[98:99], v185, v12
	v_cmp_ne_u32_e64 s[100:101], v186, v12
	v_cndmask_b32_e32 v184, 0, v184, vcc
	v_cndmask_b32_e64 v185, 0, v185, s[98:99]
	v_cndmask_b32_e64 v186, 0, v186, s[100:101]
	v_cmp_ne_u32_e32 vcc, v187, v12
	v_cmp_ne_u32_e64 s[98:99], v188, v12
	v_cmp_ne_u32_e64 s[100:101], v189, v12
	v_cndmask_b32_e32 v187, 0, v187, vcc
	v_cndmask_b32_e64 v188, 0, v188, s[98:99]
	v_cndmask_b32_e64 v189, 0, v189, s[100:101]
	v_cmp_ne_u32_e32 vcc, v190, v12
	v_cmp_ne_u32_e64 s[98:99], v191, v12
	v_cmp_ne_u32_e64 s[100:101], v13, v12
	v_cndmask_b32_e32 v190, 0, v190, vcc
	v_cndmask_b32_e64 v191, 0, v191, s[98:99]
	v_cndmask_b32_e64 v192, 0, v13, s[100:101]
	v_cmp_ne_u32_e32 vcc, v14, v12
	v_max_u32_e32 v13, v184, v185
	v_max3_u32 v13, v13, v186, v187
	v_cndmask_b32_e32 v14, 0, v14, vcc
	v_cmp_ne_u32_e64 s[98:99], v15, v12
	v_max3_u32 v13, v13, v188, v189
	v_max3_u32 v13, v13, v190, v191
	v_cndmask_b32_e64 v15, 0, v15, s[98:99]
	v_cmp_ne_u32_e64 s[100:101], v86, v12
	v_max3_u32 v13, v13, v192, v14
	v_cmp_ne_u32_e32 vcc, v87, v12
	v_cndmask_b32_e64 v86, 0, v86, s[100:101]
	v_max3_u32 v13, v13, v15, v86
	v_cndmask_b32_e32 v87, 0, v87, vcc
	v_cmp_ne_u32_e64 s[98:99], v88, v12
	v_cmp_ne_u32_e64 s[100:101], v89, v12
	v_cmp_ne_u32_e32 vcc, v164, v12
	v_cndmask_b32_e64 v88, 0, v88, s[98:99]
	v_max3_u32 v13, v13, v87, v88
	v_cndmask_b32_e64 v89, 0, v89, s[100:101]
	v_cndmask_b32_e32 v164, 0, v164, vcc
	v_cmp_ne_u32_e64 s[98:99], v165, v12
	v_max3_u32 v13, v13, v89, v164
	v_cmp_ne_u32_e64 s[100:101], v166, v12
	v_cndmask_b32_e64 v165, 0, v165, s[98:99]
	v_cmp_ne_u32_e32 vcc, v167, v12
	v_cndmask_b32_e64 v166, 0, v166, s[100:101]
	v_max3_u32 v13, v13, v165, v166
	v_cndmask_b32_e32 v167, 0, v167, vcc
	v_cmp_ne_u32_e64 s[98:99], v168, v12
	v_cmp_ne_u32_e64 s[100:101], v169, v12
	v_cmp_ne_u32_e32 vcc, v171, v12
	v_cndmask_b32_e64 v168, 0, v168, s[98:99]
	v_max3_u32 v13, v13, v167, v168
	v_cndmask_b32_e64 v169, 0, v169, s[100:101]
	v_cndmask_b32_e32 v171, 0, v171, vcc
	v_cmp_ne_u32_e64 s[98:99], v172, v12
	v_max3_u32 v13, v13, v169, v171
	v_cmp_ne_u32_e64 s[100:101], v173, v12
	v_cndmask_b32_e64 v172, 0, v172, s[98:99]
	v_cmp_ne_u32_e32 vcc, v176, v12
	v_cndmask_b32_e64 v173, 0, v173, s[100:101]
	v_max3_u32 v13, v13, v172, v173
	v_cndmask_b32_e32 v176, 0, v176, vcc
	v_cmp_ne_u32_e64 s[98:99], v177, v12
	v_cmp_ne_u32_e64 s[100:101], v178, v12
	v_cmp_ne_u32_e32 vcc, v179, v12
	v_cndmask_b32_e64 v177, 0, v177, s[98:99]
	v_max3_u32 v13, v13, v176, v177
	v_cndmask_b32_e64 v178, 0, v178, s[100:101]
	v_cndmask_b32_e32 v179, 0, v179, vcc
	v_cmp_ne_u32_e64 s[98:99], v183, v12
	v_max3_u32 v13, v13, v178, v179
	v_cmp_ne_u32_e64 s[100:101], v180, v12
	v_cndmask_b32_e64 v183, 0, v183, s[98:99]
	v_cmp_ne_u32_e32 vcc, v181, v12
	v_cndmask_b32_e64 v180, 0, v180, s[100:101]
	v_max3_u32 v13, v13, v183, v180
	v_cndmask_b32_e32 v181, 0, v181, vcc
	v_cmp_ne_u32_e64 s[98:99], v182, v12
	s_nop 0
	s_nop 0
	v_cndmask_b32_e64 v182, 0, v182, s[98:99]
	v_max3_u32 v13, v13, v181, v182
	ds_bpermute_b32 v193, v111, v13
	s_waitcnt lgkmcnt(0)
; DI void peer_topk_wave(const Params& p, int item, unsigned* lds  ) {
;     ...
;     for (int rr = 0; rr < 16; ++rr) {
;       unsigned m = 0;
; #pragma unroll
;       for (int i = 0; i < 32; ++i) m = umax(m, kk[i]);
;       m = umax(m, (unsigned)__shfl_xor((int)m, 16));
;       m = umax(m, (unsigned)__shfl_xor((int)m, 32));
;       win[pp][rr] = m;
; #pragma unroll
;       for (int i = 0; i < 32; ++i) kk[i] = (kk[i] == m) ? 0u : kk[i];
;     }
	v_max_u32_e32 v13, v13, v193
	ds_bpermute_b32 v193, v112, v13
	s_waitcnt lgkmcnt(0)
	v_max_u32_e32 v13, v13, v193
	v_cmp_ne_u32_e32 vcc, v184, v13
	v_cmp_ne_u32_e64 s[98:99], v185, v13
	v_cmp_ne_u32_e64 s[100:101], v186, v13
	v_cndmask_b32_e32 v184, 0, v184, vcc
	v_cndmask_b32_e64 v185, 0, v185, s[98:99]
	v_cndmask_b32_e64 v186, 0, v186, s[100:101]
	v_cmp_ne_u32_e32 vcc, v187, v13
	v_cmp_ne_u32_e64 s[98:99], v188, v13
	v_cmp_ne_u32_e64 s[100:101], v189, v13
	v_cndmask_b32_e32 v187, 0, v187, vcc
	v_cndmask_b32_e64 v188, 0, v188, s[98:99]
	v_cndmask_b32_e64 v189, 0, v189, s[100:101]
	v_cmp_ne_u32_e32 vcc, v190, v13
	v_cmp_ne_u32_e64 s[98:99], v191, v13
	v_cmp_ne_u32_e64 s[100:101], v192, v13
	v_cndmask_b32_e32 v190, 0, v190, vcc
	v_cndmask_b32_e64 v191, 0, v191, s[98:99]
	v_cndmask_b32_e64 v192, 0, v192, s[100:101]
	v_cmp_ne_u32_e32 vcc, v14, v13
	v_cmp_ne_u32_e64 s[98:99], v15, v13
	v_cmp_ne_u32_e64 s[100:101], v86, v13
	v_cndmask_b32_e32 v193, 0, v14, vcc
	v_max_u32_e32 v14, v184, v185
	v_max3_u32 v14, v14, v186, v187
	v_cndmask_b32_e64 v15, 0, v15, s[98:99]
	v_max3_u32 v14, v14, v188, v189
	v_max3_u32 v14, v14, v190, v191
	v_cndmask_b32_e64 v86, 0, v86, s[100:101]
	v_cmp_ne_u32_e32 vcc, v87, v13
	v_max3_u32 v14, v14, v192, v193
	v_max3_u32 v14, v14, v15, v86
	v_cndmask_b32_e32 v87, 0, v87, vcc
	v_cmp_ne_u32_e64 s[98:99], v88, v13
	v_cmp_ne_u32_e64 s[100:101], v89, v13
	v_cmp_ne_u32_e32 vcc, v164, v13
	v_cndmask_b32_e64 v88, 0, v88, s[98:99]
	v_max3_u32 v14, v14, v87, v88
	v_cndmask_b32_e64 v89, 0, v89, s[100:101]
	v_cndmask_b32_e32 v164, 0, v164, vcc
	v_cmp_ne_u32_e64 s[98:99], v165, v13
	v_max3_u32 v14, v14, v89, v164
	v_cmp_ne_u32_e64 s[100:101], v166, v13
	v_cndmask_b32_e64 v165, 0, v165, s[98:99]
	v_cmp_ne_u32_e32 vcc, v167, v13
	v_cndmask_b32_e64 v166, 0, v166, s[100:101]
	v_max3_u32 v14, v14, v165, v166
	v_cndmask_b32_e32 v167, 0, v167, vcc
	v_cmp_ne_u32_e64 s[98:99], v168, v13
	v_cmp_ne_u32_e64 s[100:101], v169, v13
	v_cmp_ne_u32_e32 vcc, v171, v13
	v_cndmask_b32_e64 v168, 0, v168, s[98:99]
	v_max3_u32 v14, v14, v167, v168
	v_cndmask_b32_e64 v169, 0, v169, s[100:101]
	v_cndmask_b32_e32 v171, 0, v171, vcc
	v_cmp_ne_u32_e64 s[98:99], v172, v13
	v_max3_u32 v14, v14, v169, v171
	v_cmp_ne_u32_e64 s[100:101], v173, v13
	v_cndmask_b32_e64 v172, 0, v172, s[98:99]
	v_cmp_ne_u32_e32 vcc, v176, v13
	v_cndmask_b32_e64 v173, 0, v173, s[100:101]
	v_max3_u32 v14, v14, v172, v173
	v_cndmask_b32_e32 v176, 0, v176, vcc
	v_cmp_ne_u32_e64 s[98:99], v177, v13
	v_cmp_ne_u32_e64 s[100:101], v178, v13
	v_cmp_ne_u32_e32 vcc, v179, v13
	v_cndmask_b32_e64 v177, 0, v177, s[98:99]
	v_max3_u32 v14, v14, v176, v177
	v_cndmask_b32_e64 v178, 0, v178, s[100:101]
	v_cndmask_b32_e32 v179, 0, v179, vcc
	v_cmp_ne_u32_e64 s[98:99], v183, v13
	v_max3_u32 v14, v14, v178, v179
	v_cmp_ne_u32_e64 s[100:101], v180, v13
	v_cndmask_b32_e64 v183, 0, v183, s[98:99]
	v_cmp_ne_u32_e32 vcc, v181, v13
	v_cndmask_b32_e64 v180, 0, v180, s[100:101]
	v_max3_u32 v14, v14, v183, v180
	v_cndmask_b32_e32 v181, 0, v181, vcc
	v_cmp_ne_u32_e64 s[98:99], v182, v13
	s_nop 0
	s_nop 0
	v_cndmask_b32_e64 v182, 0, v182, s[98:99]
	v_max3_u32 v14, v14, v181, v182
	ds_bpermute_b32 v194, v111, v14
	s_waitcnt lgkmcnt(0)
	v_max_u32_e32 v14, v14, v194
	ds_bpermute_b32 v194, v112, v14
	s_waitcnt lgkmcnt(0)
; DI float unordf(unsigned k) { unsigned u = (k & 0x80000000u) ? (k & 0x7fffffffu) : ~k; return __uint_as_float(u); }
; DI void peer_topk_wave(const Params& p, int item, unsigned* lds  ) {
;     ...
;     for (int rr = 0; rr < 16; ++rr) {
;       unsigned m = 0;
; #pragma unroll
;       for (int i = 0; i < 32; ++i) m = umax(m, kk[i]);
;       m = umax(m, (unsigned)__shfl_xor((int)m, 16));
;       m = umax(m, (unsigned)__shfl_xor((int)m, 32));
;       win[pp][rr] = m;
; #pragma unroll
;       for (int i = 0; i < 32; ++i) kk[i] = (kk[i] == m) ? 0u : kk[i];
;     }
;     ...
;   float f0[16], f1[16];
; #pragma unroll
;   for (int i = 0; i < 16; ++i) { f0[i] = unordf(win[0][i] & ~127u); f1[i] = unordf(win[1][i] & ~127u); }
;   unsigned cand[13];
;     ...
;   CAND(0, 0, 0, 0, 13, 2, 0, 6, 1)
	v_max_u32_e32 v14, v14, v194
	v_cmp_ne_u32_e32 vcc, v185, v14
	v_cmp_eq_u32_e64 s[68:69], v184, v14
	v_cmp_eq_u32_e64 s[70:71], v186, v14
	v_cndmask_b32_e32 v185, 0, v185, vcc
	v_max_u32_e32 v184, v184, v185
	v_cndmask_b32_e64 v184, v184, v185, s[68:69]
	v_max_u32_e32 v185, v184, v186
	v_cndmask_b32_e64 v184, v185, v184, s[70:71]
	v_cmp_eq_u32_e64 s[66:67], v187, v14
	v_max_u32_e32 v185, v184, v187
	v_cmp_eq_u32_e64 s[64:65], v188, v14
	v_cndmask_b32_e64 v184, v185, v184, s[66:67]
	v_max_u32_e32 v185, v184, v188
	v_cndmask_b32_e64 v184, v185, v184, s[64:65]
	v_cmp_eq_u32_e64 s[62:63], v189, v14
	v_max_u32_e32 v185, v184, v189
	v_cmp_eq_u32_e64 s[60:61], v190, v14
	v_cndmask_b32_e64 v184, v185, v184, s[62:63]
	v_max_u32_e32 v185, v184, v190
	v_cndmask_b32_e64 v184, v185, v184, s[60:61]
	v_cmp_eq_u32_e64 s[58:59], v191, v14
	v_max_u32_e32 v185, v184, v191
	v_cmp_eq_u32_e64 s[56:57], v192, v14
	v_cndmask_b32_e64 v184, v185, v184, s[58:59]
	v_max_u32_e32 v185, v184, v192
	v_cndmask_b32_e64 v184, v185, v184, s[56:57]
	v_cmp_eq_u32_e64 s[54:55], v193, v14
	v_max_u32_e32 v185, v184, v193
	v_cmp_eq_u32_e64 s[52:53], v15, v14
	v_cndmask_b32_e64 v184, v185, v184, s[54:55]
	v_max_u32_e32 v15, v184, v15
	v_cndmask_b32_e64 v15, v15, v184, s[52:53]
	v_cmp_eq_u32_e64 s[50:51], v86, v14
	v_max_u32_e32 v86, v15, v86
	v_cmp_eq_u32_e64 s[48:49], v87, v14
	v_cndmask_b32_e64 v15, v86, v15, s[50:51]
	v_max_u32_e32 v86, v15, v87
	v_cndmask_b32_e64 v15, v86, v15, s[48:49]
	v_cmp_eq_u32_e64 s[46:47], v88, v14
	v_max_u32_e32 v86, v15, v88
	v_cmp_eq_u32_e64 s[44:45], v89, v14
	v_cndmask_b32_e64 v15, v86, v15, s[46:47]
	v_max_u32_e32 v86, v15, v89
	v_cndmask_b32_e64 v15, v86, v15, s[44:45]
	v_cmp_eq_u32_e64 s[42:43], v164, v14
	v_max_u32_e32 v86, v15, v164
	v_cmp_eq_u32_e64 s[40:41], v165, v14
	v_cndmask_b32_e64 v15, v86, v15, s[42:43]
	v_max_u32_e32 v86, v15, v165
	v_cndmask_b32_e64 v15, v86, v15, s[40:41]
	v_cmp_eq_u32_e64 s[38:39], v166, v14
	v_max_u32_e32 v86, v15, v166
	v_cmp_eq_u32_e64 s[36:37], v167, v14
	v_cndmask_b32_e64 v15, v86, v15, s[38:39]
	v_max_u32_e32 v86, v15, v167
	v_cndmask_b32_e64 v15, v86, v15, s[36:37]
	v_cmp_eq_u32_e64 s[34:35], v168, v14
	v_max_u32_e32 v86, v15, v168
	v_cmp_eq_u32_e64 s[30:31], v169, v14
	v_cndmask_b32_e64 v15, v86, v15, s[34:35]
	v_max_u32_e32 v86, v15, v169
	v_cndmask_b32_e64 v15, v86, v15, s[30:31]
	v_cmp_eq_u32_e64 s[28:29], v171, v14
	v_max_u32_e32 v86, v15, v171
	v_cmp_eq_u32_e64 s[26:27], v172, v14
	v_cndmask_b32_e64 v15, v86, v15, s[28:29]
	v_max_u32_e32 v86, v15, v172
	v_cndmask_b32_e64 v15, v86, v15, s[26:27]
	v_cmp_eq_u32_e64 s[24:25], v173, v14
	v_max_u32_e32 v86, v15, v173
	v_cmp_eq_u32_e64 s[22:23], v176, v14
	v_cndmask_b32_e64 v15, v86, v15, s[24:25]
	v_max_u32_e32 v86, v15, v176
	v_cndmask_b32_e64 v15, v86, v15, s[22:23]
	v_cmp_eq_u32_e64 s[20:21], v177, v14
	v_max_u32_e32 v86, v15, v177
	v_cmp_eq_u32_e64 s[18:19], v178, v14
	v_cndmask_b32_e64 v15, v86, v15, s[20:21]
	v_max_u32_e32 v86, v15, v178
	v_cndmask_b32_e64 v15, v86, v15, s[18:19]
	v_cmp_eq_u32_e64 s[16:17], v179, v14
	v_max_u32_e32 v86, v15, v179
	v_cmp_eq_u32_e64 s[14:15], v183, v14
	v_cndmask_b32_e64 v15, v86, v15, s[16:17]
	v_max_u32_e32 v86, v15, v183
	v_cndmask_b32_e64 v15, v86, v15, s[14:15]
	v_cmp_eq_u32_e64 s[2:3], v180, v14
	v_max_u32_e32 v86, v15, v180
	v_cmp_eq_u32_e64 s[0:1], v181, v14
	v_cndmask_b32_e64 v15, v86, v15, s[2:3]
	v_max_u32_e32 v86, v15, v181
	v_cndmask_b32_e64 v15, v86, v15, s[0:1]
	v_cmp_eq_u32_e32 vcc, v182, v14
	v_max_u32_e32 v86, v15, v182
	v_bitop3_b32 v87, v0, s81, v0 bitop3:0xcf
	v_cndmask_b32_e32 v15, v86, v15, vcc
	ds_bpermute_b32 v86, v111, v15
	v_cmp_gt_i32_e32 vcc, 0, v0
	s_waitcnt lgkmcnt(0)
	v_max_u32_e32 v15, v15, v86
	ds_bpermute_b32 v166, v112, v15
	v_and_b32_e32 v86, 0x7fffff80, v0
	v_cndmask_b32_e32 v89, v87, v86, vcc
	v_and_b32_e32 v86, 0x7fffff80, v1
	v_bitop3_b32 v87, v1, s81, v1 bitop3:0xcf
	v_cmp_gt_i32_e32 vcc, 0, v1
	s_nop 1
	v_cndmask_b32_e32 v164, v87, v86, vcc
	v_cmp_lt_i32_e32 vcc, 0, v175
	v_mov_b32_e32 v86, v89
	s_and_saveexec_b64 s[0:1], vcc
	s_cbranch_execz .LBB0_1097
	v_cmp_ne_u32_e32 vcc, 1, v175
	s_and_saveexec_b64 s[2:3], vcc
	s_xor_b64 s[2:3], exec, s[2:3]
	v_cndmask_b32_e64 v86, v164, v89, s[10:11]
	s_andn2_saveexec_b64 s[2:3], s[2:3]
	v_and_b32_e32 v86, 0x7fffff80, v13
	v_bitop3_b32 v87, v13, s81, v13 bitop3:0xcf
	v_cmp_gt_i32_e32 vcc, 0, v13
	s_nop 1
	v_cndmask_b32_e32 v86, v87, v86, vcc
	s_or_b64 exec, exec, s[2:3]
